# K-loop MFMA segments: priority raised before the opening barrier, the duplicate already-satisfied lgkmcnt(0) dropped, closing barrier taken before the priority drop
# speedup vs baseline: 1.0263x; 1.0044x over previous
; #define PG8_STAGE(bufoff, gbase, voff) do { _Pragma("unroll") for (int _i = 0; _i < 2; ++_i) \
;         __builtin_amdgcn_global_load_lds((const unsigned*)((const char*)(gbase) + (voff)[_i]), (PG8_LAS unsigned*)(lds + (bufoff) + ldsw + _i * 8192), 16, 0, 0); } while (0)
; #define PG8_LDA(dst, b, h) do { _Pragma("unroll") for (int m = 0; m < 4; ++m) _Pragma("unroll") for (int k = 0; k < 2; ++k) dst[m][k] = *(const PG8_LAS bf16x8*)(lds + PG8_SA(b, h) + aoff + m * 2048 + k * 1024); } while (0)
; #define PG8_LDB(dst, b, h) do { _Pragma("unroll") for (int n = 0; n < 2; ++n) _Pragma("unroll") for (int k = 0; k < 2; ++k) dst[n][k] = *(const PG8_LAS bf16x8*)(lds + PG8_SB(b, h) + boff + n * 2048 + k * 1024); } while (0)
; #define PG8_WAIT_V(n) asm volatile("s_waitcnt vmcnt(" #n ")" ::: "memory")
; #define PG8_WAIT_L(n) asm volatile("s_waitcnt lgkmcnt(" #n ")" ::: "memory")
; #define PG8_BAR __builtin_amdgcn_s_barrier()
; #define PG8_SCHED __builtin_amdgcn_sched_barrier(0)
; template <class Epi, class Sched, bool ALIGN_EPI = false, bool SP2 = false>
; __device__ __forceinline__ void gemm_phase(PG8_LAS unsigned char* lds, const Gemm g, const Sched& S, const Epi& E) {
;     ...
;             const char* a1 = cA + (size_t)(t + 1) * kstep;
;             const char* a2 = last ? nA : cA + (size_t)(t + 2) * kstep; const char* b2 = last ? nB : cB + (size_t)(t + 2) * kstep;
;             const char* a3 = a2 + kstep; const char* b3 = b2 + kstep;
;             if (last && has_next) S.a_ready(nxt);
;             if constexpr (SP2) {
;             PG8_LDB(B0, 0, 0); PG8_LDB(B1, 0, 1); PG8_SCHED; PG8_LDA(At, 0, 0); PG8_STAGE(PG8_SA(1, 1), a1 + hstepA, voffA);
;             if (plast) PG8_WAIT_V(10); else PG8_WAIT_SEL(defer, 12, 16);
;             PG8_WAIT_L(0); PG8_BAR; PG8_MMA(0, 0, At, B0); PG8_MMA(0, 1, At, B1);
;             if constexpr (Epi::SPLIT) { if (defer) {
;                 E.second(acc, prev, rv1, wr, wc, fr, fq);
;                 _Pragma("unroll") for (int b = 0; b < 2; ++b) _Pragma("unroll") for (int m = 0; m < 4; ++m) _Pragma("unroll") for (int n = 0; n < 2; ++n) acc[1][b][m][n] = (f32x4){0.f, 0.f, 0.f, 0.f}; } }
;             PG8_BAR; PG8_SCHED;
;             PG8_LDA(At, 0, 1); PG8_STAGE(PG8_SB(0, 0), b2, voffB); PG8_STAGE(PG8_SB(0, 1), b2 + hstep, voffB); PG8_STAGE(PG8_SA(0, 0), a2, voffA);
;             if (plast) PG8_WAIT_V(10); else PG8_WAIT_SEL(defer, 16, 24);
.Lpk_ip_259:
	s_add_u32 s30, s24, 0x80
	s_addc_u32 s31, s25, 0
	s_waitcnt lgkmcnt(0)
	s_and_b64 s[26:27], s[26:27], exec
	s_cselect_b32 s27, s7, s31
	s_cselect_b32 s26, s6, s30
	s_cselect_b32 s31, s21, s33
	s_cselect_b32 s30, s20, s23
	s_setprio 1
	s_barrier
	v_mfma_f32_16x16x32_bf16 v[124:127], v[144:147], v[184:187], 0
	v_mfma_f32_16x16x32_bf16 v[120:123], v[152:155], v[184:187], 0
	v_mfma_f32_16x16x32_bf16 v[108:111], v[144:147], v[176:179], 0
	v_mfma_f32_16x16x32_bf16 v[104:107], v[152:155], v[176:179], 0
	v_mfma_f32_16x16x32_bf16 v[92:95], v[144:147], v[168:171], 0
	v_mfma_f32_16x16x32_bf16 v[88:91], v[152:155], v[168:171], 0
	v_mfma_f32_16x16x32_bf16 v[76:79], v[144:147], v[160:163], 0
	v_mfma_f32_16x16x32_bf16 v[72:75], v[152:155], v[160:163], 0
	v_mfma_f32_16x16x32_bf16 v[124:127], v[148:151], v[188:191], v[124:127]
	v_mfma_f32_16x16x32_bf16 v[120:123], v[156:159], v[188:191], v[120:123]
	v_mfma_f32_16x16x32_bf16 v[108:111], v[148:151], v[180:183], v[108:111]
	v_mfma_f32_16x16x32_bf16 v[104:107], v[156:159], v[180:183], v[104:107]
	v_mfma_f32_16x16x32_bf16 v[92:95], v[148:151], v[172:175], v[92:95]
	v_mfma_f32_16x16x32_bf16 v[88:91], v[156:159], v[172:175], v[88:91]
	v_mfma_f32_16x16x32_bf16 v[76:79], v[148:151], v[164:167], v[76:79]
	v_mfma_f32_16x16x32_bf16 v[72:75], v[156:159], v[164:167], v[72:75]
	s_setprio 0
	s_setprio 1
	v_mfma_f32_16x16x32_bf16 v[116:119], v[128:131], v[184:187], 0
	v_mfma_f32_16x16x32_bf16 v[112:115], v[136:139], v[184:187], 0
	v_mfma_f32_16x16x32_bf16 v[100:103], v[128:131], v[176:179], 0
	v_mfma_f32_16x16x32_bf16 v[96:99], v[136:139], v[176:179], 0
	v_mfma_f32_16x16x32_bf16 v[84:87], v[128:131], v[168:171], 0
	v_mfma_f32_16x16x32_bf16 v[80:83], v[136:139], v[168:171], 0
	v_mfma_f32_16x16x32_bf16 v[68:71], v[128:131], v[160:163], 0
	v_mfma_f32_16x16x32_bf16 v[64:67], v[136:139], v[160:163], 0
	v_mfma_f32_16x16x32_bf16 v[116:119], v[132:135], v[188:191], v[116:119]
	v_mfma_f32_16x16x32_bf16 v[112:115], v[140:143], v[188:191], v[112:115]
	v_mfma_f32_16x16x32_bf16 v[100:103], v[132:135], v[180:183], v[100:103]
	v_mfma_f32_16x16x32_bf16 v[96:99], v[140:143], v[180:183], v[96:99]
	v_mfma_f32_16x16x32_bf16 v[84:87], v[132:135], v[172:175], v[84:87]
	v_mfma_f32_16x16x32_bf16 v[80:83], v[140:143], v[172:175], v[80:83]
	v_mfma_f32_16x16x32_bf16 v[68:71], v[132:135], v[164:167], v[68:71]
	v_mfma_f32_16x16x32_bf16 v[64:67], v[140:143], v[164:167], v[64:67]
	s_barrier
	s_setprio 0
	s_mov_b32 m0, s36
	v_lshl_add_u64 v[222:223], s[30:31], 0, v[192:193]
	v_lshl_add_u64 v[220:221], s[30:31], 0, v[204:205]
	s_add_u32 s30, s30, s12
	ds_read_b128 v[184:187], v240 offset:16384
	ds_read_b128 v[188:191], v240 offset:17408
	ds_read_b128 v[176:179], v240 offset:18432
	ds_read_b128 v[180:183], v240 offset:19456
	ds_read_b128 v[168:171], v240 offset:20480
	ds_read_b128 v[172:175], v240 offset:21504
	ds_read_b128 v[160:163], v240 offset:22528
	ds_read_b128 v[164:167], v240 offset:23552
	global_load_lds_dwordx4 v[222:223], off
	s_mov_b32 m0, s37
	s_addc_u32 s31, s31, s13
	global_load_lds_dwordx4 v[220:221], off
	v_lshl_add_u64 v[230:231], s[30:31], 0, v[192:193]
	s_mov_b32 m0, s38
	v_lshl_add_u64 v[228:229], s[30:31], 0, v[204:205]
	global_load_lds_dwordx4 v[230:231], off
	s_mov_b32 m0, s39
	v_lshl_add_u64 v[224:225], s[26:27], 0, v[208:209]
	global_load_lds_dwordx4 v[228:229], off
	s_mov_b32 m0, s35
	v_lshl_add_u64 v[226:227], s[26:27], 0, v[206:207]
	global_load_lds_dwordx4 v[224:225], off
	s_mov_b32 m0, s40
	s_mov_b64 s[30:31], -1
	global_load_lds_dwordx4 v[226:227], off
	s_and_b64 vcc, exec, s[28:29]
	s_cbranch_vccz .Lpk_ip_261
	s_waitcnt vmcnt(8)
	s_mov_b64 s[30:31], 0

; #define PG8_STAGE(bufoff, gbase, voff) do { _Pragma("unroll") for (int _i = 0; _i < 2; ++_i) \
;         __builtin_amdgcn_global_load_lds((const unsigned*)((const char*)(gbase) + (voff)[_i]), (PG8_LAS unsigned*)(lds + (bufoff) + ldsw + _i * 8192), 16, 0, 0); } while (0)
; #define PG8_LDA(dst, b, h) do { _Pragma("unroll") for (int m = 0; m < 4; ++m) _Pragma("unroll") for (int k = 0; k < 2; ++k) dst[m][k] = *(const PG8_LAS bf16x8*)(lds + PG8_SA(b, h) + aoff + m * 2048 + k * 1024); } while (0)
; #define PG8_LDB(dst, b, h) do { _Pragma("unroll") for (int n = 0; n < 2; ++n) _Pragma("unroll") for (int k = 0; k < 2; ++k) dst[n][k] = *(const PG8_LAS bf16x8*)(lds + PG8_SB(b, h) + boff + n * 2048 + k * 1024); } while (0)
; #define PG8_MMA(ai, bj, At, Bt) do { __builtin_amdgcn_s_setprio(1); _Pragma("unroll") for (int m = 0; m < 4; ++m) _Pragma("unroll") for (int n = 0; n < 2; ++n) _Pragma("unroll") for (int k = 0; k < 2; ++k) \
;         acc[ai][bj][m][n] = __builtin_amdgcn_mfma_f32_16x16x32_bf16(Bt[n][k], At[m][k], acc[ai][bj][m][n], 0, 0, 0); __builtin_amdgcn_s_setprio(0); } while (0)
; #define PG8_WAIT_SEL(d, w4, w8) do { if constexpr (Epi::SPLIT) { if (d) { if constexpr (Epi::NSH == 4) PG8_WAIT_V(w4); else PG8_WAIT_V(w8); } else PG8_WAIT_V(8); } else PG8_WAIT_V(8); } while (0)
; #define PG8_WAIT_L(n) asm volatile("s_waitcnt lgkmcnt(" #n ")" ::: "memory")
; #define PG8_BAR __builtin_amdgcn_s_barrier()
; #define PG8_SCHED __builtin_amdgcn_sched_barrier(0)
; template <class Epi, class Sched, bool ALIGN_EPI = false, bool SP2 = false>
; __device__ __forceinline__ void gemm_phase(PG8_LAS unsigned char* lds, const Gemm g, const Sched& S, const Epi& E) {
;     ...
;             PG8_WAIT_L(0); PG8_BAR; PG8_MMA(1, 0, At, B0); PG8_MMA(1, 1, At, B1); PG8_BAR; PG8_SCHED;
;             PG8_LDB(B0, 1, 0); PG8_LDB(B1, 1, 1); PG8_SCHED; PG8_LDA(At, 1, 0); PG8_STAGE(PG8_SA(0, 1), a2 + hstepA, voffA);
;             PG8_WAIT_SEL(defer, 12, 16); PG8_WAIT_L(0); PG8_BAR; PG8_MMA(0, 0, At, B0); PG8_MMA(0, 1, At, B1); PG8_BAR; PG8_SCHED;
.Lpk_ip_252:
	s_waitcnt lgkmcnt(0)
	s_add_i32 s51, s51, 2
	s_setprio 1
	s_barrier
	v_mfma_f32_16x16x32_bf16 v[60:63], v[144:147], v[184:187], 0
	v_mfma_f32_16x16x32_bf16 v[56:59], v[152:155], v[184:187], 0
	v_mfma_f32_16x16x32_bf16 v[44:47], v[144:147], v[176:179], 0
	v_mfma_f32_16x16x32_bf16 v[40:43], v[152:155], v[176:179], 0
	v_mfma_f32_16x16x32_bf16 v[28:31], v[144:147], v[168:171], 0
	v_mfma_f32_16x16x32_bf16 v[24:27], v[152:155], v[168:171], 0
	v_mfma_f32_16x16x32_bf16 v[12:15], v[144:147], v[160:163], 0
	v_mfma_f32_16x16x32_bf16 v[8:11], v[152:155], v[160:163], 0
	v_mfma_f32_16x16x32_bf16 v[60:63], v[148:151], v[188:191], v[60:63]
	v_mfma_f32_16x16x32_bf16 v[56:59], v[156:159], v[188:191], v[56:59]
	v_mfma_f32_16x16x32_bf16 v[44:47], v[148:151], v[180:183], v[44:47]
	v_mfma_f32_16x16x32_bf16 v[40:43], v[156:159], v[180:183], v[40:43]
	v_mfma_f32_16x16x32_bf16 v[28:31], v[148:151], v[172:175], v[28:31]
	v_mfma_f32_16x16x32_bf16 v[24:27], v[156:159], v[172:175], v[24:27]
	v_mfma_f32_16x16x32_bf16 v[12:15], v[148:151], v[164:167], v[12:15]
	v_mfma_f32_16x16x32_bf16 v[8:11], v[156:159], v[164:167], v[8:11]
	s_setprio 0
	s_setprio 1
	v_mfma_f32_16x16x32_bf16 v[52:55], v[128:131], v[184:187], 0
	v_mfma_f32_16x16x32_bf16 v[48:51], v[136:139], v[184:187], 0
	v_mfma_f32_16x16x32_bf16 v[36:39], v[128:131], v[176:179], 0
	v_mfma_f32_16x16x32_bf16 v[32:35], v[136:139], v[176:179], 0
	v_mfma_f32_16x16x32_bf16 v[20:23], v[128:131], v[168:171], 0
	v_mfma_f32_16x16x32_bf16 v[16:19], v[136:139], v[168:171], 0
	v_mfma_f32_16x16x32_bf16 v[4:7], v[128:131], v[160:163], 0
	v_mfma_f32_16x16x32_bf16 v[0:3], v[136:139], v[160:163], 0
	v_mfma_f32_16x16x32_bf16 v[52:55], v[132:135], v[188:191], v[52:55]
	v_mfma_f32_16x16x32_bf16 v[48:51], v[140:143], v[188:191], v[48:51]
	v_mfma_f32_16x16x32_bf16 v[36:39], v[132:135], v[180:183], v[36:39]
	v_mfma_f32_16x16x32_bf16 v[32:35], v[140:143], v[180:183], v[32:35]
	v_mfma_f32_16x16x32_bf16 v[20:23], v[132:135], v[172:175], v[20:23]
	v_mfma_f32_16x16x32_bf16 v[16:19], v[140:143], v[172:175], v[16:19]
	v_mfma_f32_16x16x32_bf16 v[4:7], v[132:135], v[164:167], v[4:7]
	v_mfma_f32_16x16x32_bf16 v[0:3], v[140:143], v[164:167], v[0:3]
	s_barrier
	s_setprio 0
	s_add_i32 s28, 0, 0x18000
	s_add_i32 s29, 0, 0x1c000
	v_add_u32_e32 v140, s28, v239
	v_add_u32_e32 v156, s29, v239
	ds_read_b128 v[128:131], v140
	ds_read_b128 v[132:135], v140 offset:1024
	ds_read_b128 v[136:139], v140 offset:2048
	ds_read_b128 v[140:143], v140 offset:3072
	ds_read_b128 v[144:147], v156
	ds_read_b128 v[148:151], v156 offset:1024
	ds_read_b128 v[152:155], v156 offset:2048
	ds_read_b128 v[156:159], v156 offset:3072
	s_add_u32 s26, s26, s8
	s_addc_u32 s27, s27, s9
	s_mov_b32 m0, s41
	v_lshl_add_u64 v[242:243], s[26:27], 0, v[208:209]
	ds_read_b128 v[160:163], v240 offset:32768
	ds_read_b128 v[164:167], v240 offset:33792
	ds_read_b128 v[168:171], v240 offset:34816
	ds_read_b128 v[172:175], v240 offset:35840
	ds_read_b128 v[176:179], v240 offset:36864
	ds_read_b128 v[180:183], v240 offset:37888
	ds_read_b128 v[184:187], v240 offset:38912
	ds_read_b128 v[188:191], v240 offset:39936
	global_load_lds_dwordx4 v[242:243], off
	v_lshl_add_u64 v[242:243], s[26:27], 0, v[206:207]
	s_mov_b32 m0, s42
	s_nop 0
	global_load_lds_dwordx4 v[242:243], off
	s_waitcnt vmcnt(8)
	s_waitcnt lgkmcnt(0)
	s_setprio 1
	s_barrier
	v_mfma_f32_16x16x32_bf16 v[124:127], v[128:131], v[160:163], v[124:127]
	v_mfma_f32_16x16x32_bf16 v[120:123], v[136:139], v[160:163], v[120:123]
	v_mfma_f32_16x16x32_bf16 v[108:111], v[128:131], v[168:171], v[108:111]
	v_mfma_f32_16x16x32_bf16 v[104:107], v[136:139], v[168:171], v[104:107]
	v_mfma_f32_16x16x32_bf16 v[92:95], v[128:131], v[176:179], v[92:95]
	v_mfma_f32_16x16x32_bf16 v[88:91], v[136:139], v[176:179], v[88:91]
	v_mfma_f32_16x16x32_bf16 v[76:79], v[128:131], v[184:187], v[76:79]
	v_mfma_f32_16x16x32_bf16 v[72:75], v[136:139], v[184:187], v[72:75]
	v_mfma_f32_16x16x32_bf16 v[124:127], v[132:135], v[164:167], v[124:127]
	v_mfma_f32_16x16x32_bf16 v[120:123], v[140:143], v[164:167], v[120:123]
	v_mfma_f32_16x16x32_bf16 v[108:111], v[132:135], v[172:175], v[108:111]
	v_mfma_f32_16x16x32_bf16 v[104:107], v[140:143], v[172:175], v[104:107]
	v_mfma_f32_16x16x32_bf16 v[92:95], v[132:135], v[180:183], v[92:95]
	v_mfma_f32_16x16x32_bf16 v[88:91], v[140:143], v[180:183], v[88:91]
	v_mfma_f32_16x16x32_bf16 v[76:79], v[132:135], v[188:191], v[76:79]
	v_mfma_f32_16x16x32_bf16 v[72:75], v[140:143], v[188:191], v[72:75]
	s_setprio 0
	s_setprio 1
	v_mfma_f32_16x16x32_bf16 v[116:119], v[144:147], v[160:163], v[116:119]
	v_mfma_f32_16x16x32_bf16 v[112:115], v[152:155], v[160:163], v[112:115]
	v_mfma_f32_16x16x32_bf16 v[100:103], v[144:147], v[168:171], v[100:103]
	v_mfma_f32_16x16x32_bf16 v[96:99], v[152:155], v[168:171], v[96:99]
	v_mfma_f32_16x16x32_bf16 v[84:87], v[144:147], v[176:179], v[84:87]
	v_mfma_f32_16x16x32_bf16 v[80:83], v[152:155], v[176:179], v[80:83]
	v_mfma_f32_16x16x32_bf16 v[68:71], v[144:147], v[184:187], v[68:71]
	v_mfma_f32_16x16x32_bf16 v[64:67], v[152:155], v[184:187], v[64:67]
	v_mfma_f32_16x16x32_bf16 v[116:119], v[148:151], v[164:167], v[116:119]
	v_mfma_f32_16x16x32_bf16 v[112:115], v[156:159], v[164:167], v[112:115]
	v_mfma_f32_16x16x32_bf16 v[100:103], v[148:151], v[172:175], v[100:103]
	v_mfma_f32_16x16x32_bf16 v[96:99], v[156:159], v[172:175], v[96:99]
	v_mfma_f32_16x16x32_bf16 v[84:87], v[148:151], v[180:183], v[84:87]
	v_mfma_f32_16x16x32_bf16 v[80:83], v[156:159], v[180:183], v[80:83]
	v_mfma_f32_16x16x32_bf16 v[68:71], v[148:151], v[188:191], v[68:71]
	v_mfma_f32_16x16x32_bf16 v[64:67], v[156:159], v[188:191], v[64:67]
	s_barrier
; #define PG8_STAGE(bufoff, gbase, voff) do { _Pragma("unroll") for (int _i = 0; _i < 2; ++_i) \
;         __builtin_amdgcn_global_load_lds((const unsigned*)((const char*)(gbase) + (voff)[_i]), (PG8_LAS unsigned*)(lds + (bufoff) + ldsw + _i * 8192), 16, 0, 0); } while (0)
; #define PG8_LDA(dst, b, h) do { _Pragma("unroll") for (int m = 0; m < 4; ++m) _Pragma("unroll") for (int k = 0; k < 2; ++k) dst[m][k] = *(const PG8_LAS bf16x8*)(lds + PG8_SA(b, h) + aoff + m * 2048 + k * 1024); } while (0)
; #define PG8_MMA(ai, bj, At, Bt) do { __builtin_amdgcn_s_setprio(1); _Pragma("unroll") for (int m = 0; m < 4; ++m) _Pragma("unroll") for (int n = 0; n < 2; ++n) _Pragma("unroll") for (int k = 0; k < 2; ++k) \
;         acc[ai][bj][m][n] = __builtin_amdgcn_mfma_f32_16x16x32_bf16(Bt[n][k], At[m][k], acc[ai][bj][m][n], 0, 0, 0); __builtin_amdgcn_s_setprio(0); } while (0)
; #define PG8_WAIT_V(n) asm volatile("s_waitcnt vmcnt(" #n ")" ::: "memory")
; #define PG8_WAIT_L(n) asm volatile("s_waitcnt lgkmcnt(" #n ")" ::: "memory")
; #define PG8_BAR __builtin_amdgcn_s_barrier()
; #define PG8_SCHED __builtin_amdgcn_sched_barrier(0)
; template <class Epi, class Sched, bool ALIGN_EPI = false, bool SP2 = false>
; __device__ __forceinline__ void gemm_phase(PG8_LAS unsigned char* lds, const Gemm g, const Sched& S, const Epi& E) {
;     ...
;             PG8_WAIT_L(0); PG8_BAR; PG8_MMA(1, 0, At, B0); PG8_MMA(1, 1, At, B1); PG8_BAR; PG8_SCHED;
;     ...
;             PG8_LDA(At, 1, 1); PG8_STAGE(PG8_SB(1, 0), b3, voffB); PG8_STAGE(PG8_SB(1, 1), b3 + hstep, voffB); PG8_STAGE(PG8_SA(1, 0), a3, voffA);
;             PG8_WAIT_V(8); PG8_WAIT_L(0); PG8_BAR; PG8_MMA(1, 0, At, B0); PG8_MMA(1, 1, At, B1); PG8_BAR; PG8_SCHED;
	s_setprio 0
	s_add_i32 s26, s28, s34
	v_lshl_add_u64 v[222:223], v[222:223], 0, s[90:91]
	s_mov_b32 m0, s26
	ds_read_b128 v[160:163], v240 offset:49152
	ds_read_b128 v[164:167], v240 offset:50176
	ds_read_b128 v[168:171], v240 offset:51200
	ds_read_b128 v[172:175], v240 offset:52224
	ds_read_b128 v[176:179], v240 offset:53248
	ds_read_b128 v[180:183], v240 offset:54272
	ds_read_b128 v[184:187], v240 offset:55296
	ds_read_b128 v[188:191], v240 offset:56320
	global_load_lds_dwordx4 v[222:223], off
	v_lshl_add_u64 v[220:221], v[220:221], 0, s[90:91]
	s_add_i32 m0, s26, 0x2000
	s_add_i32 s26, s29, s34
	global_load_lds_dwordx4 v[220:221], off
	v_lshl_add_u64 v[220:221], v[230:231], 0, s[90:91]
	s_mov_b32 m0, s26
	s_nop 0
	global_load_lds_dwordx4 v[220:221], off
	v_lshl_add_u64 v[220:221], v[228:229], 0, s[90:91]
	s_add_i32 m0, s26, 0x2000
	s_nop 0
	global_load_lds_dwordx4 v[220:221], off
	v_lshl_add_u64 v[220:221], v[224:225], 0, s[90:91]
	s_mov_b32 m0, s43
	s_nop 0
	global_load_lds_dwordx4 v[220:221], off
	v_lshl_add_u64 v[220:221], v[226:227], 0, s[90:91]
	s_mov_b32 m0, s44
	s_nop 0
	global_load_lds_dwordx4 v[220:221], off
	s_waitcnt vmcnt(8)
	s_waitcnt lgkmcnt(0)
	s_setprio 1
	s_barrier
	v_mfma_f32_16x16x32_bf16 v[60:63], v[128:131], v[160:163], v[60:63]
	v_mfma_f32_16x16x32_bf16 v[56:59], v[136:139], v[160:163], v[56:59]
	v_mfma_f32_16x16x32_bf16 v[44:47], v[128:131], v[168:171], v[44:47]
	v_mfma_f32_16x16x32_bf16 v[40:43], v[136:139], v[168:171], v[40:43]
	v_mfma_f32_16x16x32_bf16 v[28:31], v[128:131], v[176:179], v[28:31]
	v_mfma_f32_16x16x32_bf16 v[24:27], v[136:139], v[176:179], v[24:27]
	v_mfma_f32_16x16x32_bf16 v[12:15], v[128:131], v[184:187], v[12:15]
	v_mfma_f32_16x16x32_bf16 v[8:11], v[136:139], v[184:187], v[8:11]
	v_mfma_f32_16x16x32_bf16 v[60:63], v[132:135], v[164:167], v[60:63]
	v_mfma_f32_16x16x32_bf16 v[56:59], v[140:143], v[164:167], v[56:59]
	v_mfma_f32_16x16x32_bf16 v[44:47], v[132:135], v[172:175], v[44:47]
	v_mfma_f32_16x16x32_bf16 v[40:43], v[140:143], v[172:175], v[40:43]
	v_mfma_f32_16x16x32_bf16 v[28:31], v[132:135], v[180:183], v[28:31]
	v_mfma_f32_16x16x32_bf16 v[24:27], v[140:143], v[180:183], v[24:27]
	v_mfma_f32_16x16x32_bf16 v[12:15], v[132:135], v[188:191], v[12:15]
	v_mfma_f32_16x16x32_bf16 v[8:11], v[140:143], v[188:191], v[8:11]
	s_setprio 0
	s_setprio 1
	v_mfma_f32_16x16x32_bf16 v[52:55], v[144:147], v[160:163], v[52:55]
	v_mfma_f32_16x16x32_bf16 v[48:51], v[152:155], v[160:163], v[48:51]
	v_mfma_f32_16x16x32_bf16 v[36:39], v[144:147], v[168:171], v[36:39]
	v_mfma_f32_16x16x32_bf16 v[32:35], v[152:155], v[168:171], v[32:35]
	v_mfma_f32_16x16x32_bf16 v[20:23], v[144:147], v[176:179], v[20:23]
	v_mfma_f32_16x16x32_bf16 v[16:19], v[152:155], v[176:179], v[16:19]
	v_mfma_f32_16x16x32_bf16 v[4:7], v[144:147], v[184:187], v[4:7]
	v_mfma_f32_16x16x32_bf16 v[0:3], v[152:155], v[184:187], v[0:3]
	v_mfma_f32_16x16x32_bf16 v[52:55], v[148:151], v[164:167], v[52:55]
	v_mfma_f32_16x16x32_bf16 v[48:51], v[156:159], v[164:167], v[48:51]
	v_mfma_f32_16x16x32_bf16 v[36:39], v[148:151], v[172:175], v[36:39]
	v_mfma_f32_16x16x32_bf16 v[32:35], v[156:159], v[172:175], v[32:35]
	v_mfma_f32_16x16x32_bf16 v[20:23], v[148:151], v[180:183], v[20:23]
	v_mfma_f32_16x16x32_bf16 v[16:19], v[156:159], v[180:183], v[16:19]
	v_mfma_f32_16x16x32_bf16 v[4:7], v[148:151], v[188:191], v[4:7]
	v_mfma_f32_16x16x32_bf16 v[0:3], v[156:159], v[188:191], v[0:3]
	s_barrier
	s_setprio 0
	s_add_u32 s24, s24, 0x100
	s_addc_u32 s25, s25, 0
	s_add_u32 s23, s23, 0x100
	s_addc_u32 s33, s33, 0
	s_cmp_ge_i32 s51, s45
	s_cbranch_scc1 .LBB0_263
	s_branch .LBB0_253
.LBB0_252:
	s_waitcnt lgkmcnt(0)
	s_add_i32 s51, s51, 2
	s_setprio 1
	s_barrier
	v_mfma_f32_16x16x32_bf16 v[60:63], v[144:147], v[184:187], v[60:63]
	v_mfma_f32_16x16x32_bf16 v[56:59], v[152:155], v[184:187], v[56:59]
	v_mfma_f32_16x16x32_bf16 v[44:47], v[144:147], v[176:179], v[44:47]
	v_mfma_f32_16x16x32_bf16 v[40:43], v[152:155], v[176:179], v[40:43]
	v_mfma_f32_16x16x32_bf16 v[28:31], v[144:147], v[168:171], v[28:31]
	v_mfma_f32_16x16x32_bf16 v[24:27], v[152:155], v[168:171], v[24:27]
	v_mfma_f32_16x16x32_bf16 v[12:15], v[144:147], v[160:163], v[12:15]
	v_mfma_f32_16x16x32_bf16 v[8:11], v[152:155], v[160:163], v[8:11]
	v_mfma_f32_16x16x32_bf16 v[60:63], v[148:151], v[188:191], v[60:63]
	v_mfma_f32_16x16x32_bf16 v[56:59], v[156:159], v[188:191], v[56:59]
	v_mfma_f32_16x16x32_bf16 v[44:47], v[148:151], v[180:183], v[44:47]
	v_mfma_f32_16x16x32_bf16 v[40:43], v[156:159], v[180:183], v[40:43]
	v_mfma_f32_16x16x32_bf16 v[28:31], v[148:151], v[172:175], v[28:31]
	v_mfma_f32_16x16x32_bf16 v[24:27], v[156:159], v[172:175], v[24:27]
	v_mfma_f32_16x16x32_bf16 v[12:15], v[148:151], v[164:167], v[12:15]
	v_mfma_f32_16x16x32_bf16 v[8:11], v[156:159], v[164:167], v[8:11]
	s_setprio 0
	s_setprio 1
	v_mfma_f32_16x16x32_bf16 v[52:55], v[128:131], v[184:187], v[52:55]
	v_mfma_f32_16x16x32_bf16 v[48:51], v[136:139], v[184:187], v[48:51]
	v_mfma_f32_16x16x32_bf16 v[36:39], v[128:131], v[176:179], v[36:39]
	v_mfma_f32_16x16x32_bf16 v[32:35], v[136:139], v[176:179], v[32:35]
	v_mfma_f32_16x16x32_bf16 v[20:23], v[128:131], v[168:171], v[20:23]
	v_mfma_f32_16x16x32_bf16 v[16:19], v[136:139], v[168:171], v[16:19]
	v_mfma_f32_16x16x32_bf16 v[4:7], v[128:131], v[160:163], v[4:7]
	v_mfma_f32_16x16x32_bf16 v[0:3], v[136:139], v[160:163], v[0:3]
	v_mfma_f32_16x16x32_bf16 v[52:55], v[132:135], v[188:191], v[52:55]
	v_mfma_f32_16x16x32_bf16 v[48:51], v[140:143], v[188:191], v[48:51]
	v_mfma_f32_16x16x32_bf16 v[36:39], v[132:135], v[180:183], v[36:39]
	v_mfma_f32_16x16x32_bf16 v[32:35], v[140:143], v[180:183], v[32:35]
	v_mfma_f32_16x16x32_bf16 v[20:23], v[132:135], v[172:175], v[20:23]
	v_mfma_f32_16x16x32_bf16 v[16:19], v[140:143], v[172:175], v[16:19]
	v_mfma_f32_16x16x32_bf16 v[4:7], v[132:135], v[164:167], v[4:7]
	v_mfma_f32_16x16x32_bf16 v[0:3], v[140:143], v[164:167], v[0:3]
	s_barrier
; #define PG8_STAGE(bufoff, gbase, voff) do { _Pragma("unroll") for (int _i = 0; _i < 2; ++_i) \
;         __builtin_amdgcn_global_load_lds((const unsigned*)((const char*)(gbase) + (voff)[_i]), (PG8_LAS unsigned*)(lds + (bufoff) + ldsw + _i * 8192), 16, 0, 0); } while (0)
; #define PG8_LDA(dst, b, h) do { _Pragma("unroll") for (int m = 0; m < 4; ++m) _Pragma("unroll") for (int k = 0; k < 2; ++k) dst[m][k] = *(const PG8_LAS bf16x8*)(lds + PG8_SA(b, h) + aoff + m * 2048 + k * 1024); } while (0)
; #define PG8_LDB(dst, b, h) do { _Pragma("unroll") for (int n = 0; n < 2; ++n) _Pragma("unroll") for (int k = 0; k < 2; ++k) dst[n][k] = *(const PG8_LAS bf16x8*)(lds + PG8_SB(b, h) + boff + n * 2048 + k * 1024); } while (0)
; #define PG8_MMA(ai, bj, At, Bt) do { __builtin_amdgcn_s_setprio(1); _Pragma("unroll") for (int m = 0; m < 4; ++m) _Pragma("unroll") for (int n = 0; n < 2; ++n) _Pragma("unroll") for (int k = 0; k < 2; ++k) \
;         acc[ai][bj][m][n] = __builtin_amdgcn_mfma_f32_16x16x32_bf16(Bt[n][k], At[m][k], acc[ai][bj][m][n], 0, 0, 0); __builtin_amdgcn_s_setprio(0); } while (0)
; #define PG8_WAIT_V(n) asm volatile("s_waitcnt vmcnt(" #n ")" ::: "memory")
; #define PG8_WAIT_SEL(d, w4, w8) do { if constexpr (Epi::SPLIT) { if (d) { if constexpr (Epi::NSH == 4) PG8_WAIT_V(w4); else PG8_WAIT_V(w8); } else PG8_WAIT_V(8); } else PG8_WAIT_V(8); } while (0)
; #define PG8_WAIT_L(n) asm volatile("s_waitcnt lgkmcnt(" #n ")" ::: "memory")
; #define PG8_BAR __builtin_amdgcn_s_barrier()
; #define PG8_SCHED __builtin_amdgcn_sched_barrier(0)
; template <class Epi, class Sched, bool ALIGN_EPI = false, bool SP2 = false>
; __device__ __forceinline__ void gemm_phase(PG8_LAS unsigned char* lds, const Gemm g, const Sched& S, const Epi& E) {
;     ...
;             PG8_LDB(B0, 1, 0); PG8_LDB(B1, 1, 1); PG8_SCHED; PG8_LDA(At, 1, 0); PG8_STAGE(PG8_SA(0, 1), a2 + hstepA, voffA);
;             PG8_WAIT_SEL(defer, 12, 16); PG8_WAIT_L(0); PG8_BAR; PG8_MMA(0, 0, At, B0); PG8_MMA(0, 1, At, B1); PG8_BAR; PG8_SCHED;
;             PG8_LDA(At, 1, 1); PG8_STAGE(PG8_SB(1, 0), b3, voffB); PG8_STAGE(PG8_SB(1, 1), b3 + hstep, voffB); PG8_STAGE(PG8_SA(1, 0), a3, voffA);
;             PG8_WAIT_V(8); PG8_WAIT_L(0); PG8_BAR; PG8_MMA(1, 0, At, B0); PG8_MMA(1, 1, At, B1); PG8_BAR; PG8_SCHED;
	s_setprio 0
	s_add_i32 s28, 0, 0x18000
	s_add_i32 s29, 0, 0x1c000
	v_add_u32_e32 v140, s28, v239
	v_add_u32_e32 v156, s29, v239
	ds_read_b128 v[128:131], v140
	ds_read_b128 v[132:135], v140 offset:1024
	ds_read_b128 v[136:139], v140 offset:2048
	ds_read_b128 v[140:143], v140 offset:3072
	ds_read_b128 v[144:147], v156
	ds_read_b128 v[148:151], v156 offset:1024
	ds_read_b128 v[152:155], v156 offset:2048
	ds_read_b128 v[156:159], v156 offset:3072
	s_add_u32 s26, s26, s8
	s_addc_u32 s27, s27, s9
	s_mov_b32 m0, s41
	v_lshl_add_u64 v[242:243], s[26:27], 0, v[208:209]
	ds_read_b128 v[160:163], v240 offset:32768
	ds_read_b128 v[164:167], v240 offset:33792
	ds_read_b128 v[168:171], v240 offset:34816
	ds_read_b128 v[172:175], v240 offset:35840
	ds_read_b128 v[176:179], v240 offset:36864
	ds_read_b128 v[180:183], v240 offset:37888
	ds_read_b128 v[184:187], v240 offset:38912
	ds_read_b128 v[188:191], v240 offset:39936
	global_load_lds_dwordx4 v[242:243], off
	v_lshl_add_u64 v[242:243], s[26:27], 0, v[206:207]
	s_mov_b32 m0, s42
	s_nop 0
	global_load_lds_dwordx4 v[242:243], off
	s_waitcnt vmcnt(8)
	s_waitcnt lgkmcnt(0)
	s_setprio 1
	s_barrier
	v_mfma_f32_16x16x32_bf16 v[124:127], v[128:131], v[160:163], v[124:127]
	v_mfma_f32_16x16x32_bf16 v[120:123], v[136:139], v[160:163], v[120:123]
	v_mfma_f32_16x16x32_bf16 v[108:111], v[128:131], v[168:171], v[108:111]
	v_mfma_f32_16x16x32_bf16 v[104:107], v[136:139], v[168:171], v[104:107]
	v_mfma_f32_16x16x32_bf16 v[92:95], v[128:131], v[176:179], v[92:95]
	v_mfma_f32_16x16x32_bf16 v[88:91], v[136:139], v[176:179], v[88:91]
	v_mfma_f32_16x16x32_bf16 v[76:79], v[128:131], v[184:187], v[76:79]
	v_mfma_f32_16x16x32_bf16 v[72:75], v[136:139], v[184:187], v[72:75]
	v_mfma_f32_16x16x32_bf16 v[124:127], v[132:135], v[164:167], v[124:127]
	v_mfma_f32_16x16x32_bf16 v[120:123], v[140:143], v[164:167], v[120:123]
	v_mfma_f32_16x16x32_bf16 v[108:111], v[132:135], v[172:175], v[108:111]
	v_mfma_f32_16x16x32_bf16 v[104:107], v[140:143], v[172:175], v[104:107]
	v_mfma_f32_16x16x32_bf16 v[92:95], v[132:135], v[180:183], v[92:95]
	v_mfma_f32_16x16x32_bf16 v[88:91], v[140:143], v[180:183], v[88:91]
	v_mfma_f32_16x16x32_bf16 v[76:79], v[132:135], v[188:191], v[76:79]
	v_mfma_f32_16x16x32_bf16 v[72:75], v[140:143], v[188:191], v[72:75]
	s_setprio 0
	s_setprio 1
	v_mfma_f32_16x16x32_bf16 v[116:119], v[144:147], v[160:163], v[116:119]
	v_mfma_f32_16x16x32_bf16 v[112:115], v[152:155], v[160:163], v[112:115]
	v_mfma_f32_16x16x32_bf16 v[100:103], v[144:147], v[168:171], v[100:103]
	v_mfma_f32_16x16x32_bf16 v[96:99], v[152:155], v[168:171], v[96:99]
	v_mfma_f32_16x16x32_bf16 v[84:87], v[144:147], v[176:179], v[84:87]
	v_mfma_f32_16x16x32_bf16 v[80:83], v[152:155], v[176:179], v[80:83]
	v_mfma_f32_16x16x32_bf16 v[68:71], v[144:147], v[184:187], v[68:71]
	v_mfma_f32_16x16x32_bf16 v[64:67], v[152:155], v[184:187], v[64:67]
	v_mfma_f32_16x16x32_bf16 v[116:119], v[148:151], v[164:167], v[116:119]
	v_mfma_f32_16x16x32_bf16 v[112:115], v[156:159], v[164:167], v[112:115]
	v_mfma_f32_16x16x32_bf16 v[100:103], v[148:151], v[172:175], v[100:103]
	v_mfma_f32_16x16x32_bf16 v[96:99], v[156:159], v[172:175], v[96:99]
	v_mfma_f32_16x16x32_bf16 v[84:87], v[148:151], v[180:183], v[84:87]
	v_mfma_f32_16x16x32_bf16 v[80:83], v[156:159], v[180:183], v[80:83]
	v_mfma_f32_16x16x32_bf16 v[68:71], v[148:151], v[188:191], v[68:71]
	v_mfma_f32_16x16x32_bf16 v[64:67], v[156:159], v[188:191], v[64:67]
	s_barrier
	s_setprio 0
	s_add_i32 s26, s28, s34
	v_lshl_add_u64 v[222:223], v[222:223], 0, s[90:91]
	s_mov_b32 m0, s26
	ds_read_b128 v[160:163], v240 offset:49152
	ds_read_b128 v[164:167], v240 offset:50176
	ds_read_b128 v[168:171], v240 offset:51200
	ds_read_b128 v[172:175], v240 offset:52224
	ds_read_b128 v[176:179], v240 offset:53248
	ds_read_b128 v[180:183], v240 offset:54272
	ds_read_b128 v[184:187], v240 offset:55296
	ds_read_b128 v[188:191], v240 offset:56320
	global_load_lds_dwordx4 v[222:223], off
	v_lshl_add_u64 v[220:221], v[220:221], 0, s[90:91]
	s_add_i32 m0, s26, 0x2000
	s_add_i32 s26, s29, s34
	global_load_lds_dwordx4 v[220:221], off
	v_lshl_add_u64 v[220:221], v[230:231], 0, s[90:91]
	s_mov_b32 m0, s26
	s_nop 0
	global_load_lds_dwordx4 v[220:221], off
	v_lshl_add_u64 v[220:221], v[228:229], 0, s[90:91]
	s_add_i32 m0, s26, 0x2000
	s_nop 0
	global_load_lds_dwordx4 v[220:221], off
	v_lshl_add_u64 v[220:221], v[224:225], 0, s[90:91]
	s_mov_b32 m0, s43
	s_nop 0
	global_load_lds_dwordx4 v[220:221], off
	v_lshl_add_u64 v[220:221], v[226:227], 0, s[90:91]
	s_mov_b32 m0, s44
	s_nop 0
	global_load_lds_dwordx4 v[220:221], off
	s_waitcnt vmcnt(8)
	s_waitcnt lgkmcnt(0)
	s_setprio 1
	s_barrier
	v_mfma_f32_16x16x32_bf16 v[60:63], v[128:131], v[160:163], v[60:63]
	v_mfma_f32_16x16x32_bf16 v[56:59], v[136:139], v[160:163], v[56:59]
	v_mfma_f32_16x16x32_bf16 v[44:47], v[128:131], v[168:171], v[44:47]
	v_mfma_f32_16x16x32_bf16 v[40:43], v[136:139], v[168:171], v[40:43]
	v_mfma_f32_16x16x32_bf16 v[28:31], v[128:131], v[176:179], v[28:31]
	v_mfma_f32_16x16x32_bf16 v[24:27], v[136:139], v[176:179], v[24:27]
	v_mfma_f32_16x16x32_bf16 v[12:15], v[128:131], v[184:187], v[12:15]
	v_mfma_f32_16x16x32_bf16 v[8:11], v[136:139], v[184:187], v[8:11]
	v_mfma_f32_16x16x32_bf16 v[60:63], v[132:135], v[164:167], v[60:63]
	v_mfma_f32_16x16x32_bf16 v[56:59], v[140:143], v[164:167], v[56:59]
	v_mfma_f32_16x16x32_bf16 v[44:47], v[132:135], v[172:175], v[44:47]
	v_mfma_f32_16x16x32_bf16 v[40:43], v[140:143], v[172:175], v[40:43]
	v_mfma_f32_16x16x32_bf16 v[28:31], v[132:135], v[180:183], v[28:31]
	v_mfma_f32_16x16x32_bf16 v[24:27], v[140:143], v[180:183], v[24:27]
	v_mfma_f32_16x16x32_bf16 v[12:15], v[132:135], v[188:191], v[12:15]
	v_mfma_f32_16x16x32_bf16 v[8:11], v[140:143], v[188:191], v[8:11]
	s_setprio 0
	s_setprio 1
	v_mfma_f32_16x16x32_bf16 v[52:55], v[144:147], v[160:163], v[52:55]
	v_mfma_f32_16x16x32_bf16 v[48:51], v[152:155], v[160:163], v[48:51]
	v_mfma_f32_16x16x32_bf16 v[36:39], v[144:147], v[168:171], v[36:39]
	v_mfma_f32_16x16x32_bf16 v[32:35], v[152:155], v[168:171], v[32:35]
	v_mfma_f32_16x16x32_bf16 v[20:23], v[144:147], v[176:179], v[20:23]
	v_mfma_f32_16x16x32_bf16 v[16:19], v[152:155], v[176:179], v[16:19]
	v_mfma_f32_16x16x32_bf16 v[4:7], v[144:147], v[184:187], v[4:7]
	v_mfma_f32_16x16x32_bf16 v[0:3], v[152:155], v[184:187], v[0:3]
	v_mfma_f32_16x16x32_bf16 v[52:55], v[148:151], v[164:167], v[52:55]
	v_mfma_f32_16x16x32_bf16 v[48:51], v[156:159], v[164:167], v[48:51]
	v_mfma_f32_16x16x32_bf16 v[36:39], v[148:151], v[172:175], v[36:39]
	v_mfma_f32_16x16x32_bf16 v[32:35], v[156:159], v[172:175], v[32:35]
	v_mfma_f32_16x16x32_bf16 v[20:23], v[148:151], v[180:183], v[20:23]
	v_mfma_f32_16x16x32_bf16 v[16:19], v[156:159], v[180:183], v[16:19]
	v_mfma_f32_16x16x32_bf16 v[4:7], v[148:151], v[188:191], v[4:7]
	v_mfma_f32_16x16x32_bf16 v[0:3], v[156:159], v[188:191], v[0:3]
	s_barrier
	s_setprio 0
	s_add_u32 s24, s24, 0x100
	s_addc_u32 s25, s25, 0
	s_add_u32 s23, s23, 0x100
	s_addc_u32 s33, s33, 0
	s_cmp_ge_i32 s51, s45
	s_cbranch_scc1 .LBB0_263

; #define PG8_STAGE(bufoff, gbase, voff) do { _Pragma("unroll") for (int _i = 0; _i < 2; ++_i) \
;         __builtin_amdgcn_global_load_lds((const unsigned*)((const char*)(gbase) + (voff)[_i]), (PG8_LAS unsigned*)(lds + (bufoff) + ldsw + _i * 8192), 16, 0, 0); } while (0)
; #define PG8_LDA(dst, b, h) do { _Pragma("unroll") for (int m = 0; m < 4; ++m) _Pragma("unroll") for (int k = 0; k < 2; ++k) dst[m][k] = *(const PG8_LAS bf16x8*)(lds + PG8_SA(b, h) + aoff + m * 2048 + k * 1024); } while (0)
; #define PG8_LDB(dst, b, h) do { _Pragma("unroll") for (int n = 0; n < 2; ++n) _Pragma("unroll") for (int k = 0; k < 2; ++k) dst[n][k] = *(const PG8_LAS bf16x8*)(lds + PG8_SB(b, h) + boff + n * 2048 + k * 1024); } while (0)
; #define PG8_WAIT_V(n) asm volatile("s_waitcnt vmcnt(" #n ")" ::: "memory")
; #define PG8_WAIT_L(n) asm volatile("s_waitcnt lgkmcnt(" #n ")" ::: "memory")
; #define PG8_BAR __builtin_amdgcn_s_barrier()
; #define PG8_SCHED __builtin_amdgcn_sched_barrier(0)
; template <class Epi, class Sched, bool ALIGN_EPI = false, bool SP2 = false>
; __device__ __forceinline__ void gemm_phase(PG8_LAS unsigned char* lds, const Gemm g, const Sched& S, const Epi& E) {
;     ...
;             const char* a1 = cA + (size_t)(t + 1) * kstep;
;             const char* a2 = last ? nA : cA + (size_t)(t + 2) * kstep; const char* b2 = last ? nB : cB + (size_t)(t + 2) * kstep;
;             const char* a3 = a2 + kstep; const char* b3 = b2 + kstep;
;             if (last && has_next) S.a_ready(nxt);
;             if constexpr (SP2) {
;             PG8_LDB(B0, 0, 0); PG8_LDB(B1, 0, 1); PG8_SCHED; PG8_LDA(At, 0, 0); PG8_STAGE(PG8_SA(1, 1), a1 + hstepA, voffA);
;             if (plast) PG8_WAIT_V(10); else PG8_WAIT_SEL(defer, 12, 16);
;             PG8_WAIT_L(0); PG8_BAR; PG8_MMA(0, 0, At, B0); PG8_MMA(0, 1, At, B1);
;             if constexpr (Epi::SPLIT) { if (defer) {
;                 E.second(acc, prev, rv1, wr, wc, fr, fq);
;                 _Pragma("unroll") for (int b = 0; b < 2; ++b) _Pragma("unroll") for (int m = 0; m < 4; ++m) _Pragma("unroll") for (int n = 0; n < 2; ++n) acc[1][b][m][n] = (f32x4){0.f, 0.f, 0.f, 0.f}; } }
;             PG8_BAR; PG8_SCHED;
;             PG8_LDA(At, 0, 1); PG8_STAGE(PG8_SB(0, 0), b2, voffB); PG8_STAGE(PG8_SB(0, 1), b2 + hstep, voffB); PG8_STAGE(PG8_SA(0, 0), a2, voffA);
;             if (plast) PG8_WAIT_V(10); else PG8_WAIT_SEL(defer, 16, 24);
.LBB0_259:
	s_add_u32 s30, s24, 0x80
	s_addc_u32 s31, s25, 0
	s_waitcnt lgkmcnt(0)
	s_and_b64 s[26:27], s[26:27], exec
	s_cselect_b32 s27, s7, s31
	s_cselect_b32 s26, s6, s30
	s_cselect_b32 s31, s21, s33
	s_cselect_b32 s30, s20, s23
	s_setprio 1
	s_barrier
	v_mfma_f32_16x16x32_bf16 v[124:127], v[144:147], v[184:187], v[124:127]
	v_mfma_f32_16x16x32_bf16 v[120:123], v[152:155], v[184:187], v[120:123]
	v_mfma_f32_16x16x32_bf16 v[108:111], v[144:147], v[176:179], v[108:111]
	v_mfma_f32_16x16x32_bf16 v[104:107], v[152:155], v[176:179], v[104:107]
	v_mfma_f32_16x16x32_bf16 v[92:95], v[144:147], v[168:171], v[92:95]
	v_mfma_f32_16x16x32_bf16 v[88:91], v[152:155], v[168:171], v[88:91]
	v_mfma_f32_16x16x32_bf16 v[76:79], v[144:147], v[160:163], v[76:79]
	v_mfma_f32_16x16x32_bf16 v[72:75], v[152:155], v[160:163], v[72:75]
	v_mfma_f32_16x16x32_bf16 v[124:127], v[148:151], v[188:191], v[124:127]
	v_mfma_f32_16x16x32_bf16 v[120:123], v[156:159], v[188:191], v[120:123]
	v_mfma_f32_16x16x32_bf16 v[108:111], v[148:151], v[180:183], v[108:111]
	v_mfma_f32_16x16x32_bf16 v[104:107], v[156:159], v[180:183], v[104:107]
	v_mfma_f32_16x16x32_bf16 v[92:95], v[148:151], v[172:175], v[92:95]
	v_mfma_f32_16x16x32_bf16 v[88:91], v[156:159], v[172:175], v[88:91]
	v_mfma_f32_16x16x32_bf16 v[76:79], v[148:151], v[164:167], v[76:79]
	v_mfma_f32_16x16x32_bf16 v[72:75], v[156:159], v[164:167], v[72:75]
	s_setprio 0
	s_setprio 1
	v_mfma_f32_16x16x32_bf16 v[116:119], v[128:131], v[184:187], v[116:119]
	v_mfma_f32_16x16x32_bf16 v[112:115], v[136:139], v[184:187], v[112:115]
	v_mfma_f32_16x16x32_bf16 v[100:103], v[128:131], v[176:179], v[100:103]
	v_mfma_f32_16x16x32_bf16 v[96:99], v[136:139], v[176:179], v[96:99]
	v_mfma_f32_16x16x32_bf16 v[84:87], v[128:131], v[168:171], v[84:87]
	v_mfma_f32_16x16x32_bf16 v[80:83], v[136:139], v[168:171], v[80:83]
	v_mfma_f32_16x16x32_bf16 v[68:71], v[128:131], v[160:163], v[68:71]
	v_mfma_f32_16x16x32_bf16 v[64:67], v[136:139], v[160:163], v[64:67]
	v_mfma_f32_16x16x32_bf16 v[116:119], v[132:135], v[188:191], v[116:119]
	v_mfma_f32_16x16x32_bf16 v[112:115], v[140:143], v[188:191], v[112:115]
	v_mfma_f32_16x16x32_bf16 v[100:103], v[132:135], v[180:183], v[100:103]
	v_mfma_f32_16x16x32_bf16 v[96:99], v[140:143], v[180:183], v[96:99]
	v_mfma_f32_16x16x32_bf16 v[84:87], v[132:135], v[172:175], v[84:87]
	v_mfma_f32_16x16x32_bf16 v[80:83], v[140:143], v[172:175], v[80:83]
	v_mfma_f32_16x16x32_bf16 v[68:71], v[132:135], v[164:167], v[68:71]
	v_mfma_f32_16x16x32_bf16 v[64:67], v[140:143], v[164:167], v[64:67]
	s_barrier
	s_setprio 0
	s_mov_b32 m0, s36
	v_lshl_add_u64 v[222:223], s[30:31], 0, v[192:193]
	v_lshl_add_u64 v[220:221], s[30:31], 0, v[204:205]
	s_add_u32 s30, s30, s12
	ds_read_b128 v[184:187], v240 offset:16384
	ds_read_b128 v[188:191], v240 offset:17408
	ds_read_b128 v[176:179], v240 offset:18432
	ds_read_b128 v[180:183], v240 offset:19456
	ds_read_b128 v[168:171], v240 offset:20480
	ds_read_b128 v[172:175], v240 offset:21504
	ds_read_b128 v[160:163], v240 offset:22528
	ds_read_b128 v[164:167], v240 offset:23552
	global_load_lds_dwordx4 v[222:223], off
	s_mov_b32 m0, s37
	s_addc_u32 s31, s31, s13
	global_load_lds_dwordx4 v[220:221], off
	v_lshl_add_u64 v[230:231], s[30:31], 0, v[192:193]
	s_mov_b32 m0, s38
	v_lshl_add_u64 v[228:229], s[30:31], 0, v[204:205]
	global_load_lds_dwordx4 v[230:231], off
	s_mov_b32 m0, s39
	v_lshl_add_u64 v[224:225], s[26:27], 0, v[208:209]
	global_load_lds_dwordx4 v[228:229], off
	s_mov_b32 m0, s35
	v_lshl_add_u64 v[226:227], s[26:27], 0, v[206:207]
	global_load_lds_dwordx4 v[224:225], off
	s_mov_b32 m0, s40
	s_mov_b64 s[30:31], -1
	global_load_lds_dwordx4 v[226:227], off
	s_and_b64 vcc, exec, s[28:29]
	s_cbranch_vccz .LBB0_261
	s_waitcnt vmcnt(8)
	s_mov_b64 s[30:31], 0

; #define PG8_STAGE(bufoff, gbase, voff) do { _Pragma("unroll") for (int _i = 0; _i < 2; ++_i) \
;         __builtin_amdgcn_global_load_lds((const unsigned*)((const char*)(gbase) + (voff)[_i]), (PG8_LAS unsigned*)(lds + (bufoff) + ldsw + _i * 8192), 16, 0, 0); } while (0)
; #define PG8_LDA(dst, b, h) do { _Pragma("unroll") for (int m = 0; m < 4; ++m) _Pragma("unroll") for (int k = 0; k < 2; ++k) dst[m][k] = *(const PG8_LAS bf16x8*)(lds + PG8_SA(b, h) + aoff + m * 2048 + k * 1024); } while (0)
; #define PG8_LDB(dst, b, h) do { _Pragma("unroll") for (int n = 0; n < 2; ++n) _Pragma("unroll") for (int k = 0; k < 2; ++k) dst[n][k] = *(const PG8_LAS bf16x8*)(lds + PG8_SB(b, h) + boff + n * 2048 + k * 1024); } while (0)
; #define PG8_WAIT_V(n) asm volatile("s_waitcnt vmcnt(" #n ")" ::: "memory")
; #define PG8_WAIT_L(n) asm volatile("s_waitcnt lgkmcnt(" #n ")" ::: "memory")
; #define PG8_BAR __builtin_amdgcn_s_barrier()
; #define PG8_SCHED __builtin_amdgcn_sched_barrier(0)
; template <class Epi, class Sched, bool ALIGN_EPI = false, bool SP2 = false>
; __device__ __forceinline__ void gemm_phase(PG8_LAS unsigned char* lds, const Gemm g, const Sched& S, const Epi& E) {
;     ...
;             const char* a1 = cA + (size_t)(t + 1) * kstep;
;             const char* a2 = last ? nA : cA + (size_t)(t + 2) * kstep; const char* b2 = last ? nB : cB + (size_t)(t + 2) * kstep;
;             const char* a3 = a2 + kstep; const char* b3 = b2 + kstep;
;             if (last && has_next) S.a_ready(nxt);
;             if constexpr (SP2) {
;             PG8_LDB(B0, 0, 0); PG8_LDB(B1, 0, 1); PG8_SCHED; PG8_LDA(At, 0, 0); PG8_STAGE(PG8_SA(1, 1), a1 + hstepA, voffA);
;             if (plast) PG8_WAIT_V(10); else PG8_WAIT_SEL(defer, 12, 16);
;             PG8_WAIT_L(0); PG8_BAR; PG8_MMA(0, 0, At, B0); PG8_MMA(0, 1, At, B1);
;             if constexpr (Epi::SPLIT) { if (defer) {
;                 E.second(acc, prev, rv1, wr, wc, fr, fq);
;                 _Pragma("unroll") for (int b = 0; b < 2; ++b) _Pragma("unroll") for (int m = 0; m < 4; ++m) _Pragma("unroll") for (int n = 0; n < 2; ++n) acc[1][b][m][n] = (f32x4){0.f, 0.f, 0.f, 0.f}; } }
;             PG8_BAR; PG8_SCHED;
;             PG8_LDA(At, 0, 1); PG8_STAGE(PG8_SB(0, 0), b2, voffB); PG8_STAGE(PG8_SB(0, 1), b2 + hstep, voffB); PG8_STAGE(PG8_SA(0, 0), a2, voffA);
;             if (plast) PG8_WAIT_V(10); else PG8_WAIT_SEL(defer, 16, 24);
.Lpk_op_353:
	s_add_i32 s51, s28, 2
	s_add_u32 s52, s0, 0x80
	s_addc_u32 s29, s1, 0
	s_add_i32 s54, 0, 0x10000
	s_cmp_eq_u32 s45, s28
	s_cselect_b32 s29, s9, s29
	s_cselect_b32 s28, s8, s52
	s_cselect_b32 s53, s27, s50
	s_cselect_b32 s52, s26, s33
	s_add_i32 s55, 0, 0x14000
	v_add_u32_e32 v140, s54, v186
	v_add_u32_e32 v166, s55, v186
	ds_read_b128 v[128:131], v140
	ds_read_b128 v[132:135], v140 offset:1024
	ds_read_b128 v[136:139], v140 offset:2048
	ds_read_b128 v[140:143], v140 offset:3072
	ds_read_b128 v[144:147], v166
	ds_read_b128 v[148:151], v166 offset:1024
	ds_read_b128 v[152:155], v166 offset:2048
	ds_read_b128 v[166:169], v166 offset:3072
	v_lshl_add_u64 v[182:183], s[0:1], 0, v[162:163]
	s_add_i32 m0, s35, 0xc000
	ds_read_b128 v[170:173], v187
	ds_read_b128 v[174:177], v187 offset:1024
	ds_read_b128 v[178:181], v187 offset:2048
	ds_read_b128 v[188:191], v187 offset:3072
	ds_read_b128 v[204:207], v187 offset:4096
	ds_read_b128 v[208:211], v187 offset:5120
	ds_read_b128 v[212:215], v187 offset:6144
	ds_read_b128 v[216:219], v187 offset:7168
	global_load_lds_dwordx4 v[182:183], off
	v_lshl_add_u64 v[182:183], s[0:1], 0, v[164:165]
	s_add_i32 m0, s35, 0xe000
	s_nop 0
	global_load_lds_dwordx4 v[182:183], off
	s_waitcnt vmcnt(8)
	s_waitcnt lgkmcnt(0)
	s_setprio 1
	s_barrier
	v_mfma_f32_16x16x32_bf16 v[120:123], v[128:131], v[170:173], 0
	v_mfma_f32_16x16x32_bf16 v[124:127], v[136:139], v[170:173], 0
	v_mfma_f32_16x16x32_bf16 v[108:111], v[128:131], v[178:181], 0
	v_mfma_f32_16x16x32_bf16 v[104:107], v[136:139], v[178:181], 0
	v_mfma_f32_16x16x32_bf16 v[92:95], v[128:131], v[204:207], 0
	v_mfma_f32_16x16x32_bf16 v[88:91], v[136:139], v[204:207], 0
	v_mfma_f32_16x16x32_bf16 v[76:79], v[128:131], v[212:215], 0
	v_mfma_f32_16x16x32_bf16 v[72:75], v[136:139], v[212:215], 0
	v_mfma_f32_16x16x32_bf16 v[120:123], v[132:135], v[174:177], v[120:123]
	v_mfma_f32_16x16x32_bf16 v[124:127], v[140:143], v[174:177], v[124:127]
	v_mfma_f32_16x16x32_bf16 v[108:111], v[132:135], v[188:191], v[108:111]
	v_mfma_f32_16x16x32_bf16 v[104:107], v[140:143], v[188:191], v[104:107]
	v_mfma_f32_16x16x32_bf16 v[92:95], v[132:135], v[208:211], v[92:95]
	v_mfma_f32_16x16x32_bf16 v[88:91], v[140:143], v[208:211], v[88:91]
	v_mfma_f32_16x16x32_bf16 v[76:79], v[132:135], v[216:219], v[76:79]
	v_mfma_f32_16x16x32_bf16 v[72:75], v[140:143], v[216:219], v[72:75]
	s_setprio 0
	s_setprio 1
	v_mfma_f32_16x16x32_bf16 v[116:119], v[144:147], v[170:173], 0
	v_mfma_f32_16x16x32_bf16 v[112:115], v[152:155], v[170:173], 0
	v_mfma_f32_16x16x32_bf16 v[100:103], v[144:147], v[178:181], 0
	v_mfma_f32_16x16x32_bf16 v[96:99], v[152:155], v[178:181], 0
	v_mfma_f32_16x16x32_bf16 v[84:87], v[144:147], v[204:207], 0
	v_mfma_f32_16x16x32_bf16 v[80:83], v[152:155], v[204:207], 0
	v_mfma_f32_16x16x32_bf16 v[68:71], v[144:147], v[212:215], 0
	v_mfma_f32_16x16x32_bf16 v[64:67], v[152:155], v[212:215], 0
	v_mfma_f32_16x16x32_bf16 v[116:119], v[148:151], v[174:177], v[116:119]
	v_mfma_f32_16x16x32_bf16 v[112:115], v[166:169], v[174:177], v[112:115]
	v_mfma_f32_16x16x32_bf16 v[100:103], v[148:151], v[188:191], v[100:103]
	v_mfma_f32_16x16x32_bf16 v[96:99], v[166:169], v[188:191], v[96:99]
	v_mfma_f32_16x16x32_bf16 v[84:87], v[148:151], v[208:211], v[84:87]
	v_mfma_f32_16x16x32_bf16 v[80:83], v[166:169], v[208:211], v[80:83]
	v_mfma_f32_16x16x32_bf16 v[68:71], v[148:151], v[216:219], v[68:71]
	v_mfma_f32_16x16x32_bf16 v[64:67], v[166:169], v[216:219], v[64:67]
	s_barrier
	s_setprio 0
	s_add_i32 s54, s54, s34
	v_lshl_add_u64 v[182:183], s[52:53], 0, v[192:193]
	s_mov_b32 m0, s54
	ds_read_b128 v[170:173], v187 offset:16384
	ds_read_b128 v[174:177], v187 offset:17408
	ds_read_b128 v[178:181], v187 offset:18432
	ds_read_b128 v[188:191], v187 offset:19456
	ds_read_b128 v[204:207], v187 offset:20480
	ds_read_b128 v[208:211], v187 offset:21504
	ds_read_b128 v[212:215], v187 offset:22528
	ds_read_b128 v[216:219], v187 offset:23552
	global_load_lds_dwordx4 v[182:183], off
	s_add_i32 m0, s54, 0x2000
	v_lshl_add_u64 v[194:195], s[52:53], 0, v[156:157]
	s_add_u32 s52, s52, s16
	s_addc_u32 s53, s53, s17
	s_add_i32 s54, s55, s34
	global_load_lds_dwordx4 v[194:195], off
	v_lshl_add_u64 v[200:201], s[52:53], 0, v[192:193]
	s_mov_b32 m0, s54
	v_lshl_add_u64 v[202:203], s[52:53], 0, v[156:157]
	global_load_lds_dwordx4 v[200:201], off
	s_add_i32 m0, s54, 0x2000
	v_lshl_add_u64 v[220:221], s[28:29], 0, v[160:161]
	global_load_lds_dwordx4 v[202:203], off
	s_mov_b32 m0, s35
	v_lshl_add_u64 v[222:223], s[28:29], 0, v[158:159]
	global_load_lds_dwordx4 v[220:221], off
	s_mov_b32 m0, s36
	s_nop 0
	global_load_lds_dwordx4 v[222:223], off
	s_waitcnt vmcnt(8)
	s_waitcnt lgkmcnt(0)
	s_setprio 1
	s_barrier
; #define PG8_STAGE(bufoff, gbase, voff) do { _Pragma("unroll") for (int _i = 0; _i < 2; ++_i) \
;         __builtin_amdgcn_global_load_lds((const unsigned*)((const char*)(gbase) + (voff)[_i]), (PG8_LAS unsigned*)(lds + (bufoff) + ldsw + _i * 8192), 16, 0, 0); } while (0)
; #define PG8_LDA(dst, b, h) do { _Pragma("unroll") for (int m = 0; m < 4; ++m) _Pragma("unroll") for (int k = 0; k < 2; ++k) dst[m][k] = *(const PG8_LAS bf16x8*)(lds + PG8_SA(b, h) + aoff + m * 2048 + k * 1024); } while (0)
; #define PG8_LDB(dst, b, h) do { _Pragma("unroll") for (int n = 0; n < 2; ++n) _Pragma("unroll") for (int k = 0; k < 2; ++k) dst[n][k] = *(const PG8_LAS bf16x8*)(lds + PG8_SB(b, h) + boff + n * 2048 + k * 1024); } while (0)
; #define PG8_MMA(ai, bj, At, Bt) do { __builtin_amdgcn_s_setprio(1); _Pragma("unroll") for (int m = 0; m < 4; ++m) _Pragma("unroll") for (int n = 0; n < 2; ++n) _Pragma("unroll") for (int k = 0; k < 2; ++k) \
;         acc[ai][bj][m][n] = __builtin_amdgcn_mfma_f32_16x16x32_bf16(Bt[n][k], At[m][k], acc[ai][bj][m][n], 0, 0, 0); __builtin_amdgcn_s_setprio(0); } while (0)
; #define PG8_WAIT_V(n) asm volatile("s_waitcnt vmcnt(" #n ")" ::: "memory")
; #define PG8_WAIT_SEL(d, w4, w8) do { if constexpr (Epi::SPLIT) { if (d) { if constexpr (Epi::NSH == 4) PG8_WAIT_V(w4); else PG8_WAIT_V(w8); } else PG8_WAIT_V(8); } else PG8_WAIT_V(8); } while (0)
; #define PG8_WAIT_L(n) asm volatile("s_waitcnt lgkmcnt(" #n ")" ::: "memory")
; #define PG8_BAR __builtin_amdgcn_s_barrier()
; #define PG8_SCHED __builtin_amdgcn_sched_barrier(0)
; template <class Epi, class Sched, bool ALIGN_EPI = false, bool SP2 = false>
; __device__ __forceinline__ void gemm_phase(PG8_LAS unsigned char* lds, const Gemm g, const Sched& S, const Epi& E) {
;     ...
;             if (plast) PG8_WAIT_V(10); else PG8_WAIT_SEL(defer, 16, 24);
;             PG8_WAIT_L(0); PG8_BAR; PG8_MMA(1, 0, At, B0); PG8_MMA(1, 1, At, B1); PG8_BAR; PG8_SCHED;
;             PG8_LDB(B0, 1, 0); PG8_LDB(B1, 1, 1); PG8_SCHED; PG8_LDA(At, 1, 0); PG8_STAGE(PG8_SA(0, 1), a2 + hstepA, voffA);
;             PG8_WAIT_SEL(defer, 12, 16); PG8_WAIT_L(0); PG8_BAR; PG8_MMA(0, 0, At, B0); PG8_MMA(0, 1, At, B1); PG8_BAR; PG8_SCHED;
	v_mfma_f32_16x16x32_bf16 v[60:63], v[128:131], v[170:173], 0
	v_mfma_f32_16x16x32_bf16 v[56:59], v[136:139], v[170:173], 0
	v_mfma_f32_16x16x32_bf16 v[44:47], v[128:131], v[178:181], 0
	v_mfma_f32_16x16x32_bf16 v[40:43], v[136:139], v[178:181], 0
	v_mfma_f32_16x16x32_bf16 v[28:31], v[128:131], v[204:207], 0
	v_mfma_f32_16x16x32_bf16 v[24:27], v[136:139], v[204:207], 0
	v_mfma_f32_16x16x32_bf16 v[12:15], v[128:131], v[212:215], 0
	v_mfma_f32_16x16x32_bf16 v[8:11], v[136:139], v[212:215], 0
	v_mfma_f32_16x16x32_bf16 v[60:63], v[132:135], v[174:177], v[60:63]
	v_mfma_f32_16x16x32_bf16 v[56:59], v[140:143], v[174:177], v[56:59]
	v_mfma_f32_16x16x32_bf16 v[44:47], v[132:135], v[188:191], v[44:47]
	v_mfma_f32_16x16x32_bf16 v[40:43], v[140:143], v[188:191], v[40:43]
	v_mfma_f32_16x16x32_bf16 v[28:31], v[132:135], v[208:211], v[28:31]
	v_mfma_f32_16x16x32_bf16 v[24:27], v[140:143], v[208:211], v[24:27]
	v_mfma_f32_16x16x32_bf16 v[12:15], v[132:135], v[216:219], v[12:15]
	v_mfma_f32_16x16x32_bf16 v[8:11], v[140:143], v[216:219], v[8:11]
	s_setprio 0
	s_setprio 1
	v_mfma_f32_16x16x32_bf16 v[52:55], v[144:147], v[170:173], 0
	v_mfma_f32_16x16x32_bf16 v[48:51], v[152:155], v[170:173], 0
	v_mfma_f32_16x16x32_bf16 v[36:39], v[144:147], v[178:181], 0
	v_mfma_f32_16x16x32_bf16 v[32:35], v[152:155], v[178:181], 0
	v_mfma_f32_16x16x32_bf16 v[20:23], v[144:147], v[204:207], 0
	v_mfma_f32_16x16x32_bf16 v[16:19], v[152:155], v[204:207], 0
	v_mfma_f32_16x16x32_bf16 v[4:7], v[144:147], v[212:215], 0
	v_mfma_f32_16x16x32_bf16 v[0:3], v[152:155], v[212:215], 0
	v_mfma_f32_16x16x32_bf16 v[52:55], v[148:151], v[174:177], v[52:55]
	v_mfma_f32_16x16x32_bf16 v[48:51], v[166:169], v[174:177], v[48:51]
	v_mfma_f32_16x16x32_bf16 v[36:39], v[148:151], v[188:191], v[36:39]
	v_mfma_f32_16x16x32_bf16 v[32:35], v[166:169], v[188:191], v[32:35]
	v_mfma_f32_16x16x32_bf16 v[20:23], v[148:151], v[208:211], v[20:23]
	v_mfma_f32_16x16x32_bf16 v[16:19], v[166:169], v[208:211], v[16:19]
	v_mfma_f32_16x16x32_bf16 v[4:7], v[148:151], v[216:219], v[4:7]
	v_mfma_f32_16x16x32_bf16 v[0:3], v[166:169], v[216:219], v[0:3]
	s_barrier
	s_setprio 0
	s_add_i32 s52, 0, 0x18000
	s_add_i32 s53, 0, 0x1c000
	v_add_u32_e32 v140, s52, v186
	v_add_u32_e32 v166, s53, v186
	ds_read_b128 v[128:131], v140
	ds_read_b128 v[132:135], v140 offset:1024
	ds_read_b128 v[136:139], v140 offset:2048
	ds_read_b128 v[140:143], v140 offset:3072
	ds_read_b128 v[144:147], v166
	ds_read_b128 v[148:151], v166 offset:1024
	ds_read_b128 v[152:155], v166 offset:2048
	ds_read_b128 v[166:169], v166 offset:3072
	s_add_u32 s28, s28, s12
	s_addc_u32 s29, s29, s13
	s_mov_b32 m0, s37
	v_lshl_add_u64 v[224:225], s[28:29], 0, v[160:161]
	ds_read_b128 v[170:173], v187 offset:32768
	ds_read_b128 v[174:177], v187 offset:33792
	ds_read_b128 v[178:181], v187 offset:34816
	ds_read_b128 v[188:191], v187 offset:35840
	ds_read_b128 v[204:207], v187 offset:36864
	ds_read_b128 v[208:211], v187 offset:37888
	ds_read_b128 v[212:215], v187 offset:38912
	ds_read_b128 v[216:219], v187 offset:39936
	global_load_lds_dwordx4 v[224:225], off
	v_lshl_add_u64 v[224:225], s[28:29], 0, v[158:159]
	s_mov_b32 m0, s38
	s_nop 0
	global_load_lds_dwordx4 v[224:225], off
	s_waitcnt vmcnt(8)
	s_waitcnt lgkmcnt(0)
	s_setprio 1
	s_barrier
	v_mfma_f32_16x16x32_bf16 v[120:123], v[128:131], v[170:173], v[120:123]
	v_mfma_f32_16x16x32_bf16 v[124:127], v[136:139], v[170:173], v[124:127]
	v_mfma_f32_16x16x32_bf16 v[108:111], v[128:131], v[178:181], v[108:111]
	v_mfma_f32_16x16x32_bf16 v[104:107], v[136:139], v[178:181], v[104:107]
	v_mfma_f32_16x16x32_bf16 v[92:95], v[128:131], v[204:207], v[92:95]
	v_mfma_f32_16x16x32_bf16 v[88:91], v[136:139], v[204:207], v[88:91]
	v_mfma_f32_16x16x32_bf16 v[76:79], v[128:131], v[212:215], v[76:79]
	v_mfma_f32_16x16x32_bf16 v[72:75], v[136:139], v[212:215], v[72:75]
	v_mfma_f32_16x16x32_bf16 v[120:123], v[132:135], v[174:177], v[120:123]
	v_mfma_f32_16x16x32_bf16 v[124:127], v[140:143], v[174:177], v[124:127]
	v_mfma_f32_16x16x32_bf16 v[108:111], v[132:135], v[188:191], v[108:111]
	v_mfma_f32_16x16x32_bf16 v[104:107], v[140:143], v[188:191], v[104:107]
	v_mfma_f32_16x16x32_bf16 v[92:95], v[132:135], v[208:211], v[92:95]
	v_mfma_f32_16x16x32_bf16 v[88:91], v[140:143], v[208:211], v[88:91]
	v_mfma_f32_16x16x32_bf16 v[76:79], v[132:135], v[216:219], v[76:79]
	v_mfma_f32_16x16x32_bf16 v[72:75], v[140:143], v[216:219], v[72:75]
	s_setprio 0
	s_setprio 1
	v_mfma_f32_16x16x32_bf16 v[116:119], v[144:147], v[170:173], v[116:119]
	v_mfma_f32_16x16x32_bf16 v[112:115], v[152:155], v[170:173], v[112:115]
	v_mfma_f32_16x16x32_bf16 v[100:103], v[144:147], v[178:181], v[100:103]
	v_mfma_f32_16x16x32_bf16 v[96:99], v[152:155], v[178:181], v[96:99]
	v_mfma_f32_16x16x32_bf16 v[84:87], v[144:147], v[204:207], v[84:87]
	v_mfma_f32_16x16x32_bf16 v[80:83], v[152:155], v[204:207], v[80:83]
	v_mfma_f32_16x16x32_bf16 v[68:71], v[144:147], v[212:215], v[68:71]
	v_mfma_f32_16x16x32_bf16 v[64:67], v[152:155], v[212:215], v[64:67]
	v_mfma_f32_16x16x32_bf16 v[116:119], v[148:151], v[174:177], v[116:119]
	v_mfma_f32_16x16x32_bf16 v[112:115], v[166:169], v[174:177], v[112:115]
	v_mfma_f32_16x16x32_bf16 v[100:103], v[148:151], v[188:191], v[100:103]
	v_mfma_f32_16x16x32_bf16 v[96:99], v[166:169], v[188:191], v[96:99]
	v_mfma_f32_16x16x32_bf16 v[84:87], v[148:151], v[208:211], v[84:87]
	v_mfma_f32_16x16x32_bf16 v[80:83], v[166:169], v[208:211], v[80:83]
	v_mfma_f32_16x16x32_bf16 v[68:71], v[148:151], v[216:219], v[68:71]
	v_mfma_f32_16x16x32_bf16 v[64:67], v[166:169], v[216:219], v[64:67]
	s_barrier
; #define PG8_STAGE(bufoff, gbase, voff) do { _Pragma("unroll") for (int _i = 0; _i < 2; ++_i) \
;         __builtin_amdgcn_global_load_lds((const unsigned*)((const char*)(gbase) + (voff)[_i]), (PG8_LAS unsigned*)(lds + (bufoff) + ldsw + _i * 8192), 16, 0, 0); } while (0)
; #define PG8_LDA(dst, b, h) do { _Pragma("unroll") for (int m = 0; m < 4; ++m) _Pragma("unroll") for (int k = 0; k < 2; ++k) dst[m][k] = *(const PG8_LAS bf16x8*)(lds + PG8_SA(b, h) + aoff + m * 2048 + k * 1024); } while (0)
; #define PG8_LDB(dst, b, h) do { _Pragma("unroll") for (int n = 0; n < 2; ++n) _Pragma("unroll") for (int k = 0; k < 2; ++k) dst[n][k] = *(const PG8_LAS bf16x8*)(lds + PG8_SB(b, h) + boff + n * 2048 + k * 1024); } while (0)
; #define PG8_MMA(ai, bj, At, Bt) do { __builtin_amdgcn_s_setprio(1); _Pragma("unroll") for (int m = 0; m < 4; ++m) _Pragma("unroll") for (int n = 0; n < 2; ++n) _Pragma("unroll") for (int k = 0; k < 2; ++k) \
;         acc[ai][bj][m][n] = __builtin_amdgcn_mfma_f32_16x16x32_bf16(Bt[n][k], At[m][k], acc[ai][bj][m][n], 0, 0, 0); __builtin_amdgcn_s_setprio(0); } while (0)
; #define PG8_WAIT_V(n) asm volatile("s_waitcnt vmcnt(" #n ")" ::: "memory")
; #define PG8_WAIT_SEL(d, w4, w8) do { if constexpr (Epi::SPLIT) { if (d) { if constexpr (Epi::NSH == 4) PG8_WAIT_V(w4); else PG8_WAIT_V(w8); } else PG8_WAIT_V(8); } else PG8_WAIT_V(8); } while (0)
; #define PG8_WAIT_L(n) asm volatile("s_waitcnt lgkmcnt(" #n ")" ::: "memory")
; #define PG8_BAR __builtin_amdgcn_s_barrier()
; #define PG8_SCHED __builtin_amdgcn_sched_barrier(0)
; template <class Epi, class Sched, bool ALIGN_EPI = false, bool SP2 = false>
; __device__ __forceinline__ void gemm_phase(PG8_LAS unsigned char* lds, const Gemm g, const Sched& S, const Epi& E) {
;     ...
;             PG8_LDB(B0, 0, 0); PG8_LDB(B1, 0, 1); PG8_SCHED; PG8_LDA(At, 0, 0); PG8_STAGE(PG8_SA(1, 1), a1 + hstepA, voffA);
;             if (plast) PG8_WAIT_V(10); else PG8_WAIT_SEL(defer, 12, 16);
;     ...
;             PG8_LDA(At, 1, 1); PG8_STAGE(PG8_SB(1, 0), b3, voffB); PG8_STAGE(PG8_SB(1, 1), b3 + hstep, voffB); PG8_STAGE(PG8_SA(1, 0), a3, voffA);
;             PG8_WAIT_V(8); PG8_WAIT_L(0); PG8_BAR; PG8_MMA(1, 0, At, B0); PG8_MMA(1, 1, At, B1); PG8_BAR; PG8_SCHED;
	s_setprio 0
	s_add_i32 s28, s52, s34
	v_lshl_add_u64 v[182:183], v[182:183], 0, s[90:91]
	s_mov_b32 m0, s28
	ds_read_b128 v[170:173], v187 offset:49152
	ds_read_b128 v[174:177], v187 offset:50176
	ds_read_b128 v[178:181], v187 offset:51200
	ds_read_b128 v[188:191], v187 offset:52224
	ds_read_b128 v[204:207], v187 offset:53248
	ds_read_b128 v[208:211], v187 offset:54272
	ds_read_b128 v[212:215], v187 offset:55296
	ds_read_b128 v[216:219], v187 offset:56320
	global_load_lds_dwordx4 v[182:183], off
	v_lshl_add_u64 v[182:183], v[194:195], 0, s[90:91]
	s_add_i32 m0, s28, 0x2000
	s_add_i32 s28, s53, s34
	global_load_lds_dwordx4 v[182:183], off
	v_lshl_add_u64 v[182:183], v[200:201], 0, s[90:91]
	s_mov_b32 m0, s28
	s_nop 0
	global_load_lds_dwordx4 v[182:183], off
	v_lshl_add_u64 v[182:183], v[202:203], 0, s[90:91]
	s_add_i32 m0, s28, 0x2000
	s_nop 0
	global_load_lds_dwordx4 v[182:183], off
	v_lshl_add_u64 v[182:183], v[220:221], 0, s[90:91]
	s_mov_b32 m0, s43
	s_nop 0
	global_load_lds_dwordx4 v[182:183], off
	v_lshl_add_u64 v[182:183], v[222:223], 0, s[90:91]
	s_mov_b32 m0, s44
	s_nop 0
	global_load_lds_dwordx4 v[182:183], off
	s_waitcnt vmcnt(8)
	s_waitcnt lgkmcnt(0)
	s_setprio 1
	s_barrier
	v_mfma_f32_16x16x32_bf16 v[60:63], v[128:131], v[170:173], v[60:63]
	v_mfma_f32_16x16x32_bf16 v[56:59], v[136:139], v[170:173], v[56:59]
	v_mfma_f32_16x16x32_bf16 v[44:47], v[128:131], v[178:181], v[44:47]
	v_mfma_f32_16x16x32_bf16 v[40:43], v[136:139], v[178:181], v[40:43]
	v_mfma_f32_16x16x32_bf16 v[28:31], v[128:131], v[204:207], v[28:31]
	v_mfma_f32_16x16x32_bf16 v[24:27], v[136:139], v[204:207], v[24:27]
	v_mfma_f32_16x16x32_bf16 v[12:15], v[128:131], v[212:215], v[12:15]
	v_mfma_f32_16x16x32_bf16 v[8:11], v[136:139], v[212:215], v[8:11]
	v_mfma_f32_16x16x32_bf16 v[60:63], v[132:135], v[174:177], v[60:63]
	v_mfma_f32_16x16x32_bf16 v[56:59], v[140:143], v[174:177], v[56:59]
	v_mfma_f32_16x16x32_bf16 v[44:47], v[132:135], v[188:191], v[44:47]
	v_mfma_f32_16x16x32_bf16 v[40:43], v[140:143], v[188:191], v[40:43]
	v_mfma_f32_16x16x32_bf16 v[28:31], v[132:135], v[208:211], v[28:31]
	v_mfma_f32_16x16x32_bf16 v[24:27], v[140:143], v[208:211], v[24:27]
	v_mfma_f32_16x16x32_bf16 v[12:15], v[132:135], v[216:219], v[12:15]
	v_mfma_f32_16x16x32_bf16 v[8:11], v[140:143], v[216:219], v[8:11]
	s_setprio 0
	s_setprio 1
	v_mfma_f32_16x16x32_bf16 v[52:55], v[144:147], v[170:173], v[52:55]
	v_mfma_f32_16x16x32_bf16 v[48:51], v[152:155], v[170:173], v[48:51]
	v_mfma_f32_16x16x32_bf16 v[36:39], v[144:147], v[178:181], v[36:39]
	v_mfma_f32_16x16x32_bf16 v[32:35], v[152:155], v[178:181], v[32:35]
	v_mfma_f32_16x16x32_bf16 v[20:23], v[144:147], v[204:207], v[20:23]
	v_mfma_f32_16x16x32_bf16 v[16:19], v[152:155], v[204:207], v[16:19]
	v_mfma_f32_16x16x32_bf16 v[4:7], v[144:147], v[212:215], v[4:7]
	v_mfma_f32_16x16x32_bf16 v[0:3], v[152:155], v[212:215], v[0:3]
	v_mfma_f32_16x16x32_bf16 v[52:55], v[148:151], v[174:177], v[52:55]
	v_mfma_f32_16x16x32_bf16 v[48:51], v[166:169], v[174:177], v[48:51]
	v_mfma_f32_16x16x32_bf16 v[36:39], v[148:151], v[188:191], v[36:39]
	v_mfma_f32_16x16x32_bf16 v[32:35], v[166:169], v[188:191], v[32:35]
	v_mfma_f32_16x16x32_bf16 v[20:23], v[148:151], v[208:211], v[20:23]
	v_mfma_f32_16x16x32_bf16 v[16:19], v[166:169], v[208:211], v[16:19]
	v_mfma_f32_16x16x32_bf16 v[4:7], v[148:151], v[216:219], v[4:7]
	v_mfma_f32_16x16x32_bf16 v[0:3], v[166:169], v[216:219], v[0:3]
	s_barrier
	s_setprio 0
	s_add_u32 s0, s0, 0x100
	s_addc_u32 s1, s1, 0
	s_add_u32 s33, s33, 0x100
	s_addc_u32 s50, s50, 0
	s_cmp_ge_i32 s51, s40
	s_mov_b32 s28, s51
	s_cbranch_scc0 .LBB0_353
	s_branch .LBB0_354
.LBB0_353:
	s_add_i32 s51, s28, 2
	s_add_u32 s52, s0, 0x80
	s_addc_u32 s29, s1, 0
	s_add_i32 s54, 0, 0x10000
	s_cmp_eq_u32 s45, s28
	s_cselect_b32 s29, s9, s29
	s_cselect_b32 s28, s8, s52
	s_cselect_b32 s53, s27, s50
	s_cselect_b32 s52, s26, s33
	s_add_i32 s55, 0, 0x14000
	v_add_u32_e32 v140, s54, v186
	v_add_u32_e32 v166, s55, v186
	ds_read_b128 v[128:131], v140
	ds_read_b128 v[132:135], v140 offset:1024
	ds_read_b128 v[136:139], v140 offset:2048
	ds_read_b128 v[140:143], v140 offset:3072
	ds_read_b128 v[144:147], v166
	ds_read_b128 v[148:151], v166 offset:1024
	ds_read_b128 v[152:155], v166 offset:2048
	ds_read_b128 v[166:169], v166 offset:3072
	v_lshl_add_u64 v[182:183], s[0:1], 0, v[162:163]
	s_add_i32 m0, s35, 0xc000
	ds_read_b128 v[170:173], v187
	ds_read_b128 v[174:177], v187 offset:1024
	ds_read_b128 v[178:181], v187 offset:2048
	ds_read_b128 v[188:191], v187 offset:3072
	ds_read_b128 v[204:207], v187 offset:4096
	ds_read_b128 v[208:211], v187 offset:5120
	ds_read_b128 v[212:215], v187 offset:6144
	ds_read_b128 v[216:219], v187 offset:7168
	global_load_lds_dwordx4 v[182:183], off
	v_lshl_add_u64 v[182:183], s[0:1], 0, v[164:165]
	s_add_i32 m0, s35, 0xe000
	s_nop 0
	global_load_lds_dwordx4 v[182:183], off
	s_waitcnt vmcnt(8)
	s_waitcnt lgkmcnt(0)
	s_setprio 1
	s_barrier
; #define PG8_STAGE(bufoff, gbase, voff) do { _Pragma("unroll") for (int _i = 0; _i < 2; ++_i) \
;         __builtin_amdgcn_global_load_lds((const unsigned*)((const char*)(gbase) + (voff)[_i]), (PG8_LAS unsigned*)(lds + (bufoff) + ldsw + _i * 8192), 16, 0, 0); } while (0)
; #define PG8_LDA(dst, b, h) do { _Pragma("unroll") for (int m = 0; m < 4; ++m) _Pragma("unroll") for (int k = 0; k < 2; ++k) dst[m][k] = *(const PG8_LAS bf16x8*)(lds + PG8_SA(b, h) + aoff + m * 2048 + k * 1024); } while (0)
; #define PG8_MMA(ai, bj, At, Bt) do { __builtin_amdgcn_s_setprio(1); _Pragma("unroll") for (int m = 0; m < 4; ++m) _Pragma("unroll") for (int n = 0; n < 2; ++n) _Pragma("unroll") for (int k = 0; k < 2; ++k) \
;         acc[ai][bj][m][n] = __builtin_amdgcn_mfma_f32_16x16x32_bf16(Bt[n][k], At[m][k], acc[ai][bj][m][n], 0, 0, 0); __builtin_amdgcn_s_setprio(0); } while (0)
; #define PG8_WAIT_V(n) asm volatile("s_waitcnt vmcnt(" #n ")" ::: "memory")
; #define PG8_WAIT_SEL(d, w4, w8) do { if constexpr (Epi::SPLIT) { if (d) { if constexpr (Epi::NSH == 4) PG8_WAIT_V(w4); else PG8_WAIT_V(w8); } else PG8_WAIT_V(8); } else PG8_WAIT_V(8); } while (0)
; #define PG8_WAIT_L(n) asm volatile("s_waitcnt lgkmcnt(" #n ")" ::: "memory")
; #define PG8_BAR __builtin_amdgcn_s_barrier()
; #define PG8_SCHED __builtin_amdgcn_sched_barrier(0)
; template <class Epi, class Sched, bool ALIGN_EPI = false, bool SP2 = false>
; __device__ __forceinline__ void gemm_phase(PG8_LAS unsigned char* lds, const Gemm g, const Sched& S, const Epi& E) {
;     ...
;             PG8_WAIT_L(0); PG8_BAR; PG8_MMA(0, 0, At, B0); PG8_MMA(0, 1, At, B1);
;             if constexpr (Epi::SPLIT) { if (defer) {
;                 E.second(acc, prev, rv1, wr, wc, fr, fq);
;                 _Pragma("unroll") for (int b = 0; b < 2; ++b) _Pragma("unroll") for (int m = 0; m < 4; ++m) _Pragma("unroll") for (int n = 0; n < 2; ++n) acc[1][b][m][n] = (f32x4){0.f, 0.f, 0.f, 0.f}; } }
;             PG8_BAR; PG8_SCHED;
;             PG8_LDA(At, 0, 1); PG8_STAGE(PG8_SB(0, 0), b2, voffB); PG8_STAGE(PG8_SB(0, 1), b2 + hstep, voffB); PG8_STAGE(PG8_SA(0, 0), a2, voffA);
;             if (plast) PG8_WAIT_V(10); else PG8_WAIT_SEL(defer, 16, 24);
;             PG8_WAIT_L(0); PG8_BAR; PG8_MMA(1, 0, At, B0); PG8_MMA(1, 1, At, B1); PG8_BAR; PG8_SCHED;
	v_mfma_f32_16x16x32_bf16 v[120:123], v[128:131], v[170:173], v[120:123]
	v_mfma_f32_16x16x32_bf16 v[124:127], v[136:139], v[170:173], v[124:127]
	v_mfma_f32_16x16x32_bf16 v[108:111], v[128:131], v[178:181], v[108:111]
	v_mfma_f32_16x16x32_bf16 v[104:107], v[136:139], v[178:181], v[104:107]
	v_mfma_f32_16x16x32_bf16 v[92:95], v[128:131], v[204:207], v[92:95]
	v_mfma_f32_16x16x32_bf16 v[88:91], v[136:139], v[204:207], v[88:91]
	v_mfma_f32_16x16x32_bf16 v[76:79], v[128:131], v[212:215], v[76:79]
	v_mfma_f32_16x16x32_bf16 v[72:75], v[136:139], v[212:215], v[72:75]
	v_mfma_f32_16x16x32_bf16 v[120:123], v[132:135], v[174:177], v[120:123]
	v_mfma_f32_16x16x32_bf16 v[124:127], v[140:143], v[174:177], v[124:127]
	v_mfma_f32_16x16x32_bf16 v[108:111], v[132:135], v[188:191], v[108:111]
	v_mfma_f32_16x16x32_bf16 v[104:107], v[140:143], v[188:191], v[104:107]
	v_mfma_f32_16x16x32_bf16 v[92:95], v[132:135], v[208:211], v[92:95]
	v_mfma_f32_16x16x32_bf16 v[88:91], v[140:143], v[208:211], v[88:91]
	v_mfma_f32_16x16x32_bf16 v[76:79], v[132:135], v[216:219], v[76:79]
	v_mfma_f32_16x16x32_bf16 v[72:75], v[140:143], v[216:219], v[72:75]
	s_setprio 0
	s_setprio 1
	v_mfma_f32_16x16x32_bf16 v[116:119], v[144:147], v[170:173], v[116:119]
	v_mfma_f32_16x16x32_bf16 v[112:115], v[152:155], v[170:173], v[112:115]
	v_mfma_f32_16x16x32_bf16 v[100:103], v[144:147], v[178:181], v[100:103]
	v_mfma_f32_16x16x32_bf16 v[96:99], v[152:155], v[178:181], v[96:99]
	v_mfma_f32_16x16x32_bf16 v[84:87], v[144:147], v[204:207], v[84:87]
	v_mfma_f32_16x16x32_bf16 v[80:83], v[152:155], v[204:207], v[80:83]
	v_mfma_f32_16x16x32_bf16 v[68:71], v[144:147], v[212:215], v[68:71]
	v_mfma_f32_16x16x32_bf16 v[64:67], v[152:155], v[212:215], v[64:67]
	v_mfma_f32_16x16x32_bf16 v[116:119], v[148:151], v[174:177], v[116:119]
	v_mfma_f32_16x16x32_bf16 v[112:115], v[166:169], v[174:177], v[112:115]
	v_mfma_f32_16x16x32_bf16 v[100:103], v[148:151], v[188:191], v[100:103]
	v_mfma_f32_16x16x32_bf16 v[96:99], v[166:169], v[188:191], v[96:99]
	v_mfma_f32_16x16x32_bf16 v[84:87], v[148:151], v[208:211], v[84:87]
	v_mfma_f32_16x16x32_bf16 v[80:83], v[166:169], v[208:211], v[80:83]
	v_mfma_f32_16x16x32_bf16 v[68:71], v[148:151], v[216:219], v[68:71]
	v_mfma_f32_16x16x32_bf16 v[64:67], v[166:169], v[216:219], v[64:67]
	s_barrier
	s_setprio 0
	s_add_i32 s54, s54, s34
	v_lshl_add_u64 v[182:183], s[52:53], 0, v[192:193]
	s_mov_b32 m0, s54
	ds_read_b128 v[170:173], v187 offset:16384
	ds_read_b128 v[174:177], v187 offset:17408
	ds_read_b128 v[178:181], v187 offset:18432
	ds_read_b128 v[188:191], v187 offset:19456
	ds_read_b128 v[204:207], v187 offset:20480
	ds_read_b128 v[208:211], v187 offset:21504
	ds_read_b128 v[212:215], v187 offset:22528
	ds_read_b128 v[216:219], v187 offset:23552
	global_load_lds_dwordx4 v[182:183], off
	s_add_i32 m0, s54, 0x2000
	v_lshl_add_u64 v[194:195], s[52:53], 0, v[156:157]
	s_add_u32 s52, s52, s16
	s_addc_u32 s53, s53, s17
	s_add_i32 s54, s55, s34
	global_load_lds_dwordx4 v[194:195], off
	v_lshl_add_u64 v[200:201], s[52:53], 0, v[192:193]
	s_mov_b32 m0, s54
	v_lshl_add_u64 v[202:203], s[52:53], 0, v[156:157]
	global_load_lds_dwordx4 v[200:201], off
	s_add_i32 m0, s54, 0x2000
	v_lshl_add_u64 v[220:221], s[28:29], 0, v[160:161]
	global_load_lds_dwordx4 v[202:203], off
	s_mov_b32 m0, s35
	v_lshl_add_u64 v[222:223], s[28:29], 0, v[158:159]
	global_load_lds_dwordx4 v[220:221], off
	s_mov_b32 m0, s36
	s_nop 0
	global_load_lds_dwordx4 v[222:223], off
	s_waitcnt vmcnt(8)
	s_waitcnt lgkmcnt(0)
	s_setprio 1
	s_barrier
	v_mfma_f32_16x16x32_bf16 v[60:63], v[128:131], v[170:173], v[60:63]
	v_mfma_f32_16x16x32_bf16 v[56:59], v[136:139], v[170:173], v[56:59]
	v_mfma_f32_16x16x32_bf16 v[44:47], v[128:131], v[178:181], v[44:47]
	v_mfma_f32_16x16x32_bf16 v[40:43], v[136:139], v[178:181], v[40:43]
	v_mfma_f32_16x16x32_bf16 v[28:31], v[128:131], v[204:207], v[28:31]
	v_mfma_f32_16x16x32_bf16 v[24:27], v[136:139], v[204:207], v[24:27]
	v_mfma_f32_16x16x32_bf16 v[12:15], v[128:131], v[212:215], v[12:15]
	v_mfma_f32_16x16x32_bf16 v[8:11], v[136:139], v[212:215], v[8:11]
	v_mfma_f32_16x16x32_bf16 v[60:63], v[132:135], v[174:177], v[60:63]
	v_mfma_f32_16x16x32_bf16 v[56:59], v[140:143], v[174:177], v[56:59]
	v_mfma_f32_16x16x32_bf16 v[44:47], v[132:135], v[188:191], v[44:47]
	v_mfma_f32_16x16x32_bf16 v[40:43], v[140:143], v[188:191], v[40:43]
	v_mfma_f32_16x16x32_bf16 v[28:31], v[132:135], v[208:211], v[28:31]
	v_mfma_f32_16x16x32_bf16 v[24:27], v[140:143], v[208:211], v[24:27]
	v_mfma_f32_16x16x32_bf16 v[12:15], v[132:135], v[216:219], v[12:15]
	v_mfma_f32_16x16x32_bf16 v[8:11], v[140:143], v[216:219], v[8:11]
	s_setprio 0
	s_setprio 1
	v_mfma_f32_16x16x32_bf16 v[52:55], v[144:147], v[170:173], v[52:55]
	v_mfma_f32_16x16x32_bf16 v[48:51], v[152:155], v[170:173], v[48:51]
	v_mfma_f32_16x16x32_bf16 v[36:39], v[144:147], v[178:181], v[36:39]
	v_mfma_f32_16x16x32_bf16 v[32:35], v[152:155], v[178:181], v[32:35]
	v_mfma_f32_16x16x32_bf16 v[20:23], v[144:147], v[204:207], v[20:23]
	v_mfma_f32_16x16x32_bf16 v[16:19], v[152:155], v[204:207], v[16:19]
	v_mfma_f32_16x16x32_bf16 v[4:7], v[144:147], v[212:215], v[4:7]
	v_mfma_f32_16x16x32_bf16 v[0:3], v[152:155], v[212:215], v[0:3]
	v_mfma_f32_16x16x32_bf16 v[52:55], v[148:151], v[174:177], v[52:55]
	v_mfma_f32_16x16x32_bf16 v[48:51], v[166:169], v[174:177], v[48:51]
	v_mfma_f32_16x16x32_bf16 v[36:39], v[148:151], v[188:191], v[36:39]
	v_mfma_f32_16x16x32_bf16 v[32:35], v[166:169], v[188:191], v[32:35]
	v_mfma_f32_16x16x32_bf16 v[20:23], v[148:151], v[208:211], v[20:23]
	v_mfma_f32_16x16x32_bf16 v[16:19], v[166:169], v[208:211], v[16:19]
	v_mfma_f32_16x16x32_bf16 v[4:7], v[148:151], v[216:219], v[4:7]
	v_mfma_f32_16x16x32_bf16 v[0:3], v[166:169], v[216:219], v[0:3]
	s_barrier
; #define PG8_STAGE(bufoff, gbase, voff) do { _Pragma("unroll") for (int _i = 0; _i < 2; ++_i) \
;         __builtin_amdgcn_global_load_lds((const unsigned*)((const char*)(gbase) + (voff)[_i]), (PG8_LAS unsigned*)(lds + (bufoff) + ldsw + _i * 8192), 16, 0, 0); } while (0)
; #define PG8_LDA(dst, b, h) do { _Pragma("unroll") for (int m = 0; m < 4; ++m) _Pragma("unroll") for (int k = 0; k < 2; ++k) dst[m][k] = *(const PG8_LAS bf16x8*)(lds + PG8_SA(b, h) + aoff + m * 2048 + k * 1024); } while (0)
; #define PG8_LDB(dst, b, h) do { _Pragma("unroll") for (int n = 0; n < 2; ++n) _Pragma("unroll") for (int k = 0; k < 2; ++k) dst[n][k] = *(const PG8_LAS bf16x8*)(lds + PG8_SB(b, h) + boff + n * 2048 + k * 1024); } while (0)
; #define PG8_MMA(ai, bj, At, Bt) do { __builtin_amdgcn_s_setprio(1); _Pragma("unroll") for (int m = 0; m < 4; ++m) _Pragma("unroll") for (int n = 0; n < 2; ++n) _Pragma("unroll") for (int k = 0; k < 2; ++k) \
;         acc[ai][bj][m][n] = __builtin_amdgcn_mfma_f32_16x16x32_bf16(Bt[n][k], At[m][k], acc[ai][bj][m][n], 0, 0, 0); __builtin_amdgcn_s_setprio(0); } while (0)
; #define PG8_WAIT_SEL(d, w4, w8) do { if constexpr (Epi::SPLIT) { if (d) { if constexpr (Epi::NSH == 4) PG8_WAIT_V(w4); else PG8_WAIT_V(w8); } else PG8_WAIT_V(8); } else PG8_WAIT_V(8); } while (0)
; #define PG8_WAIT_L(n) asm volatile("s_waitcnt lgkmcnt(" #n ")" ::: "memory")
; #define PG8_BAR __builtin_amdgcn_s_barrier()
; #define PG8_SCHED __builtin_amdgcn_sched_barrier(0)
; template <class Epi, class Sched, bool ALIGN_EPI = false, bool SP2 = false>
; __device__ __forceinline__ void gemm_phase(PG8_LAS unsigned char* lds, const Gemm g, const Sched& S, const Epi& E) {
;     ...
;             PG8_LDB(B0, 1, 0); PG8_LDB(B1, 1, 1); PG8_SCHED; PG8_LDA(At, 1, 0); PG8_STAGE(PG8_SA(0, 1), a2 + hstepA, voffA);
;             PG8_WAIT_SEL(defer, 12, 16); PG8_WAIT_L(0); PG8_BAR; PG8_MMA(0, 0, At, B0); PG8_MMA(0, 1, At, B1); PG8_BAR; PG8_SCHED;
	s_setprio 0
	s_add_i32 s52, 0, 0x18000
	s_add_i32 s53, 0, 0x1c000
	v_add_u32_e32 v140, s52, v186
	v_add_u32_e32 v166, s53, v186
	ds_read_b128 v[128:131], v140
	ds_read_b128 v[132:135], v140 offset:1024
	ds_read_b128 v[136:139], v140 offset:2048
	ds_read_b128 v[140:143], v140 offset:3072
	ds_read_b128 v[144:147], v166
	ds_read_b128 v[148:151], v166 offset:1024
	ds_read_b128 v[152:155], v166 offset:2048
	ds_read_b128 v[166:169], v166 offset:3072
	s_add_u32 s28, s28, s12
	s_addc_u32 s29, s29, s13
	s_mov_b32 m0, s37
	v_lshl_add_u64 v[224:225], s[28:29], 0, v[160:161]
	ds_read_b128 v[170:173], v187 offset:32768
	ds_read_b128 v[174:177], v187 offset:33792
	ds_read_b128 v[178:181], v187 offset:34816
	ds_read_b128 v[188:191], v187 offset:35840
	ds_read_b128 v[204:207], v187 offset:36864
	ds_read_b128 v[208:211], v187 offset:37888
	ds_read_b128 v[212:215], v187 offset:38912
	ds_read_b128 v[216:219], v187 offset:39936
	global_load_lds_dwordx4 v[224:225], off
	v_lshl_add_u64 v[224:225], s[28:29], 0, v[158:159]
	s_mov_b32 m0, s38
	s_nop 0
	global_load_lds_dwordx4 v[224:225], off
	s_waitcnt vmcnt(8)
	s_waitcnt lgkmcnt(0)
	s_setprio 1
	s_barrier
	v_mfma_f32_16x16x32_bf16 v[120:123], v[128:131], v[170:173], v[120:123]
	v_mfma_f32_16x16x32_bf16 v[124:127], v[136:139], v[170:173], v[124:127]
	v_mfma_f32_16x16x32_bf16 v[108:111], v[128:131], v[178:181], v[108:111]
	v_mfma_f32_16x16x32_bf16 v[104:107], v[136:139], v[178:181], v[104:107]
	v_mfma_f32_16x16x32_bf16 v[92:95], v[128:131], v[204:207], v[92:95]
	v_mfma_f32_16x16x32_bf16 v[88:91], v[136:139], v[204:207], v[88:91]
	v_mfma_f32_16x16x32_bf16 v[76:79], v[128:131], v[212:215], v[76:79]
	v_mfma_f32_16x16x32_bf16 v[72:75], v[136:139], v[212:215], v[72:75]
	v_mfma_f32_16x16x32_bf16 v[120:123], v[132:135], v[174:177], v[120:123]
	v_mfma_f32_16x16x32_bf16 v[124:127], v[140:143], v[174:177], v[124:127]
	v_mfma_f32_16x16x32_bf16 v[108:111], v[132:135], v[188:191], v[108:111]
	v_mfma_f32_16x16x32_bf16 v[104:107], v[140:143], v[188:191], v[104:107]
	v_mfma_f32_16x16x32_bf16 v[92:95], v[132:135], v[208:211], v[92:95]
	v_mfma_f32_16x16x32_bf16 v[88:91], v[140:143], v[208:211], v[88:91]
	v_mfma_f32_16x16x32_bf16 v[76:79], v[132:135], v[216:219], v[76:79]
	v_mfma_f32_16x16x32_bf16 v[72:75], v[140:143], v[216:219], v[72:75]
	s_setprio 0
	s_setprio 1
	v_mfma_f32_16x16x32_bf16 v[116:119], v[144:147], v[170:173], v[116:119]
	v_mfma_f32_16x16x32_bf16 v[112:115], v[152:155], v[170:173], v[112:115]
	v_mfma_f32_16x16x32_bf16 v[100:103], v[144:147], v[178:181], v[100:103]
	v_mfma_f32_16x16x32_bf16 v[96:99], v[152:155], v[178:181], v[96:99]
	v_mfma_f32_16x16x32_bf16 v[84:87], v[144:147], v[204:207], v[84:87]
	v_mfma_f32_16x16x32_bf16 v[80:83], v[152:155], v[204:207], v[80:83]
	v_mfma_f32_16x16x32_bf16 v[68:71], v[144:147], v[212:215], v[68:71]
	v_mfma_f32_16x16x32_bf16 v[64:67], v[152:155], v[212:215], v[64:67]
	v_mfma_f32_16x16x32_bf16 v[116:119], v[148:151], v[174:177], v[116:119]
	v_mfma_f32_16x16x32_bf16 v[112:115], v[166:169], v[174:177], v[112:115]
	v_mfma_f32_16x16x32_bf16 v[100:103], v[148:151], v[188:191], v[100:103]
	v_mfma_f32_16x16x32_bf16 v[96:99], v[166:169], v[188:191], v[96:99]
	v_mfma_f32_16x16x32_bf16 v[84:87], v[148:151], v[208:211], v[84:87]
	v_mfma_f32_16x16x32_bf16 v[80:83], v[166:169], v[208:211], v[80:83]
	v_mfma_f32_16x16x32_bf16 v[68:71], v[148:151], v[216:219], v[68:71]
	v_mfma_f32_16x16x32_bf16 v[64:67], v[166:169], v[216:219], v[64:67]
	s_barrier
; #define PG8_STAGE(bufoff, gbase, voff) do { _Pragma("unroll") for (int _i = 0; _i < 2; ++_i) \
;         __builtin_amdgcn_global_load_lds((const unsigned*)((const char*)(gbase) + (voff)[_i]), (PG8_LAS unsigned*)(lds + (bufoff) + ldsw + _i * 8192), 16, 0, 0); } while (0)
; #define PG8_LDA(dst, b, h) do { _Pragma("unroll") for (int m = 0; m < 4; ++m) _Pragma("unroll") for (int k = 0; k < 2; ++k) dst[m][k] = *(const PG8_LAS bf16x8*)(lds + PG8_SA(b, h) + aoff + m * 2048 + k * 1024); } while (0)
; #define PG8_MMA(ai, bj, At, Bt) do { __builtin_amdgcn_s_setprio(1); _Pragma("unroll") for (int m = 0; m < 4; ++m) _Pragma("unroll") for (int n = 0; n < 2; ++n) _Pragma("unroll") for (int k = 0; k < 2; ++k) \
;         acc[ai][bj][m][n] = __builtin_amdgcn_mfma_f32_16x16x32_bf16(Bt[n][k], At[m][k], acc[ai][bj][m][n], 0, 0, 0); __builtin_amdgcn_s_setprio(0); } while (0)
; #define PG8_WAIT_V(n) asm volatile("s_waitcnt vmcnt(" #n ")" ::: "memory")
; #define PG8_WAIT_L(n) asm volatile("s_waitcnt lgkmcnt(" #n ")" ::: "memory")
; #define PG8_BAR __builtin_amdgcn_s_barrier()
; #define PG8_SCHED __builtin_amdgcn_sched_barrier(0)
; template <class Epi, class Sched, bool ALIGN_EPI = false, bool SP2 = false>
; __device__ __forceinline__ void gemm_phase(PG8_LAS unsigned char* lds, const Gemm g, const Sched& S, const Epi& E) {
;     ...
;             PG8_LDA(At, 1, 1); PG8_STAGE(PG8_SB(1, 0), b3, voffB); PG8_STAGE(PG8_SB(1, 1), b3 + hstep, voffB); PG8_STAGE(PG8_SA(1, 0), a3, voffA);
;             PG8_WAIT_V(8); PG8_WAIT_L(0); PG8_BAR; PG8_MMA(1, 0, At, B0); PG8_MMA(1, 1, At, B1); PG8_BAR; PG8_SCHED;
	s_setprio 0
	s_add_i32 s28, s52, s34
	v_lshl_add_u64 v[182:183], v[182:183], 0, s[90:91]
	s_mov_b32 m0, s28
	ds_read_b128 v[170:173], v187 offset:49152
	ds_read_b128 v[174:177], v187 offset:50176
	ds_read_b128 v[178:181], v187 offset:51200
	ds_read_b128 v[188:191], v187 offset:52224
	ds_read_b128 v[204:207], v187 offset:53248
	ds_read_b128 v[208:211], v187 offset:54272
	ds_read_b128 v[212:215], v187 offset:55296
	ds_read_b128 v[216:219], v187 offset:56320
	global_load_lds_dwordx4 v[182:183], off
	v_lshl_add_u64 v[182:183], v[194:195], 0, s[90:91]
	s_add_i32 m0, s28, 0x2000
	s_add_i32 s28, s53, s34
	global_load_lds_dwordx4 v[182:183], off
	v_lshl_add_u64 v[182:183], v[200:201], 0, s[90:91]
	s_mov_b32 m0, s28
	s_nop 0
	global_load_lds_dwordx4 v[182:183], off
	v_lshl_add_u64 v[182:183], v[202:203], 0, s[90:91]
	s_add_i32 m0, s28, 0x2000
	s_nop 0
	global_load_lds_dwordx4 v[182:183], off
	v_lshl_add_u64 v[182:183], v[220:221], 0, s[90:91]
	s_mov_b32 m0, s43
	s_nop 0
	global_load_lds_dwordx4 v[182:183], off
	v_lshl_add_u64 v[182:183], v[222:223], 0, s[90:91]
	s_mov_b32 m0, s44
	s_nop 0
	global_load_lds_dwordx4 v[182:183], off
	s_waitcnt vmcnt(8)
	s_waitcnt lgkmcnt(0)
	s_setprio 1
	s_barrier
	v_mfma_f32_16x16x32_bf16 v[60:63], v[128:131], v[170:173], v[60:63]
	v_mfma_f32_16x16x32_bf16 v[56:59], v[136:139], v[170:173], v[56:59]
	v_mfma_f32_16x16x32_bf16 v[44:47], v[128:131], v[178:181], v[44:47]
	v_mfma_f32_16x16x32_bf16 v[40:43], v[136:139], v[178:181], v[40:43]
	v_mfma_f32_16x16x32_bf16 v[28:31], v[128:131], v[204:207], v[28:31]
	v_mfma_f32_16x16x32_bf16 v[24:27], v[136:139], v[204:207], v[24:27]
	v_mfma_f32_16x16x32_bf16 v[12:15], v[128:131], v[212:215], v[12:15]
	v_mfma_f32_16x16x32_bf16 v[8:11], v[136:139], v[212:215], v[8:11]
	v_mfma_f32_16x16x32_bf16 v[60:63], v[132:135], v[174:177], v[60:63]
	v_mfma_f32_16x16x32_bf16 v[56:59], v[140:143], v[174:177], v[56:59]
	v_mfma_f32_16x16x32_bf16 v[44:47], v[132:135], v[188:191], v[44:47]
	v_mfma_f32_16x16x32_bf16 v[40:43], v[140:143], v[188:191], v[40:43]
	v_mfma_f32_16x16x32_bf16 v[28:31], v[132:135], v[208:211], v[28:31]
	v_mfma_f32_16x16x32_bf16 v[24:27], v[140:143], v[208:211], v[24:27]
	v_mfma_f32_16x16x32_bf16 v[12:15], v[132:135], v[216:219], v[12:15]
	v_mfma_f32_16x16x32_bf16 v[8:11], v[140:143], v[216:219], v[8:11]
	s_setprio 0
	s_setprio 1
	v_mfma_f32_16x16x32_bf16 v[52:55], v[144:147], v[170:173], v[52:55]
	v_mfma_f32_16x16x32_bf16 v[48:51], v[152:155], v[170:173], v[48:51]
	v_mfma_f32_16x16x32_bf16 v[36:39], v[144:147], v[178:181], v[36:39]
	v_mfma_f32_16x16x32_bf16 v[32:35], v[152:155], v[178:181], v[32:35]
	v_mfma_f32_16x16x32_bf16 v[20:23], v[144:147], v[204:207], v[20:23]
	v_mfma_f32_16x16x32_bf16 v[16:19], v[152:155], v[204:207], v[16:19]
	v_mfma_f32_16x16x32_bf16 v[4:7], v[144:147], v[212:215], v[4:7]
	v_mfma_f32_16x16x32_bf16 v[0:3], v[152:155], v[212:215], v[0:3]
	v_mfma_f32_16x16x32_bf16 v[52:55], v[148:151], v[174:177], v[52:55]
	v_mfma_f32_16x16x32_bf16 v[48:51], v[166:169], v[174:177], v[48:51]
	v_mfma_f32_16x16x32_bf16 v[36:39], v[148:151], v[188:191], v[36:39]
	v_mfma_f32_16x16x32_bf16 v[32:35], v[166:169], v[188:191], v[32:35]
	v_mfma_f32_16x16x32_bf16 v[20:23], v[148:151], v[208:211], v[20:23]
	v_mfma_f32_16x16x32_bf16 v[16:19], v[166:169], v[208:211], v[16:19]
	v_mfma_f32_16x16x32_bf16 v[4:7], v[148:151], v[216:219], v[4:7]
	v_mfma_f32_16x16x32_bf16 v[0:3], v[166:169], v[216:219], v[0:3]
	s_barrier
	s_setprio 0
	s_add_u32 s0, s0, 0x100
	s_addc_u32 s1, s1, 0
	s_add_u32 s33, s33, 0x100
	s_addc_u32 s50, s50, 0
	s_cmp_ge_i32 s51, s40
	s_mov_b32 s28, s51
	s_cbranch_scc0 .LBB0_353

; #define PG8_STAGE(bufoff, gbase, voff) do { _Pragma("unroll") for (int _i = 0; _i < 2; ++_i) \
;         __builtin_amdgcn_global_load_lds((const unsigned*)((const char*)(gbase) + (voff)[_i]), (PG8_LAS unsigned*)(lds + (bufoff) + ldsw + _i * 8192), 16, 0, 0); } while (0)
; #define PG8_LDA(dst, b, h) do { _Pragma("unroll") for (int m = 0; m < 4; ++m) _Pragma("unroll") for (int k = 0; k < 2; ++k) dst[m][k] = *(const PG8_LAS bf16x8*)(lds + PG8_SA(b, h) + aoff + m * 2048 + k * 1024); } while (0)
; #define PG8_LDB(dst, b, h) do { _Pragma("unroll") for (int n = 0; n < 2; ++n) _Pragma("unroll") for (int k = 0; k < 2; ++k) dst[n][k] = *(const PG8_LAS bf16x8*)(lds + PG8_SB(b, h) + boff + n * 2048 + k * 1024); } while (0)
; #define PG8_WAIT_V(n) asm volatile("s_waitcnt vmcnt(" #n ")" ::: "memory")
; #define PG8_WAIT_L(n) asm volatile("s_waitcnt lgkmcnt(" #n ")" ::: "memory")
; #define PG8_BAR __builtin_amdgcn_s_barrier()
; #define PG8_SCHED __builtin_amdgcn_sched_barrier(0)
; template <class Epi, class Sched, bool ALIGN_EPI = false, bool SP2 = false>
; __device__ __forceinline__ void gemm_phase(PG8_LAS unsigned char* lds, const Gemm g, const Sched& S, const Epi& E) {
;     ...
;             const char* a1 = cA + (size_t)(t + 1) * kstep;
;             const char* a2 = last ? nA : cA + (size_t)(t + 2) * kstep; const char* b2 = last ? nB : cB + (size_t)(t + 2) * kstep;
;             const char* a3 = a2 + kstep; const char* b3 = b2 + kstep;
;             if (last && has_next) S.a_ready(nxt);
;             if constexpr (SP2) {
;             PG8_LDB(B0, 0, 0); PG8_LDB(B1, 0, 1); PG8_SCHED; PG8_LDA(At, 0, 0); PG8_STAGE(PG8_SA(1, 1), a1 + hstepA, voffA);
;             if (plast) PG8_WAIT_V(10); else PG8_WAIT_SEL(defer, 12, 16);
;             PG8_WAIT_L(0); PG8_BAR; PG8_MMA(0, 0, At, B0); PG8_MMA(0, 1, At, B1);
;             if constexpr (Epi::SPLIT) { if (defer) {
;                 E.second(acc, prev, rv1, wr, wc, fr, fq);
;                 _Pragma("unroll") for (int b = 0; b < 2; ++b) _Pragma("unroll") for (int m = 0; m < 4; ++m) _Pragma("unroll") for (int n = 0; n < 2; ++n) acc[1][b][m][n] = (f32x4){0.f, 0.f, 0.f, 0.f}; } }
;             PG8_BAR; PG8_SCHED;
;             PG8_LDA(At, 0, 1); PG8_STAGE(PG8_SB(0, 0), b2, voffB); PG8_STAGE(PG8_SB(0, 1), b2 + hstep, voffB); PG8_STAGE(PG8_SA(0, 0), a2, voffA);
;             if (plast) PG8_WAIT_V(10); else PG8_WAIT_SEL(defer, 16, 24);
.Lpk_gu_419:
	s_add_u32 s34, s26, 0x80
	s_addc_u32 s35, s27, 0
	s_waitcnt lgkmcnt(0)
	s_and_b64 s[28:29], s[28:29], exec
	s_cselect_b32 s29, s9, s35
	s_cselect_b32 s28, s8, s34
	s_cselect_b32 s35, s11, s33
	s_cselect_b32 s34, s10, s1
	s_setprio 1
	s_barrier
	v_mfma_f32_16x16x32_bf16 v[120:123], v[144:147], v[184:187], 0
	v_mfma_f32_16x16x32_bf16 v[112:115], v[152:155], v[184:187], 0
	v_mfma_f32_16x16x32_bf16 v[104:107], v[144:147], v[176:179], 0
	v_mfma_f32_16x16x32_bf16 v[96:99], v[152:155], v[176:179], 0
	v_mfma_f32_16x16x32_bf16 v[88:91], v[144:147], v[168:171], 0
	v_mfma_f32_16x16x32_bf16 v[80:83], v[152:155], v[168:171], 0
	v_mfma_f32_16x16x32_bf16 v[72:75], v[144:147], v[160:163], 0
	v_mfma_f32_16x16x32_bf16 v[64:67], v[152:155], v[160:163], 0
	v_mfma_f32_16x16x32_bf16 v[120:123], v[148:151], v[188:191], v[120:123]
	v_mfma_f32_16x16x32_bf16 v[112:115], v[156:159], v[188:191], v[112:115]
	v_mfma_f32_16x16x32_bf16 v[104:107], v[148:151], v[180:183], v[104:107]
	v_mfma_f32_16x16x32_bf16 v[96:99], v[156:159], v[180:183], v[96:99]
	v_mfma_f32_16x16x32_bf16 v[88:91], v[148:151], v[172:175], v[88:91]
	v_mfma_f32_16x16x32_bf16 v[80:83], v[156:159], v[172:175], v[80:83]
	v_mfma_f32_16x16x32_bf16 v[72:75], v[148:151], v[164:167], v[72:75]
	v_mfma_f32_16x16x32_bf16 v[64:67], v[156:159], v[164:167], v[64:67]
	s_setprio 0
	s_setprio 1
	v_mfma_f32_16x16x32_bf16 v[124:127], v[128:131], v[184:187], 0
	v_mfma_f32_16x16x32_bf16 v[116:119], v[136:139], v[184:187], 0
	v_mfma_f32_16x16x32_bf16 v[108:111], v[128:131], v[176:179], 0
	v_mfma_f32_16x16x32_bf16 v[100:103], v[136:139], v[176:179], 0
	v_mfma_f32_16x16x32_bf16 v[92:95], v[128:131], v[168:171], 0
	v_mfma_f32_16x16x32_bf16 v[84:87], v[136:139], v[168:171], 0
	v_mfma_f32_16x16x32_bf16 v[76:79], v[128:131], v[160:163], 0
	v_mfma_f32_16x16x32_bf16 v[68:71], v[136:139], v[160:163], 0
	v_mfma_f32_16x16x32_bf16 v[124:127], v[132:135], v[188:191], v[124:127]
	v_mfma_f32_16x16x32_bf16 v[116:119], v[140:143], v[188:191], v[116:119]
	v_mfma_f32_16x16x32_bf16 v[108:111], v[132:135], v[180:183], v[108:111]
	v_mfma_f32_16x16x32_bf16 v[100:103], v[140:143], v[180:183], v[100:103]
	v_mfma_f32_16x16x32_bf16 v[92:95], v[132:135], v[172:175], v[92:95]
	v_mfma_f32_16x16x32_bf16 v[84:87], v[140:143], v[172:175], v[84:87]
	v_mfma_f32_16x16x32_bf16 v[76:79], v[132:135], v[164:167], v[76:79]
	v_mfma_f32_16x16x32_bf16 v[68:71], v[140:143], v[164:167], v[68:71]
	s_barrier
	s_setprio 0
	s_mov_b32 m0, s40
	v_lshl_add_u64 v[222:223], s[34:35], 0, v[192:193]
	v_lshl_add_u64 v[220:221], s[34:35], 0, v[204:205]
	s_add_u32 s34, s34, s16
	ds_read_b128 v[184:187], v240 offset:16384
	ds_read_b128 v[188:191], v240 offset:17408
	ds_read_b128 v[176:179], v240 offset:18432
	ds_read_b128 v[180:183], v240 offset:19456
	ds_read_b128 v[168:171], v240 offset:20480
	ds_read_b128 v[172:175], v240 offset:21504
	ds_read_b128 v[160:163], v240 offset:22528
	ds_read_b128 v[164:167], v240 offset:23552
	global_load_lds_dwordx4 v[222:223], off
	s_mov_b32 m0, s41
	s_addc_u32 s35, s35, s17
	global_load_lds_dwordx4 v[220:221], off
	v_lshl_add_u64 v[230:231], s[34:35], 0, v[192:193]
	s_mov_b32 m0, s42
	v_lshl_add_u64 v[228:229], s[34:35], 0, v[204:205]
	global_load_lds_dwordx4 v[230:231], off
	s_mov_b32 m0, s43
	v_lshl_add_u64 v[224:225], s[28:29], 0, v[208:209]
	global_load_lds_dwordx4 v[228:229], off
	s_mov_b32 m0, s39
	v_lshl_add_u64 v[226:227], s[28:29], 0, v[206:207]
	global_load_lds_dwordx4 v[224:225], off
	s_mov_b32 m0, s44
	s_mov_b64 s[34:35], -1
	global_load_lds_dwordx4 v[226:227], off
	s_and_b64 vcc, exec, s[30:31]
	s_cbranch_vccz .Lpk_gu_421
	s_waitcnt vmcnt(8)
	s_mov_b64 s[34:35], 0

; #define PG8_STAGE(bufoff, gbase, voff) do { _Pragma("unroll") for (int _i = 0; _i < 2; ++_i) \
;         __builtin_amdgcn_global_load_lds((const unsigned*)((const char*)(gbase) + (voff)[_i]), (PG8_LAS unsigned*)(lds + (bufoff) + ldsw + _i * 8192), 16, 0, 0); } while (0)
; #define PG8_LDA(dst, b, h) do { _Pragma("unroll") for (int m = 0; m < 4; ++m) _Pragma("unroll") for (int k = 0; k < 2; ++k) dst[m][k] = *(const PG8_LAS bf16x8*)(lds + PG8_SA(b, h) + aoff + m * 2048 + k * 1024); } while (0)
; #define PG8_LDB(dst, b, h) do { _Pragma("unroll") for (int n = 0; n < 2; ++n) _Pragma("unroll") for (int k = 0; k < 2; ++k) dst[n][k] = *(const PG8_LAS bf16x8*)(lds + PG8_SB(b, h) + boff + n * 2048 + k * 1024); } while (0)
; #define PG8_MMA(ai, bj, At, Bt) do { __builtin_amdgcn_s_setprio(1); _Pragma("unroll") for (int m = 0; m < 4; ++m) _Pragma("unroll") for (int n = 0; n < 2; ++n) _Pragma("unroll") for (int k = 0; k < 2; ++k) \
;         acc[ai][bj][m][n] = __builtin_amdgcn_mfma_f32_16x16x32_bf16(Bt[n][k], At[m][k], acc[ai][bj][m][n], 0, 0, 0); __builtin_amdgcn_s_setprio(0); } while (0)
; #define PG8_WAIT_SEL(d, w4, w8) do { if constexpr (Epi::SPLIT) { if (d) { if constexpr (Epi::NSH == 4) PG8_WAIT_V(w4); else PG8_WAIT_V(w8); } else PG8_WAIT_V(8); } else PG8_WAIT_V(8); } while (0)
; #define PG8_WAIT_L(n) asm volatile("s_waitcnt lgkmcnt(" #n ")" ::: "memory")
; #define PG8_BAR __builtin_amdgcn_s_barrier()
; #define PG8_SCHED __builtin_amdgcn_sched_barrier(0)
; template <class Epi, class Sched, bool ALIGN_EPI = false, bool SP2 = false>
; __device__ __forceinline__ void gemm_phase(PG8_LAS unsigned char* lds, const Gemm g, const Sched& S, const Epi& E) {
;     ...
;             PG8_WAIT_L(0); PG8_BAR; PG8_MMA(1, 0, At, B0); PG8_MMA(1, 1, At, B1); PG8_BAR; PG8_SCHED;
;             PG8_LDB(B0, 1, 0); PG8_LDB(B1, 1, 1); PG8_SCHED; PG8_LDA(At, 1, 0); PG8_STAGE(PG8_SA(0, 1), a2 + hstepA, voffA);
;             PG8_WAIT_SEL(defer, 12, 16); PG8_WAIT_L(0); PG8_BAR; PG8_MMA(0, 0, At, B0); PG8_MMA(0, 1, At, B1); PG8_BAR; PG8_SCHED;
.Lpk_gu_412:
	s_waitcnt lgkmcnt(0)
	s_add_i32 s55, s55, 2
	s_setprio 1
	s_barrier
	v_mfma_f32_16x16x32_bf16 v[56:59], v[144:147], v[184:187], 0
	v_mfma_f32_16x16x32_bf16 v[48:51], v[152:155], v[184:187], 0
	v_mfma_f32_16x16x32_bf16 v[40:43], v[144:147], v[176:179], 0
	v_mfma_f32_16x16x32_bf16 v[32:35], v[152:155], v[176:179], 0
	v_mfma_f32_16x16x32_bf16 v[24:27], v[144:147], v[168:171], 0
	v_mfma_f32_16x16x32_bf16 v[16:19], v[152:155], v[168:171], 0
	v_mfma_f32_16x16x32_bf16 v[8:11], v[144:147], v[160:163], 0
	v_mfma_f32_16x16x32_bf16 v[4:7], v[152:155], v[160:163], 0
	v_mfma_f32_16x16x32_bf16 v[56:59], v[148:151], v[188:191], v[56:59]
	v_mfma_f32_16x16x32_bf16 v[48:51], v[156:159], v[188:191], v[48:51]
	v_mfma_f32_16x16x32_bf16 v[40:43], v[148:151], v[180:183], v[40:43]
	v_mfma_f32_16x16x32_bf16 v[32:35], v[156:159], v[180:183], v[32:35]
	v_mfma_f32_16x16x32_bf16 v[24:27], v[148:151], v[172:175], v[24:27]
	v_mfma_f32_16x16x32_bf16 v[16:19], v[156:159], v[172:175], v[16:19]
	v_mfma_f32_16x16x32_bf16 v[8:11], v[148:151], v[164:167], v[8:11]
	v_mfma_f32_16x16x32_bf16 v[4:7], v[156:159], v[164:167], v[4:7]
	s_setprio 0
	s_setprio 1
	v_mfma_f32_16x16x32_bf16 v[60:63], v[128:131], v[184:187], 0
	v_mfma_f32_16x16x32_bf16 v[52:55], v[136:139], v[184:187], 0
	v_mfma_f32_16x16x32_bf16 v[44:47], v[128:131], v[176:179], 0
	v_mfma_f32_16x16x32_bf16 v[36:39], v[136:139], v[176:179], 0
	v_mfma_f32_16x16x32_bf16 v[28:31], v[128:131], v[168:171], 0
	v_mfma_f32_16x16x32_bf16 v[20:23], v[136:139], v[168:171], 0
	v_mfma_f32_16x16x32_bf16 v[12:15], v[128:131], v[160:163], 0
	v_mfma_f32_16x16x32_bf16 v[0:3], v[136:139], v[160:163], 0
	v_mfma_f32_16x16x32_bf16 v[60:63], v[132:135], v[188:191], v[60:63]
	v_mfma_f32_16x16x32_bf16 v[52:55], v[140:143], v[188:191], v[52:55]
	v_mfma_f32_16x16x32_bf16 v[44:47], v[132:135], v[180:183], v[44:47]
	v_mfma_f32_16x16x32_bf16 v[36:39], v[140:143], v[180:183], v[36:39]
	v_mfma_f32_16x16x32_bf16 v[28:31], v[132:135], v[172:175], v[28:31]
	v_mfma_f32_16x16x32_bf16 v[20:23], v[140:143], v[172:175], v[20:23]
	v_mfma_f32_16x16x32_bf16 v[12:15], v[132:135], v[164:167], v[12:15]
	v_mfma_f32_16x16x32_bf16 v[0:3], v[140:143], v[164:167], v[0:3]
	s_barrier
	s_setprio 0
	s_add_i32 s30, 0, 0x18000
	s_add_i32 s31, 0, 0x1c000
	v_add_u32_e32 v140, s30, v239
	v_add_u32_e32 v156, s31, v239
	ds_read_b128 v[128:131], v140
	ds_read_b128 v[132:135], v140 offset:1024
	ds_read_b128 v[136:139], v140 offset:2048
	ds_read_b128 v[140:143], v140 offset:3072
	ds_read_b128 v[144:147], v156
	ds_read_b128 v[148:151], v156 offset:1024
	ds_read_b128 v[152:155], v156 offset:2048
	ds_read_b128 v[156:159], v156 offset:3072
	s_add_u32 s28, s28, s12
	s_addc_u32 s29, s29, s13
	s_mov_b32 m0, s45
	v_lshl_add_u64 v[194:195], s[28:29], 0, v[208:209]
	ds_read_b128 v[160:163], v240 offset:32768
	ds_read_b128 v[164:167], v240 offset:33792
	ds_read_b128 v[168:171], v240 offset:34816
	ds_read_b128 v[172:175], v240 offset:35840
	ds_read_b128 v[176:179], v240 offset:36864
	ds_read_b128 v[180:183], v240 offset:37888
	ds_read_b128 v[184:187], v240 offset:38912
	ds_read_b128 v[188:191], v240 offset:39936
	global_load_lds_dwordx4 v[194:195], off
	v_lshl_add_u64 v[194:195], s[28:29], 0, v[206:207]
	s_mov_b32 m0, s46
	s_nop 0
	global_load_lds_dwordx4 v[194:195], off
	s_waitcnt vmcnt(8)
	s_waitcnt lgkmcnt(0)
	s_setprio 1
	s_barrier
	v_mfma_f32_16x16x32_bf16 v[120:123], v[128:131], v[160:163], v[120:123]
	v_mfma_f32_16x16x32_bf16 v[112:115], v[136:139], v[160:163], v[112:115]
	v_mfma_f32_16x16x32_bf16 v[104:107], v[128:131], v[168:171], v[104:107]
	v_mfma_f32_16x16x32_bf16 v[96:99], v[136:139], v[168:171], v[96:99]
	v_mfma_f32_16x16x32_bf16 v[88:91], v[128:131], v[176:179], v[88:91]
	v_mfma_f32_16x16x32_bf16 v[80:83], v[136:139], v[176:179], v[80:83]
	v_mfma_f32_16x16x32_bf16 v[72:75], v[128:131], v[184:187], v[72:75]
	v_mfma_f32_16x16x32_bf16 v[64:67], v[136:139], v[184:187], v[64:67]
	v_mfma_f32_16x16x32_bf16 v[120:123], v[132:135], v[164:167], v[120:123]
	v_mfma_f32_16x16x32_bf16 v[112:115], v[140:143], v[164:167], v[112:115]
	v_mfma_f32_16x16x32_bf16 v[104:107], v[132:135], v[172:175], v[104:107]
	v_mfma_f32_16x16x32_bf16 v[96:99], v[140:143], v[172:175], v[96:99]
	v_mfma_f32_16x16x32_bf16 v[88:91], v[132:135], v[180:183], v[88:91]
	v_mfma_f32_16x16x32_bf16 v[80:83], v[140:143], v[180:183], v[80:83]
	v_mfma_f32_16x16x32_bf16 v[72:75], v[132:135], v[188:191], v[72:75]
	v_mfma_f32_16x16x32_bf16 v[64:67], v[140:143], v[188:191], v[64:67]
	s_setprio 0
	s_setprio 1
	v_mfma_f32_16x16x32_bf16 v[124:127], v[144:147], v[160:163], v[124:127]
	v_mfma_f32_16x16x32_bf16 v[116:119], v[152:155], v[160:163], v[116:119]
	v_mfma_f32_16x16x32_bf16 v[108:111], v[144:147], v[168:171], v[108:111]
	v_mfma_f32_16x16x32_bf16 v[100:103], v[152:155], v[168:171], v[100:103]
	v_mfma_f32_16x16x32_bf16 v[92:95], v[144:147], v[176:179], v[92:95]
	v_mfma_f32_16x16x32_bf16 v[84:87], v[152:155], v[176:179], v[84:87]
	v_mfma_f32_16x16x32_bf16 v[76:79], v[144:147], v[184:187], v[76:79]
	v_mfma_f32_16x16x32_bf16 v[68:71], v[152:155], v[184:187], v[68:71]
	v_mfma_f32_16x16x32_bf16 v[124:127], v[148:151], v[164:167], v[124:127]
	v_mfma_f32_16x16x32_bf16 v[116:119], v[156:159], v[164:167], v[116:119]
	v_mfma_f32_16x16x32_bf16 v[108:111], v[148:151], v[172:175], v[108:111]
	v_mfma_f32_16x16x32_bf16 v[100:103], v[156:159], v[172:175], v[100:103]
	v_mfma_f32_16x16x32_bf16 v[92:95], v[148:151], v[180:183], v[92:95]
	v_mfma_f32_16x16x32_bf16 v[84:87], v[156:159], v[180:183], v[84:87]
	v_mfma_f32_16x16x32_bf16 v[76:79], v[148:151], v[188:191], v[76:79]
	v_mfma_f32_16x16x32_bf16 v[68:71], v[156:159], v[188:191], v[68:71]
	s_barrier
; #define PG8_STAGE(bufoff, gbase, voff) do { _Pragma("unroll") for (int _i = 0; _i < 2; ++_i) \
;         __builtin_amdgcn_global_load_lds((const unsigned*)((const char*)(gbase) + (voff)[_i]), (PG8_LAS unsigned*)(lds + (bufoff) + ldsw + _i * 8192), 16, 0, 0); } while (0)
; #define PG8_LDA(dst, b, h) do { _Pragma("unroll") for (int m = 0; m < 4; ++m) _Pragma("unroll") for (int k = 0; k < 2; ++k) dst[m][k] = *(const PG8_LAS bf16x8*)(lds + PG8_SA(b, h) + aoff + m * 2048 + k * 1024); } while (0)
; #define PG8_MMA(ai, bj, At, Bt) do { __builtin_amdgcn_s_setprio(1); _Pragma("unroll") for (int m = 0; m < 4; ++m) _Pragma("unroll") for (int n = 0; n < 2; ++n) _Pragma("unroll") for (int k = 0; k < 2; ++k) \
;         acc[ai][bj][m][n] = __builtin_amdgcn_mfma_f32_16x16x32_bf16(Bt[n][k], At[m][k], acc[ai][bj][m][n], 0, 0, 0); __builtin_amdgcn_s_setprio(0); } while (0)
; #define PG8_WAIT_V(n) asm volatile("s_waitcnt vmcnt(" #n ")" ::: "memory")
; #define PG8_WAIT_L(n) asm volatile("s_waitcnt lgkmcnt(" #n ")" ::: "memory")
; #define PG8_BAR __builtin_amdgcn_s_barrier()
; #define PG8_SCHED __builtin_amdgcn_sched_barrier(0)
; template <class Epi, class Sched, bool ALIGN_EPI = false, bool SP2 = false>
; __device__ __forceinline__ void gemm_phase(PG8_LAS unsigned char* lds, const Gemm g, const Sched& S, const Epi& E) {
;     ...
;             PG8_WAIT_L(0); PG8_BAR; PG8_MMA(1, 0, At, B0); PG8_MMA(1, 1, At, B1); PG8_BAR; PG8_SCHED;
;     ...
;             PG8_LDA(At, 1, 1); PG8_STAGE(PG8_SB(1, 0), b3, voffB); PG8_STAGE(PG8_SB(1, 1), b3 + hstep, voffB); PG8_STAGE(PG8_SA(1, 0), a3, voffA);
;             PG8_WAIT_V(8); PG8_WAIT_L(0); PG8_BAR; PG8_MMA(1, 0, At, B0); PG8_MMA(1, 1, At, B1); PG8_BAR; PG8_SCHED;
	s_setprio 0
	s_add_i32 s28, s30, s38
	v_lshl_add_u64 v[194:195], v[222:223], 0, s[90:91]
	s_mov_b32 m0, s28
	ds_read_b128 v[160:163], v240 offset:49152
	ds_read_b128 v[164:167], v240 offset:50176
	ds_read_b128 v[168:171], v240 offset:51200
	ds_read_b128 v[172:175], v240 offset:52224
	ds_read_b128 v[176:179], v240 offset:53248
	ds_read_b128 v[180:183], v240 offset:54272
	ds_read_b128 v[184:187], v240 offset:55296
	ds_read_b128 v[188:191], v240 offset:56320
	global_load_lds_dwordx4 v[194:195], off
	v_lshl_add_u64 v[194:195], v[220:221], 0, s[90:91]
	s_add_i32 m0, s28, 0x2000
	s_add_i32 s28, s31, s38
	global_load_lds_dwordx4 v[194:195], off
	v_lshl_add_u64 v[194:195], v[230:231], 0, s[90:91]
	s_mov_b32 m0, s28
	s_nop 0
	global_load_lds_dwordx4 v[194:195], off
	v_lshl_add_u64 v[194:195], v[228:229], 0, s[90:91]
	s_add_i32 m0, s28, 0x2000
	s_nop 0
	global_load_lds_dwordx4 v[194:195], off
	v_lshl_add_u64 v[194:195], v[224:225], 0, s[90:91]
	s_mov_b32 m0, s49
	s_nop 0
	global_load_lds_dwordx4 v[194:195], off
	v_lshl_add_u64 v[194:195], v[226:227], 0, s[90:91]
	s_mov_b32 m0, s50
	s_nop 0
	global_load_lds_dwordx4 v[194:195], off
	s_waitcnt vmcnt(8)
	s_waitcnt lgkmcnt(0)
	s_setprio 1
	s_barrier
	v_mfma_f32_16x16x32_bf16 v[56:59], v[128:131], v[160:163], v[56:59]
	v_mfma_f32_16x16x32_bf16 v[48:51], v[136:139], v[160:163], v[48:51]
	v_mfma_f32_16x16x32_bf16 v[40:43], v[128:131], v[168:171], v[40:43]
	v_mfma_f32_16x16x32_bf16 v[32:35], v[136:139], v[168:171], v[32:35]
	v_mfma_f32_16x16x32_bf16 v[24:27], v[128:131], v[176:179], v[24:27]
	v_mfma_f32_16x16x32_bf16 v[16:19], v[136:139], v[176:179], v[16:19]
	v_mfma_f32_16x16x32_bf16 v[8:11], v[128:131], v[184:187], v[8:11]
	v_mfma_f32_16x16x32_bf16 v[4:7], v[136:139], v[184:187], v[4:7]
	v_mfma_f32_16x16x32_bf16 v[56:59], v[132:135], v[164:167], v[56:59]
	v_mfma_f32_16x16x32_bf16 v[48:51], v[140:143], v[164:167], v[48:51]
	v_mfma_f32_16x16x32_bf16 v[40:43], v[132:135], v[172:175], v[40:43]
	v_mfma_f32_16x16x32_bf16 v[32:35], v[140:143], v[172:175], v[32:35]
	v_mfma_f32_16x16x32_bf16 v[24:27], v[132:135], v[180:183], v[24:27]
	v_mfma_f32_16x16x32_bf16 v[16:19], v[140:143], v[180:183], v[16:19]
	v_mfma_f32_16x16x32_bf16 v[8:11], v[132:135], v[188:191], v[8:11]
	v_mfma_f32_16x16x32_bf16 v[4:7], v[140:143], v[188:191], v[4:7]
	s_setprio 0
	s_setprio 1
	v_mfma_f32_16x16x32_bf16 v[60:63], v[144:147], v[160:163], v[60:63]
	v_mfma_f32_16x16x32_bf16 v[52:55], v[152:155], v[160:163], v[52:55]
	v_mfma_f32_16x16x32_bf16 v[44:47], v[144:147], v[168:171], v[44:47]
	v_mfma_f32_16x16x32_bf16 v[36:39], v[152:155], v[168:171], v[36:39]
	v_mfma_f32_16x16x32_bf16 v[28:31], v[144:147], v[176:179], v[28:31]
	v_mfma_f32_16x16x32_bf16 v[20:23], v[152:155], v[176:179], v[20:23]
	v_mfma_f32_16x16x32_bf16 v[12:15], v[144:147], v[184:187], v[12:15]
	v_mfma_f32_16x16x32_bf16 v[0:3], v[152:155], v[184:187], v[0:3]
	v_mfma_f32_16x16x32_bf16 v[60:63], v[148:151], v[164:167], v[60:63]
	v_mfma_f32_16x16x32_bf16 v[52:55], v[156:159], v[164:167], v[52:55]
	v_mfma_f32_16x16x32_bf16 v[44:47], v[148:151], v[172:175], v[44:47]
	v_mfma_f32_16x16x32_bf16 v[36:39], v[156:159], v[172:175], v[36:39]
	v_mfma_f32_16x16x32_bf16 v[28:31], v[148:151], v[180:183], v[28:31]
	v_mfma_f32_16x16x32_bf16 v[20:23], v[156:159], v[180:183], v[20:23]
	v_mfma_f32_16x16x32_bf16 v[12:15], v[148:151], v[188:191], v[12:15]
	v_mfma_f32_16x16x32_bf16 v[0:3], v[156:159], v[188:191], v[0:3]
	s_barrier
	s_setprio 0
	s_add_u32 s26, s26, 0x100
	s_addc_u32 s27, s27, 0
	s_add_u32 s1, s1, 0x100
	s_addc_u32 s33, s33, 0
	s_cmp_ge_i32 s55, s47
	s_cbranch_scc1 .LBB0_423
	s_branch .LBB0_413
.LBB0_412:
	s_waitcnt lgkmcnt(0)
	s_add_i32 s55, s55, 2
	s_setprio 1
	s_barrier
	v_mfma_f32_16x16x32_bf16 v[56:59], v[144:147], v[184:187], v[56:59]
	v_mfma_f32_16x16x32_bf16 v[48:51], v[152:155], v[184:187], v[48:51]
	v_mfma_f32_16x16x32_bf16 v[40:43], v[144:147], v[176:179], v[40:43]
	v_mfma_f32_16x16x32_bf16 v[32:35], v[152:155], v[176:179], v[32:35]
	v_mfma_f32_16x16x32_bf16 v[24:27], v[144:147], v[168:171], v[24:27]
	v_mfma_f32_16x16x32_bf16 v[16:19], v[152:155], v[168:171], v[16:19]
	v_mfma_f32_16x16x32_bf16 v[8:11], v[144:147], v[160:163], v[8:11]
	v_mfma_f32_16x16x32_bf16 v[4:7], v[152:155], v[160:163], v[4:7]
	v_mfma_f32_16x16x32_bf16 v[56:59], v[148:151], v[188:191], v[56:59]
	v_mfma_f32_16x16x32_bf16 v[48:51], v[156:159], v[188:191], v[48:51]
	v_mfma_f32_16x16x32_bf16 v[40:43], v[148:151], v[180:183], v[40:43]
	v_mfma_f32_16x16x32_bf16 v[32:35], v[156:159], v[180:183], v[32:35]
	v_mfma_f32_16x16x32_bf16 v[24:27], v[148:151], v[172:175], v[24:27]
	v_mfma_f32_16x16x32_bf16 v[16:19], v[156:159], v[172:175], v[16:19]
	v_mfma_f32_16x16x32_bf16 v[8:11], v[148:151], v[164:167], v[8:11]
	v_mfma_f32_16x16x32_bf16 v[4:7], v[156:159], v[164:167], v[4:7]
	s_setprio 0
	s_setprio 1
	v_mfma_f32_16x16x32_bf16 v[60:63], v[128:131], v[184:187], v[60:63]
	v_mfma_f32_16x16x32_bf16 v[52:55], v[136:139], v[184:187], v[52:55]
	v_mfma_f32_16x16x32_bf16 v[44:47], v[128:131], v[176:179], v[44:47]
	v_mfma_f32_16x16x32_bf16 v[36:39], v[136:139], v[176:179], v[36:39]
	v_mfma_f32_16x16x32_bf16 v[28:31], v[128:131], v[168:171], v[28:31]
	v_mfma_f32_16x16x32_bf16 v[20:23], v[136:139], v[168:171], v[20:23]
	v_mfma_f32_16x16x32_bf16 v[12:15], v[128:131], v[160:163], v[12:15]
	v_mfma_f32_16x16x32_bf16 v[0:3], v[136:139], v[160:163], v[0:3]
	v_mfma_f32_16x16x32_bf16 v[60:63], v[132:135], v[188:191], v[60:63]
	v_mfma_f32_16x16x32_bf16 v[52:55], v[140:143], v[188:191], v[52:55]
	v_mfma_f32_16x16x32_bf16 v[44:47], v[132:135], v[180:183], v[44:47]
	v_mfma_f32_16x16x32_bf16 v[36:39], v[140:143], v[180:183], v[36:39]
	v_mfma_f32_16x16x32_bf16 v[28:31], v[132:135], v[172:175], v[28:31]
	v_mfma_f32_16x16x32_bf16 v[20:23], v[140:143], v[172:175], v[20:23]
	v_mfma_f32_16x16x32_bf16 v[12:15], v[132:135], v[164:167], v[12:15]
	v_mfma_f32_16x16x32_bf16 v[0:3], v[140:143], v[164:167], v[0:3]
	s_barrier
; #define PG8_STAGE(bufoff, gbase, voff) do { _Pragma("unroll") for (int _i = 0; _i < 2; ++_i) \
;         __builtin_amdgcn_global_load_lds((const unsigned*)((const char*)(gbase) + (voff)[_i]), (PG8_LAS unsigned*)(lds + (bufoff) + ldsw + _i * 8192), 16, 0, 0); } while (0)
; #define PG8_LDA(dst, b, h) do { _Pragma("unroll") for (int m = 0; m < 4; ++m) _Pragma("unroll") for (int k = 0; k < 2; ++k) dst[m][k] = *(const PG8_LAS bf16x8*)(lds + PG8_SA(b, h) + aoff + m * 2048 + k * 1024); } while (0)
; #define PG8_LDB(dst, b, h) do { _Pragma("unroll") for (int n = 0; n < 2; ++n) _Pragma("unroll") for (int k = 0; k < 2; ++k) dst[n][k] = *(const PG8_LAS bf16x8*)(lds + PG8_SB(b, h) + boff + n * 2048 + k * 1024); } while (0)
; #define PG8_MMA(ai, bj, At, Bt) do { __builtin_amdgcn_s_setprio(1); _Pragma("unroll") for (int m = 0; m < 4; ++m) _Pragma("unroll") for (int n = 0; n < 2; ++n) _Pragma("unroll") for (int k = 0; k < 2; ++k) \
;         acc[ai][bj][m][n] = __builtin_amdgcn_mfma_f32_16x16x32_bf16(Bt[n][k], At[m][k], acc[ai][bj][m][n], 0, 0, 0); __builtin_amdgcn_s_setprio(0); } while (0)
; #define PG8_WAIT_V(n) asm volatile("s_waitcnt vmcnt(" #n ")" ::: "memory")
; #define PG8_WAIT_SEL(d, w4, w8) do { if constexpr (Epi::SPLIT) { if (d) { if constexpr (Epi::NSH == 4) PG8_WAIT_V(w4); else PG8_WAIT_V(w8); } else PG8_WAIT_V(8); } else PG8_WAIT_V(8); } while (0)
; #define PG8_WAIT_L(n) asm volatile("s_waitcnt lgkmcnt(" #n ")" ::: "memory")
; #define PG8_BAR __builtin_amdgcn_s_barrier()
; #define PG8_SCHED __builtin_amdgcn_sched_barrier(0)
; template <class Epi, class Sched, bool ALIGN_EPI = false, bool SP2 = false>
; __device__ __forceinline__ void gemm_phase(PG8_LAS unsigned char* lds, const Gemm g, const Sched& S, const Epi& E) {
;     ...
;             PG8_LDB(B0, 1, 0); PG8_LDB(B1, 1, 1); PG8_SCHED; PG8_LDA(At, 1, 0); PG8_STAGE(PG8_SA(0, 1), a2 + hstepA, voffA);
;             PG8_WAIT_SEL(defer, 12, 16); PG8_WAIT_L(0); PG8_BAR; PG8_MMA(0, 0, At, B0); PG8_MMA(0, 1, At, B1); PG8_BAR; PG8_SCHED;
;             PG8_LDA(At, 1, 1); PG8_STAGE(PG8_SB(1, 0), b3, voffB); PG8_STAGE(PG8_SB(1, 1), b3 + hstep, voffB); PG8_STAGE(PG8_SA(1, 0), a3, voffA);
;             PG8_WAIT_V(8); PG8_WAIT_L(0); PG8_BAR; PG8_MMA(1, 0, At, B0); PG8_MMA(1, 1, At, B1); PG8_BAR; PG8_SCHED;
	s_setprio 0
	s_add_i32 s30, 0, 0x18000
	s_add_i32 s31, 0, 0x1c000
	v_add_u32_e32 v140, s30, v239
	v_add_u32_e32 v156, s31, v239
	ds_read_b128 v[128:131], v140
	ds_read_b128 v[132:135], v140 offset:1024
	ds_read_b128 v[136:139], v140 offset:2048
	ds_read_b128 v[140:143], v140 offset:3072
	ds_read_b128 v[144:147], v156
	ds_read_b128 v[148:151], v156 offset:1024
	ds_read_b128 v[152:155], v156 offset:2048
	ds_read_b128 v[156:159], v156 offset:3072
	s_add_u32 s28, s28, s12
	s_addc_u32 s29, s29, s13
	s_mov_b32 m0, s45
	v_lshl_add_u64 v[194:195], s[28:29], 0, v[208:209]
	ds_read_b128 v[160:163], v240 offset:32768
	ds_read_b128 v[164:167], v240 offset:33792
	ds_read_b128 v[168:171], v240 offset:34816
	ds_read_b128 v[172:175], v240 offset:35840
	ds_read_b128 v[176:179], v240 offset:36864
	ds_read_b128 v[180:183], v240 offset:37888
	ds_read_b128 v[184:187], v240 offset:38912
	ds_read_b128 v[188:191], v240 offset:39936
	global_load_lds_dwordx4 v[194:195], off
	v_lshl_add_u64 v[194:195], s[28:29], 0, v[206:207]
	s_mov_b32 m0, s46
	s_nop 0
	global_load_lds_dwordx4 v[194:195], off
	s_waitcnt vmcnt(8)
	s_waitcnt lgkmcnt(0)
	s_setprio 1
	s_barrier
	v_mfma_f32_16x16x32_bf16 v[120:123], v[128:131], v[160:163], v[120:123]
	v_mfma_f32_16x16x32_bf16 v[112:115], v[136:139], v[160:163], v[112:115]
	v_mfma_f32_16x16x32_bf16 v[104:107], v[128:131], v[168:171], v[104:107]
	v_mfma_f32_16x16x32_bf16 v[96:99], v[136:139], v[168:171], v[96:99]
	v_mfma_f32_16x16x32_bf16 v[88:91], v[128:131], v[176:179], v[88:91]
	v_mfma_f32_16x16x32_bf16 v[80:83], v[136:139], v[176:179], v[80:83]
	v_mfma_f32_16x16x32_bf16 v[72:75], v[128:131], v[184:187], v[72:75]
	v_mfma_f32_16x16x32_bf16 v[64:67], v[136:139], v[184:187], v[64:67]
	v_mfma_f32_16x16x32_bf16 v[120:123], v[132:135], v[164:167], v[120:123]
	v_mfma_f32_16x16x32_bf16 v[112:115], v[140:143], v[164:167], v[112:115]
	v_mfma_f32_16x16x32_bf16 v[104:107], v[132:135], v[172:175], v[104:107]
	v_mfma_f32_16x16x32_bf16 v[96:99], v[140:143], v[172:175], v[96:99]
	v_mfma_f32_16x16x32_bf16 v[88:91], v[132:135], v[180:183], v[88:91]
	v_mfma_f32_16x16x32_bf16 v[80:83], v[140:143], v[180:183], v[80:83]
	v_mfma_f32_16x16x32_bf16 v[72:75], v[132:135], v[188:191], v[72:75]
	v_mfma_f32_16x16x32_bf16 v[64:67], v[140:143], v[188:191], v[64:67]
	s_setprio 0
	s_setprio 1
	v_mfma_f32_16x16x32_bf16 v[124:127], v[144:147], v[160:163], v[124:127]
	v_mfma_f32_16x16x32_bf16 v[116:119], v[152:155], v[160:163], v[116:119]
	v_mfma_f32_16x16x32_bf16 v[108:111], v[144:147], v[168:171], v[108:111]
	v_mfma_f32_16x16x32_bf16 v[100:103], v[152:155], v[168:171], v[100:103]
	v_mfma_f32_16x16x32_bf16 v[92:95], v[144:147], v[176:179], v[92:95]
	v_mfma_f32_16x16x32_bf16 v[84:87], v[152:155], v[176:179], v[84:87]
	v_mfma_f32_16x16x32_bf16 v[76:79], v[144:147], v[184:187], v[76:79]
	v_mfma_f32_16x16x32_bf16 v[68:71], v[152:155], v[184:187], v[68:71]
	v_mfma_f32_16x16x32_bf16 v[124:127], v[148:151], v[164:167], v[124:127]
	v_mfma_f32_16x16x32_bf16 v[116:119], v[156:159], v[164:167], v[116:119]
	v_mfma_f32_16x16x32_bf16 v[108:111], v[148:151], v[172:175], v[108:111]
	v_mfma_f32_16x16x32_bf16 v[100:103], v[156:159], v[172:175], v[100:103]
	v_mfma_f32_16x16x32_bf16 v[92:95], v[148:151], v[180:183], v[92:95]
	v_mfma_f32_16x16x32_bf16 v[84:87], v[156:159], v[180:183], v[84:87]
	v_mfma_f32_16x16x32_bf16 v[76:79], v[148:151], v[188:191], v[76:79]
	v_mfma_f32_16x16x32_bf16 v[68:71], v[156:159], v[188:191], v[68:71]
	s_barrier
	s_setprio 0
	s_add_i32 s28, s30, s38
	v_lshl_add_u64 v[194:195], v[222:223], 0, s[90:91]
	s_mov_b32 m0, s28
	ds_read_b128 v[160:163], v240 offset:49152
	ds_read_b128 v[164:167], v240 offset:50176
	ds_read_b128 v[168:171], v240 offset:51200
	ds_read_b128 v[172:175], v240 offset:52224
	ds_read_b128 v[176:179], v240 offset:53248
	ds_read_b128 v[180:183], v240 offset:54272
	ds_read_b128 v[184:187], v240 offset:55296
	ds_read_b128 v[188:191], v240 offset:56320
	global_load_lds_dwordx4 v[194:195], off
	v_lshl_add_u64 v[194:195], v[220:221], 0, s[90:91]
	s_add_i32 m0, s28, 0x2000
	s_add_i32 s28, s31, s38
	global_load_lds_dwordx4 v[194:195], off
	v_lshl_add_u64 v[194:195], v[230:231], 0, s[90:91]
	s_mov_b32 m0, s28
	s_nop 0
	global_load_lds_dwordx4 v[194:195], off
	v_lshl_add_u64 v[194:195], v[228:229], 0, s[90:91]
	s_add_i32 m0, s28, 0x2000
	s_nop 0
	global_load_lds_dwordx4 v[194:195], off
	v_lshl_add_u64 v[194:195], v[224:225], 0, s[90:91]
	s_mov_b32 m0, s49
	s_nop 0
	global_load_lds_dwordx4 v[194:195], off
	v_lshl_add_u64 v[194:195], v[226:227], 0, s[90:91]
	s_mov_b32 m0, s50
	s_nop 0
	global_load_lds_dwordx4 v[194:195], off
	s_waitcnt vmcnt(8)
	s_waitcnt lgkmcnt(0)
	s_setprio 1
	s_barrier
	v_mfma_f32_16x16x32_bf16 v[56:59], v[128:131], v[160:163], v[56:59]
	v_mfma_f32_16x16x32_bf16 v[48:51], v[136:139], v[160:163], v[48:51]
	v_mfma_f32_16x16x32_bf16 v[40:43], v[128:131], v[168:171], v[40:43]
	v_mfma_f32_16x16x32_bf16 v[32:35], v[136:139], v[168:171], v[32:35]
	v_mfma_f32_16x16x32_bf16 v[24:27], v[128:131], v[176:179], v[24:27]
	v_mfma_f32_16x16x32_bf16 v[16:19], v[136:139], v[176:179], v[16:19]
	v_mfma_f32_16x16x32_bf16 v[8:11], v[128:131], v[184:187], v[8:11]
	v_mfma_f32_16x16x32_bf16 v[4:7], v[136:139], v[184:187], v[4:7]
	v_mfma_f32_16x16x32_bf16 v[56:59], v[132:135], v[164:167], v[56:59]
	v_mfma_f32_16x16x32_bf16 v[48:51], v[140:143], v[164:167], v[48:51]
	v_mfma_f32_16x16x32_bf16 v[40:43], v[132:135], v[172:175], v[40:43]
	v_mfma_f32_16x16x32_bf16 v[32:35], v[140:143], v[172:175], v[32:35]
	v_mfma_f32_16x16x32_bf16 v[24:27], v[132:135], v[180:183], v[24:27]
	v_mfma_f32_16x16x32_bf16 v[16:19], v[140:143], v[180:183], v[16:19]
	v_mfma_f32_16x16x32_bf16 v[8:11], v[132:135], v[188:191], v[8:11]
	v_mfma_f32_16x16x32_bf16 v[4:7], v[140:143], v[188:191], v[4:7]
	s_setprio 0
	s_setprio 1
	v_mfma_f32_16x16x32_bf16 v[60:63], v[144:147], v[160:163], v[60:63]
	v_mfma_f32_16x16x32_bf16 v[52:55], v[152:155], v[160:163], v[52:55]
	v_mfma_f32_16x16x32_bf16 v[44:47], v[144:147], v[168:171], v[44:47]
	v_mfma_f32_16x16x32_bf16 v[36:39], v[152:155], v[168:171], v[36:39]
	v_mfma_f32_16x16x32_bf16 v[28:31], v[144:147], v[176:179], v[28:31]
	v_mfma_f32_16x16x32_bf16 v[20:23], v[152:155], v[176:179], v[20:23]
	v_mfma_f32_16x16x32_bf16 v[12:15], v[144:147], v[184:187], v[12:15]
	v_mfma_f32_16x16x32_bf16 v[0:3], v[152:155], v[184:187], v[0:3]
	v_mfma_f32_16x16x32_bf16 v[60:63], v[148:151], v[164:167], v[60:63]
	v_mfma_f32_16x16x32_bf16 v[52:55], v[156:159], v[164:167], v[52:55]
	v_mfma_f32_16x16x32_bf16 v[44:47], v[148:151], v[172:175], v[44:47]
	v_mfma_f32_16x16x32_bf16 v[36:39], v[156:159], v[172:175], v[36:39]
	v_mfma_f32_16x16x32_bf16 v[28:31], v[148:151], v[180:183], v[28:31]
	v_mfma_f32_16x16x32_bf16 v[20:23], v[156:159], v[180:183], v[20:23]
	v_mfma_f32_16x16x32_bf16 v[12:15], v[148:151], v[188:191], v[12:15]
	v_mfma_f32_16x16x32_bf16 v[0:3], v[156:159], v[188:191], v[0:3]
	s_barrier
	s_setprio 0
	s_add_u32 s26, s26, 0x100
	s_addc_u32 s27, s27, 0
	s_add_u32 s1, s1, 0x100
	s_addc_u32 s33, s33, 0
	s_cmp_ge_i32 s55, s47
	s_cbranch_scc1 .LBB0_423

; #define PG8_STAGE(bufoff, gbase, voff) do { _Pragma("unroll") for (int _i = 0; _i < 2; ++_i) \
;         __builtin_amdgcn_global_load_lds((const unsigned*)((const char*)(gbase) + (voff)[_i]), (PG8_LAS unsigned*)(lds + (bufoff) + ldsw + _i * 8192), 16, 0, 0); } while (0)
; #define PG8_LDA(dst, b, h) do { _Pragma("unroll") for (int m = 0; m < 4; ++m) _Pragma("unroll") for (int k = 0; k < 2; ++k) dst[m][k] = *(const PG8_LAS bf16x8*)(lds + PG8_SA(b, h) + aoff + m * 2048 + k * 1024); } while (0)
; #define PG8_LDB(dst, b, h) do { _Pragma("unroll") for (int n = 0; n < 2; ++n) _Pragma("unroll") for (int k = 0; k < 2; ++k) dst[n][k] = *(const PG8_LAS bf16x8*)(lds + PG8_SB(b, h) + boff + n * 2048 + k * 1024); } while (0)
; #define PG8_WAIT_V(n) asm volatile("s_waitcnt vmcnt(" #n ")" ::: "memory")
; #define PG8_WAIT_L(n) asm volatile("s_waitcnt lgkmcnt(" #n ")" ::: "memory")
; #define PG8_BAR __builtin_amdgcn_s_barrier()
; #define PG8_SCHED __builtin_amdgcn_sched_barrier(0)
; template <class Epi, class Sched, bool ALIGN_EPI = false, bool SP2 = false>
; __device__ __forceinline__ void gemm_phase(PG8_LAS unsigned char* lds, const Gemm g, const Sched& S, const Epi& E) {
;     ...
;             const char* a1 = cA + (size_t)(t + 1) * kstep;
;             const char* a2 = last ? nA : cA + (size_t)(t + 2) * kstep; const char* b2 = last ? nB : cB + (size_t)(t + 2) * kstep;
;             const char* a3 = a2 + kstep; const char* b3 = b2 + kstep;
;             if (last && has_next) S.a_ready(nxt);
;             if constexpr (SP2) {
;             PG8_LDB(B0, 0, 0); PG8_LDB(B1, 0, 1); PG8_SCHED; PG8_LDA(At, 0, 0); PG8_STAGE(PG8_SA(1, 1), a1 + hstepA, voffA);
;             if (plast) PG8_WAIT_V(10); else PG8_WAIT_SEL(defer, 12, 16);
;             PG8_WAIT_L(0); PG8_BAR; PG8_MMA(0, 0, At, B0); PG8_MMA(0, 1, At, B1);
;             if constexpr (Epi::SPLIT) { if (defer) {
;                 E.second(acc, prev, rv1, wr, wc, fr, fq);
;                 _Pragma("unroll") for (int b = 0; b < 2; ++b) _Pragma("unroll") for (int m = 0; m < 4; ++m) _Pragma("unroll") for (int n = 0; n < 2; ++n) acc[1][b][m][n] = (f32x4){0.f, 0.f, 0.f, 0.f}; } }
;             PG8_BAR; PG8_SCHED;
;             PG8_LDA(At, 0, 1); PG8_STAGE(PG8_SB(0, 0), b2, voffB); PG8_STAGE(PG8_SB(0, 1), b2 + hstep, voffB); PG8_STAGE(PG8_SA(0, 0), a2, voffA);
;             if (plast) PG8_WAIT_V(10); else PG8_WAIT_SEL(defer, 16, 24);
.LBB0_419:
	s_add_u32 s34, s26, 0x80
	s_addc_u32 s35, s27, 0
	s_waitcnt lgkmcnt(0)
	s_and_b64 s[28:29], s[28:29], exec
	s_cselect_b32 s29, s9, s35
	s_cselect_b32 s28, s8, s34
	s_cselect_b32 s35, s11, s33
	s_cselect_b32 s34, s10, s1
	s_setprio 1
	s_barrier
	v_mfma_f32_16x16x32_bf16 v[120:123], v[144:147], v[184:187], v[120:123]
	v_mfma_f32_16x16x32_bf16 v[112:115], v[152:155], v[184:187], v[112:115]
	v_mfma_f32_16x16x32_bf16 v[104:107], v[144:147], v[176:179], v[104:107]
	v_mfma_f32_16x16x32_bf16 v[96:99], v[152:155], v[176:179], v[96:99]
	v_mfma_f32_16x16x32_bf16 v[88:91], v[144:147], v[168:171], v[88:91]
	v_mfma_f32_16x16x32_bf16 v[80:83], v[152:155], v[168:171], v[80:83]
	v_mfma_f32_16x16x32_bf16 v[72:75], v[144:147], v[160:163], v[72:75]
	v_mfma_f32_16x16x32_bf16 v[64:67], v[152:155], v[160:163], v[64:67]
	v_mfma_f32_16x16x32_bf16 v[120:123], v[148:151], v[188:191], v[120:123]
	v_mfma_f32_16x16x32_bf16 v[112:115], v[156:159], v[188:191], v[112:115]
	v_mfma_f32_16x16x32_bf16 v[104:107], v[148:151], v[180:183], v[104:107]
	v_mfma_f32_16x16x32_bf16 v[96:99], v[156:159], v[180:183], v[96:99]
	v_mfma_f32_16x16x32_bf16 v[88:91], v[148:151], v[172:175], v[88:91]
	v_mfma_f32_16x16x32_bf16 v[80:83], v[156:159], v[172:175], v[80:83]
	v_mfma_f32_16x16x32_bf16 v[72:75], v[148:151], v[164:167], v[72:75]
	v_mfma_f32_16x16x32_bf16 v[64:67], v[156:159], v[164:167], v[64:67]
	s_setprio 0
	s_setprio 1
	v_mfma_f32_16x16x32_bf16 v[124:127], v[128:131], v[184:187], v[124:127]
	v_mfma_f32_16x16x32_bf16 v[116:119], v[136:139], v[184:187], v[116:119]
	v_mfma_f32_16x16x32_bf16 v[108:111], v[128:131], v[176:179], v[108:111]
	v_mfma_f32_16x16x32_bf16 v[100:103], v[136:139], v[176:179], v[100:103]
	v_mfma_f32_16x16x32_bf16 v[92:95], v[128:131], v[168:171], v[92:95]
	v_mfma_f32_16x16x32_bf16 v[84:87], v[136:139], v[168:171], v[84:87]
	v_mfma_f32_16x16x32_bf16 v[76:79], v[128:131], v[160:163], v[76:79]
	v_mfma_f32_16x16x32_bf16 v[68:71], v[136:139], v[160:163], v[68:71]
	v_mfma_f32_16x16x32_bf16 v[124:127], v[132:135], v[188:191], v[124:127]
	v_mfma_f32_16x16x32_bf16 v[116:119], v[140:143], v[188:191], v[116:119]
	v_mfma_f32_16x16x32_bf16 v[108:111], v[132:135], v[180:183], v[108:111]
	v_mfma_f32_16x16x32_bf16 v[100:103], v[140:143], v[180:183], v[100:103]
	v_mfma_f32_16x16x32_bf16 v[92:95], v[132:135], v[172:175], v[92:95]
	v_mfma_f32_16x16x32_bf16 v[84:87], v[140:143], v[172:175], v[84:87]
	v_mfma_f32_16x16x32_bf16 v[76:79], v[132:135], v[164:167], v[76:79]
	v_mfma_f32_16x16x32_bf16 v[68:71], v[140:143], v[164:167], v[68:71]
	s_barrier
	s_setprio 0
	s_mov_b32 m0, s40
	v_lshl_add_u64 v[222:223], s[34:35], 0, v[192:193]
	v_lshl_add_u64 v[220:221], s[34:35], 0, v[204:205]
	s_add_u32 s34, s34, s16
	ds_read_b128 v[184:187], v240 offset:16384
	ds_read_b128 v[188:191], v240 offset:17408
	ds_read_b128 v[176:179], v240 offset:18432
	ds_read_b128 v[180:183], v240 offset:19456
	ds_read_b128 v[168:171], v240 offset:20480
	ds_read_b128 v[172:175], v240 offset:21504
	ds_read_b128 v[160:163], v240 offset:22528
	ds_read_b128 v[164:167], v240 offset:23552
	global_load_lds_dwordx4 v[222:223], off
	s_mov_b32 m0, s41
	s_addc_u32 s35, s35, s17
	global_load_lds_dwordx4 v[220:221], off
	v_lshl_add_u64 v[230:231], s[34:35], 0, v[192:193]
	s_mov_b32 m0, s42
	v_lshl_add_u64 v[228:229], s[34:35], 0, v[204:205]
	global_load_lds_dwordx4 v[230:231], off
	s_mov_b32 m0, s43
	v_lshl_add_u64 v[224:225], s[28:29], 0, v[208:209]
	global_load_lds_dwordx4 v[228:229], off
	s_mov_b32 m0, s39
	v_lshl_add_u64 v[226:227], s[28:29], 0, v[206:207]
	global_load_lds_dwordx4 v[224:225], off
	s_mov_b32 m0, s44
	s_mov_b64 s[34:35], -1
	global_load_lds_dwordx4 v[226:227], off
	s_and_b64 vcc, exec, s[30:31]
	s_cbranch_vccz .LBB0_421
	s_waitcnt vmcnt(8)
	s_mov_b64 s[34:35], 0

; #define PG8_STAGE(bufoff, gbase, voff) do { _Pragma("unroll") for (int _i = 0; _i < 2; ++_i) \
;         __builtin_amdgcn_global_load_lds((const unsigned*)((const char*)(gbase) + (voff)[_i]), (PG8_LAS unsigned*)(lds + (bufoff) + ldsw + _i * 8192), 16, 0, 0); } while (0)
; #define PG8_LDA(dst, b, h) do { _Pragma("unroll") for (int m = 0; m < 4; ++m) _Pragma("unroll") for (int k = 0; k < 2; ++k) dst[m][k] = *(const PG8_LAS bf16x8*)(lds + PG8_SA(b, h) + aoff + m * 2048 + k * 1024); } while (0)
; #define PG8_LDB(dst, b, h) do { _Pragma("unroll") for (int n = 0; n < 2; ++n) _Pragma("unroll") for (int k = 0; k < 2; ++k) dst[n][k] = *(const PG8_LAS bf16x8*)(lds + PG8_SB(b, h) + boff + n * 2048 + k * 1024); } while (0)
; #define PG8_WAIT_V(n) asm volatile("s_waitcnt vmcnt(" #n ")" ::: "memory")
; #define PG8_WAIT_L(n) asm volatile("s_waitcnt lgkmcnt(" #n ")" ::: "memory")
; #define PG8_BAR __builtin_amdgcn_s_barrier()
; #define PG8_SCHED __builtin_amdgcn_sched_barrier(0)
; template <class Epi, class Sched, bool ALIGN_EPI = false, bool SP2 = false>
; __device__ __forceinline__ void gemm_phase(PG8_LAS unsigned char* lds, const Gemm g, const Sched& S, const Epi& E) {
;     ...
;             const char* a1 = cA + (size_t)(t + 1) * kstep;
;             const char* a2 = last ? nA : cA + (size_t)(t + 2) * kstep; const char* b2 = last ? nB : cB + (size_t)(t + 2) * kstep;
;             const char* a3 = a2 + kstep; const char* b3 = b2 + kstep;
;             if (last && has_next) S.a_ready(nxt);
;             if constexpr (SP2) {
;             PG8_LDB(B0, 0, 0); PG8_LDB(B1, 0, 1); PG8_SCHED; PG8_LDA(At, 0, 0); PG8_STAGE(PG8_SA(1, 1), a1 + hstepA, voffA);
;             if (plast) PG8_WAIT_V(10); else PG8_WAIT_SEL(defer, 12, 16);
;             PG8_WAIT_L(0); PG8_BAR; PG8_MMA(0, 0, At, B0); PG8_MMA(0, 1, At, B1);
;             if constexpr (Epi::SPLIT) { if (defer) {
;                 E.second(acc, prev, rv1, wr, wc, fr, fq);
;                 _Pragma("unroll") for (int b = 0; b < 2; ++b) _Pragma("unroll") for (int m = 0; m < 4; ++m) _Pragma("unroll") for (int n = 0; n < 2; ++n) acc[1][b][m][n] = (f32x4){0.f, 0.f, 0.f, 0.f}; } }
;             PG8_BAR; PG8_SCHED;
;             PG8_LDA(At, 0, 1); PG8_STAGE(PG8_SB(0, 0), b2, voffB); PG8_STAGE(PG8_SB(0, 1), b2 + hstep, voffB); PG8_STAGE(PG8_SA(0, 0), a2, voffA);
;             if (plast) PG8_WAIT_V(10); else PG8_WAIT_SEL(defer, 16, 24);
.Lpk_pp_464:
	s_add_i32 s49, s26, 2
	s_add_u32 s50, s24, 0x80
	s_addc_u32 s27, s25, 0
	s_add_i32 s52, 0, 0x10000
	s_cmp_eq_u32 s42, s26
	s_cselect_b32 s27, s9, s27
	s_cselect_b32 s26, s8, s50
	s_cselect_b32 s51, s23, s48
	s_cselect_b32 s50, s22, s33
	s_add_i32 s53, 0, 0x14000
	v_add_u32_e32 v154, s52, v140
	v_add_u32_e32 v170, s53, v140
	ds_read_b128 v[142:145], v154
	ds_read_b128 v[146:149], v154 offset:1024
	ds_read_b128 v[150:153], v154 offset:2048
	ds_read_b128 v[154:157], v154 offset:3072
	ds_read_b128 v[158:161], v170
	ds_read_b128 v[162:165], v170 offset:1024
	ds_read_b128 v[166:169], v170 offset:2048
	ds_read_b128 v[170:173], v170 offset:3072
	v_lshl_add_u64 v[190:191], s[24:25], 0, v[134:135]
	s_add_i32 m0, s34, 0xc000
	ds_read_b128 v[174:177], v141
	ds_read_b128 v[178:181], v141 offset:1024
	ds_read_b128 v[182:185], v141 offset:2048
	ds_read_b128 v[186:189], v141 offset:3072
	ds_read_b128 v[204:207], v141 offset:4096
	ds_read_b128 v[208:211], v141 offset:5120
	ds_read_b128 v[212:215], v141 offset:6144
	ds_read_b128 v[216:219], v141 offset:7168
	global_load_lds_dwordx4 v[190:191], off
	v_lshl_add_u64 v[190:191], s[24:25], 0, v[136:137]
	s_add_i32 m0, s34, 0xe000
	s_nop 0
	global_load_lds_dwordx4 v[190:191], off
	s_waitcnt vmcnt(8)
	s_waitcnt lgkmcnt(0)
	s_setprio 1
	s_barrier
	v_mfma_f32_16x16x32_bf16 v[120:123], v[142:145], v[174:177], 0
	v_mfma_f32_16x16x32_bf16 v[124:127], v[150:153], v[174:177], 0
	v_mfma_f32_16x16x32_bf16 v[108:111], v[142:145], v[182:185], 0
	v_mfma_f32_16x16x32_bf16 v[104:107], v[150:153], v[182:185], 0
	v_mfma_f32_16x16x32_bf16 v[92:95], v[142:145], v[204:207], 0
	v_mfma_f32_16x16x32_bf16 v[88:91], v[150:153], v[204:207], 0
	v_mfma_f32_16x16x32_bf16 v[76:79], v[142:145], v[212:215], 0
	v_mfma_f32_16x16x32_bf16 v[72:75], v[150:153], v[212:215], 0
	v_mfma_f32_16x16x32_bf16 v[120:123], v[146:149], v[178:181], v[120:123]
	v_mfma_f32_16x16x32_bf16 v[124:127], v[154:157], v[178:181], v[124:127]
	v_mfma_f32_16x16x32_bf16 v[108:111], v[146:149], v[186:189], v[108:111]
	v_mfma_f32_16x16x32_bf16 v[104:107], v[154:157], v[186:189], v[104:107]
	v_mfma_f32_16x16x32_bf16 v[92:95], v[146:149], v[208:211], v[92:95]
	v_mfma_f32_16x16x32_bf16 v[88:91], v[154:157], v[208:211], v[88:91]
	v_mfma_f32_16x16x32_bf16 v[76:79], v[146:149], v[216:219], v[76:79]
	v_mfma_f32_16x16x32_bf16 v[72:75], v[154:157], v[216:219], v[72:75]
	s_setprio 0
	s_setprio 1
	v_mfma_f32_16x16x32_bf16 v[116:119], v[158:161], v[174:177], 0
	v_mfma_f32_16x16x32_bf16 v[112:115], v[166:169], v[174:177], 0
	v_mfma_f32_16x16x32_bf16 v[100:103], v[158:161], v[182:185], 0
	v_mfma_f32_16x16x32_bf16 v[96:99], v[166:169], v[182:185], 0
	v_mfma_f32_16x16x32_bf16 v[84:87], v[158:161], v[204:207], 0
	v_mfma_f32_16x16x32_bf16 v[80:83], v[166:169], v[204:207], 0
	v_mfma_f32_16x16x32_bf16 v[68:71], v[158:161], v[212:215], 0
	v_mfma_f32_16x16x32_bf16 v[64:67], v[166:169], v[212:215], 0
	v_mfma_f32_16x16x32_bf16 v[116:119], v[162:165], v[178:181], v[116:119]
	v_mfma_f32_16x16x32_bf16 v[112:115], v[170:173], v[178:181], v[112:115]
	v_mfma_f32_16x16x32_bf16 v[100:103], v[162:165], v[186:189], v[100:103]
	v_mfma_f32_16x16x32_bf16 v[96:99], v[170:173], v[186:189], v[96:99]
	v_mfma_f32_16x16x32_bf16 v[84:87], v[162:165], v[208:211], v[84:87]
	v_mfma_f32_16x16x32_bf16 v[80:83], v[170:173], v[208:211], v[80:83]
	v_mfma_f32_16x16x32_bf16 v[68:71], v[162:165], v[216:219], v[68:71]
	v_mfma_f32_16x16x32_bf16 v[64:67], v[170:173], v[216:219], v[64:67]
	s_barrier
	s_setprio 0
	s_add_i32 s52, s52, s31
	v_lshl_add_u64 v[190:191], s[50:51], 0, v[192:193]
	s_mov_b32 m0, s52
	ds_read_b128 v[174:177], v141 offset:16384
	ds_read_b128 v[178:181], v141 offset:17408
	ds_read_b128 v[182:185], v141 offset:18432
	ds_read_b128 v[186:189], v141 offset:19456
	ds_read_b128 v[204:207], v141 offset:20480
	ds_read_b128 v[208:211], v141 offset:21504
	ds_read_b128 v[212:215], v141 offset:22528
	ds_read_b128 v[216:219], v141 offset:23552
	global_load_lds_dwordx4 v[190:191], off
	s_add_i32 m0, s52, 0x2000
	v_lshl_add_u64 v[194:195], s[50:51], 0, v[128:129]
	s_add_u32 s50, s50, s12
	s_addc_u32 s51, s51, s13
	s_add_i32 s52, s53, s31
	global_load_lds_dwordx4 v[194:195], off
	v_lshl_add_u64 v[200:201], s[50:51], 0, v[192:193]
	s_mov_b32 m0, s52
	v_lshl_add_u64 v[202:203], s[50:51], 0, v[128:129]
	global_load_lds_dwordx4 v[200:201], off
	s_add_i32 m0, s52, 0x2000
	v_lshl_add_u64 v[220:221], s[26:27], 0, v[132:133]
	global_load_lds_dwordx4 v[202:203], off
	s_mov_b32 m0, s34
	v_lshl_add_u64 v[222:223], s[26:27], 0, v[130:131]
	global_load_lds_dwordx4 v[220:221], off
	s_mov_b32 m0, s35
	s_nop 0
	global_load_lds_dwordx4 v[222:223], off
	s_waitcnt vmcnt(8)
	s_waitcnt lgkmcnt(0)
	s_setprio 1
	s_barrier
; #define PG8_STAGE(bufoff, gbase, voff) do { _Pragma("unroll") for (int _i = 0; _i < 2; ++_i) \
;         __builtin_amdgcn_global_load_lds((const unsigned*)((const char*)(gbase) + (voff)[_i]), (PG8_LAS unsigned*)(lds + (bufoff) + ldsw + _i * 8192), 16, 0, 0); } while (0)
; #define PG8_LDA(dst, b, h) do { _Pragma("unroll") for (int m = 0; m < 4; ++m) _Pragma("unroll") for (int k = 0; k < 2; ++k) dst[m][k] = *(const PG8_LAS bf16x8*)(lds + PG8_SA(b, h) + aoff + m * 2048 + k * 1024); } while (0)
; #define PG8_LDB(dst, b, h) do { _Pragma("unroll") for (int n = 0; n < 2; ++n) _Pragma("unroll") for (int k = 0; k < 2; ++k) dst[n][k] = *(const PG8_LAS bf16x8*)(lds + PG8_SB(b, h) + boff + n * 2048 + k * 1024); } while (0)
; #define PG8_MMA(ai, bj, At, Bt) do { __builtin_amdgcn_s_setprio(1); _Pragma("unroll") for (int m = 0; m < 4; ++m) _Pragma("unroll") for (int n = 0; n < 2; ++n) _Pragma("unroll") for (int k = 0; k < 2; ++k) \
;         acc[ai][bj][m][n] = __builtin_amdgcn_mfma_f32_16x16x32_bf16(Bt[n][k], At[m][k], acc[ai][bj][m][n], 0, 0, 0); __builtin_amdgcn_s_setprio(0); } while (0)
; #define PG8_WAIT_SEL(d, w4, w8) do { if constexpr (Epi::SPLIT) { if (d) { if constexpr (Epi::NSH == 4) PG8_WAIT_V(w4); else PG8_WAIT_V(w8); } else PG8_WAIT_V(8); } else PG8_WAIT_V(8); } while (0)
; #define PG8_WAIT_L(n) asm volatile("s_waitcnt lgkmcnt(" #n ")" ::: "memory")
; #define PG8_BAR __builtin_amdgcn_s_barrier()
; #define PG8_SCHED __builtin_amdgcn_sched_barrier(0)
; template <class Epi, class Sched, bool ALIGN_EPI = false, bool SP2 = false>
; __device__ __forceinline__ void gemm_phase(PG8_LAS unsigned char* lds, const Gemm g, const Sched& S, const Epi& E) {
;     ...
;             PG8_WAIT_L(0); PG8_BAR; PG8_MMA(1, 0, At, B0); PG8_MMA(1, 1, At, B1); PG8_BAR; PG8_SCHED;
;             PG8_LDB(B0, 1, 0); PG8_LDB(B1, 1, 1); PG8_SCHED; PG8_LDA(At, 1, 0); PG8_STAGE(PG8_SA(0, 1), a2 + hstepA, voffA);
;             PG8_WAIT_SEL(defer, 12, 16); PG8_WAIT_L(0); PG8_BAR; PG8_MMA(0, 0, At, B0); PG8_MMA(0, 1, At, B1); PG8_BAR; PG8_SCHED;
	v_mfma_f32_16x16x32_bf16 v[60:63], v[142:145], v[174:177], 0
	v_mfma_f32_16x16x32_bf16 v[56:59], v[150:153], v[174:177], 0
	v_mfma_f32_16x16x32_bf16 v[44:47], v[142:145], v[182:185], 0
	v_mfma_f32_16x16x32_bf16 v[40:43], v[150:153], v[182:185], 0
	v_mfma_f32_16x16x32_bf16 v[28:31], v[142:145], v[204:207], 0
	v_mfma_f32_16x16x32_bf16 v[24:27], v[150:153], v[204:207], 0
	v_mfma_f32_16x16x32_bf16 v[12:15], v[142:145], v[212:215], 0
	v_mfma_f32_16x16x32_bf16 v[8:11], v[150:153], v[212:215], 0
	v_mfma_f32_16x16x32_bf16 v[60:63], v[146:149], v[178:181], v[60:63]
	v_mfma_f32_16x16x32_bf16 v[56:59], v[154:157], v[178:181], v[56:59]
	v_mfma_f32_16x16x32_bf16 v[44:47], v[146:149], v[186:189], v[44:47]
	v_mfma_f32_16x16x32_bf16 v[40:43], v[154:157], v[186:189], v[40:43]
	v_mfma_f32_16x16x32_bf16 v[28:31], v[146:149], v[208:211], v[28:31]
	v_mfma_f32_16x16x32_bf16 v[24:27], v[154:157], v[208:211], v[24:27]
	v_mfma_f32_16x16x32_bf16 v[12:15], v[146:149], v[216:219], v[12:15]
	v_mfma_f32_16x16x32_bf16 v[8:11], v[154:157], v[216:219], v[8:11]
	s_setprio 0
	s_setprio 1
	v_mfma_f32_16x16x32_bf16 v[52:55], v[158:161], v[174:177], 0
	v_mfma_f32_16x16x32_bf16 v[48:51], v[166:169], v[174:177], 0
	v_mfma_f32_16x16x32_bf16 v[36:39], v[158:161], v[182:185], 0
	v_mfma_f32_16x16x32_bf16 v[32:35], v[166:169], v[182:185], 0
	v_mfma_f32_16x16x32_bf16 v[20:23], v[158:161], v[204:207], 0
	v_mfma_f32_16x16x32_bf16 v[16:19], v[166:169], v[204:207], 0
	v_mfma_f32_16x16x32_bf16 v[4:7], v[158:161], v[212:215], 0
	v_mfma_f32_16x16x32_bf16 v[0:3], v[166:169], v[212:215], 0
	v_mfma_f32_16x16x32_bf16 v[52:55], v[162:165], v[178:181], v[52:55]
	v_mfma_f32_16x16x32_bf16 v[48:51], v[170:173], v[178:181], v[48:51]
	v_mfma_f32_16x16x32_bf16 v[36:39], v[162:165], v[186:189], v[36:39]
	v_mfma_f32_16x16x32_bf16 v[32:35], v[170:173], v[186:189], v[32:35]
	v_mfma_f32_16x16x32_bf16 v[20:23], v[162:165], v[208:211], v[20:23]
	v_mfma_f32_16x16x32_bf16 v[16:19], v[170:173], v[208:211], v[16:19]
	v_mfma_f32_16x16x32_bf16 v[4:7], v[162:165], v[216:219], v[4:7]
	v_mfma_f32_16x16x32_bf16 v[0:3], v[170:173], v[216:219], v[0:3]
	s_barrier
	s_setprio 0
	s_add_i32 s50, 0, 0x18000
	s_add_i32 s51, 0, 0x1c000
	v_add_u32_e32 v154, s50, v140
	v_add_u32_e32 v170, s51, v140
	ds_read_b128 v[142:145], v154
	ds_read_b128 v[146:149], v154 offset:1024
	ds_read_b128 v[150:153], v154 offset:2048
	ds_read_b128 v[154:157], v154 offset:3072
	ds_read_b128 v[158:161], v170
	ds_read_b128 v[162:165], v170 offset:1024
	ds_read_b128 v[166:169], v170 offset:2048
	ds_read_b128 v[170:173], v170 offset:3072
	s_add_u32 s26, s26, s0
	s_addc_u32 s27, s27, s1
	s_mov_b32 m0, s36
	v_lshl_add_u64 v[224:225], s[26:27], 0, v[132:133]
	ds_read_b128 v[174:177], v141 offset:32768
	ds_read_b128 v[178:181], v141 offset:33792
	ds_read_b128 v[182:185], v141 offset:34816
	ds_read_b128 v[186:189], v141 offset:35840
	ds_read_b128 v[204:207], v141 offset:36864
	ds_read_b128 v[208:211], v141 offset:37888
	ds_read_b128 v[212:215], v141 offset:38912
	ds_read_b128 v[216:219], v141 offset:39936
	global_load_lds_dwordx4 v[224:225], off
	v_lshl_add_u64 v[224:225], s[26:27], 0, v[130:131]
	s_mov_b32 m0, s37
	s_nop 0
	global_load_lds_dwordx4 v[224:225], off
	s_waitcnt vmcnt(8)
	s_waitcnt lgkmcnt(0)
	s_setprio 1
	s_barrier
	v_mfma_f32_16x16x32_bf16 v[120:123], v[142:145], v[174:177], v[120:123]
	v_mfma_f32_16x16x32_bf16 v[124:127], v[150:153], v[174:177], v[124:127]
	v_mfma_f32_16x16x32_bf16 v[108:111], v[142:145], v[182:185], v[108:111]
	v_mfma_f32_16x16x32_bf16 v[104:107], v[150:153], v[182:185], v[104:107]
	v_mfma_f32_16x16x32_bf16 v[92:95], v[142:145], v[204:207], v[92:95]
	v_mfma_f32_16x16x32_bf16 v[88:91], v[150:153], v[204:207], v[88:91]
	v_mfma_f32_16x16x32_bf16 v[76:79], v[142:145], v[212:215], v[76:79]
	v_mfma_f32_16x16x32_bf16 v[72:75], v[150:153], v[212:215], v[72:75]
	v_mfma_f32_16x16x32_bf16 v[120:123], v[146:149], v[178:181], v[120:123]
	v_mfma_f32_16x16x32_bf16 v[124:127], v[154:157], v[178:181], v[124:127]
	v_mfma_f32_16x16x32_bf16 v[108:111], v[146:149], v[186:189], v[108:111]
	v_mfma_f32_16x16x32_bf16 v[104:107], v[154:157], v[186:189], v[104:107]
	v_mfma_f32_16x16x32_bf16 v[92:95], v[146:149], v[208:211], v[92:95]
	v_mfma_f32_16x16x32_bf16 v[88:91], v[154:157], v[208:211], v[88:91]
	v_mfma_f32_16x16x32_bf16 v[76:79], v[146:149], v[216:219], v[76:79]
	v_mfma_f32_16x16x32_bf16 v[72:75], v[154:157], v[216:219], v[72:75]
	s_setprio 0
	s_setprio 1
	v_mfma_f32_16x16x32_bf16 v[116:119], v[158:161], v[174:177], v[116:119]
	v_mfma_f32_16x16x32_bf16 v[112:115], v[166:169], v[174:177], v[112:115]
	v_mfma_f32_16x16x32_bf16 v[100:103], v[158:161], v[182:185], v[100:103]
	v_mfma_f32_16x16x32_bf16 v[96:99], v[166:169], v[182:185], v[96:99]
	v_mfma_f32_16x16x32_bf16 v[84:87], v[158:161], v[204:207], v[84:87]
	v_mfma_f32_16x16x32_bf16 v[80:83], v[166:169], v[204:207], v[80:83]
	v_mfma_f32_16x16x32_bf16 v[68:71], v[158:161], v[212:215], v[68:71]
	v_mfma_f32_16x16x32_bf16 v[64:67], v[166:169], v[212:215], v[64:67]
	v_mfma_f32_16x16x32_bf16 v[116:119], v[162:165], v[178:181], v[116:119]
	v_mfma_f32_16x16x32_bf16 v[112:115], v[170:173], v[178:181], v[112:115]
	v_mfma_f32_16x16x32_bf16 v[100:103], v[162:165], v[186:189], v[100:103]
	v_mfma_f32_16x16x32_bf16 v[96:99], v[170:173], v[186:189], v[96:99]
	v_mfma_f32_16x16x32_bf16 v[84:87], v[162:165], v[208:211], v[84:87]
	v_mfma_f32_16x16x32_bf16 v[80:83], v[170:173], v[208:211], v[80:83]
	v_mfma_f32_16x16x32_bf16 v[68:71], v[162:165], v[216:219], v[68:71]
	v_mfma_f32_16x16x32_bf16 v[64:67], v[170:173], v[216:219], v[64:67]
	s_barrier
; #define PG8_STAGE(bufoff, gbase, voff) do { _Pragma("unroll") for (int _i = 0; _i < 2; ++_i) \
;         __builtin_amdgcn_global_load_lds((const unsigned*)((const char*)(gbase) + (voff)[_i]), (PG8_LAS unsigned*)(lds + (bufoff) + ldsw + _i * 8192), 16, 0, 0); } while (0)
; #define PG8_LDA(dst, b, h) do { _Pragma("unroll") for (int m = 0; m < 4; ++m) _Pragma("unroll") for (int k = 0; k < 2; ++k) dst[m][k] = *(const PG8_LAS bf16x8*)(lds + PG8_SA(b, h) + aoff + m * 2048 + k * 1024); } while (0)
; #define PG8_LDB(dst, b, h) do { _Pragma("unroll") for (int n = 0; n < 2; ++n) _Pragma("unroll") for (int k = 0; k < 2; ++k) dst[n][k] = *(const PG8_LAS bf16x8*)(lds + PG8_SB(b, h) + boff + n * 2048 + k * 1024); } while (0)
; #define PG8_MMA(ai, bj, At, Bt) do { __builtin_amdgcn_s_setprio(1); _Pragma("unroll") for (int m = 0; m < 4; ++m) _Pragma("unroll") for (int n = 0; n < 2; ++n) _Pragma("unroll") for (int k = 0; k < 2; ++k) \
;         acc[ai][bj][m][n] = __builtin_amdgcn_mfma_f32_16x16x32_bf16(Bt[n][k], At[m][k], acc[ai][bj][m][n], 0, 0, 0); __builtin_amdgcn_s_setprio(0); } while (0)
; #define PG8_WAIT_V(n) asm volatile("s_waitcnt vmcnt(" #n ")" ::: "memory")
; #define PG8_WAIT_SEL(d, w4, w8) do { if constexpr (Epi::SPLIT) { if (d) { if constexpr (Epi::NSH == 4) PG8_WAIT_V(w4); else PG8_WAIT_V(w8); } else PG8_WAIT_V(8); } else PG8_WAIT_V(8); } while (0)
; template <class Epi, class Sched, bool ALIGN_EPI = false, bool SP2 = false>
; __device__ __forceinline__ void gemm_phase(PG8_LAS unsigned char* lds, const Gemm g, const Sched& S, const Epi& E) {
;     ...
;             const char* a1 = cA + (size_t)(t + 1) * kstep;
;             const char* a2 = last ? nA : cA + (size_t)(t + 2) * kstep; const char* b2 = last ? nB : cB + (size_t)(t + 2) * kstep;
;             const char* a3 = a2 + kstep; const char* b3 = b2 + kstep;
;             if (last && has_next) S.a_ready(nxt);
;             if constexpr (SP2) {
;             PG8_LDB(B0, 0, 0); PG8_LDB(B1, 0, 1); PG8_SCHED; PG8_LDA(At, 0, 0); PG8_STAGE(PG8_SA(1, 1), a1 + hstepA, voffA);
;             if (plast) PG8_WAIT_V(10); else PG8_WAIT_SEL(defer, 12, 16);
;     ...
;             PG8_LDA(At, 1, 1); PG8_STAGE(PG8_SB(1, 0), b3, voffB); PG8_STAGE(PG8_SB(1, 1), b3 + hstep, voffB); PG8_STAGE(PG8_SA(1, 0), a3, voffA);
;             PG8_WAIT_V(8); PG8_WAIT_L(0); PG8_BAR; PG8_MMA(1, 0, At, B0); PG8_MMA(1, 1, At, B1); PG8_BAR; PG8_SCHED;
	s_setprio 0
	s_add_i32 s26, s50, s31
	v_lshl_add_u64 v[190:191], v[190:191], 0, s[90:91]
	s_mov_b32 m0, s26
	ds_read_b128 v[174:177], v141 offset:49152
	ds_read_b128 v[178:181], v141 offset:50176
	ds_read_b128 v[182:185], v141 offset:51200
	ds_read_b128 v[186:189], v141 offset:52224
	ds_read_b128 v[204:207], v141 offset:53248
	ds_read_b128 v[208:211], v141 offset:54272
	ds_read_b128 v[212:215], v141 offset:55296
	ds_read_b128 v[216:219], v141 offset:56320
	global_load_lds_dwordx4 v[190:191], off
	v_lshl_add_u64 v[190:191], v[194:195], 0, s[90:91]
	s_add_i32 m0, s26, 0x2000
	s_add_i32 s26, s51, s31
	global_load_lds_dwordx4 v[190:191], off
	v_lshl_add_u64 v[190:191], v[200:201], 0, s[90:91]
	s_mov_b32 m0, s26
	s_nop 0
	global_load_lds_dwordx4 v[190:191], off
	v_lshl_add_u64 v[190:191], v[202:203], 0, s[90:91]
	s_add_i32 m0, s26, 0x2000
	s_nop 0
	global_load_lds_dwordx4 v[190:191], off
	v_lshl_add_u64 v[190:191], v[220:221], 0, s[90:91]
	s_mov_b32 m0, s40
	s_nop 0
	global_load_lds_dwordx4 v[190:191], off
	v_lshl_add_u64 v[190:191], v[222:223], 0, s[90:91]
	s_mov_b32 m0, s41
	s_nop 0
	global_load_lds_dwordx4 v[190:191], off
	s_waitcnt vmcnt(8)
	s_waitcnt lgkmcnt(0)
	s_setprio 1
	s_barrier
	v_mfma_f32_16x16x32_bf16 v[60:63], v[142:145], v[174:177], v[60:63]
	v_mfma_f32_16x16x32_bf16 v[56:59], v[150:153], v[174:177], v[56:59]
	v_mfma_f32_16x16x32_bf16 v[44:47], v[142:145], v[182:185], v[44:47]
	v_mfma_f32_16x16x32_bf16 v[40:43], v[150:153], v[182:185], v[40:43]
	v_mfma_f32_16x16x32_bf16 v[28:31], v[142:145], v[204:207], v[28:31]
	v_mfma_f32_16x16x32_bf16 v[24:27], v[150:153], v[204:207], v[24:27]
	v_mfma_f32_16x16x32_bf16 v[12:15], v[142:145], v[212:215], v[12:15]
	v_mfma_f32_16x16x32_bf16 v[8:11], v[150:153], v[212:215], v[8:11]
	v_mfma_f32_16x16x32_bf16 v[60:63], v[146:149], v[178:181], v[60:63]
	v_mfma_f32_16x16x32_bf16 v[56:59], v[154:157], v[178:181], v[56:59]
	v_mfma_f32_16x16x32_bf16 v[44:47], v[146:149], v[186:189], v[44:47]
	v_mfma_f32_16x16x32_bf16 v[40:43], v[154:157], v[186:189], v[40:43]
	v_mfma_f32_16x16x32_bf16 v[28:31], v[146:149], v[208:211], v[28:31]
	v_mfma_f32_16x16x32_bf16 v[24:27], v[154:157], v[208:211], v[24:27]
	v_mfma_f32_16x16x32_bf16 v[12:15], v[146:149], v[216:219], v[12:15]
	v_mfma_f32_16x16x32_bf16 v[8:11], v[154:157], v[216:219], v[8:11]
	s_setprio 0
	s_setprio 1
	v_mfma_f32_16x16x32_bf16 v[52:55], v[158:161], v[174:177], v[52:55]
	v_mfma_f32_16x16x32_bf16 v[48:51], v[166:169], v[174:177], v[48:51]
	v_mfma_f32_16x16x32_bf16 v[36:39], v[158:161], v[182:185], v[36:39]
	v_mfma_f32_16x16x32_bf16 v[32:35], v[166:169], v[182:185], v[32:35]
	v_mfma_f32_16x16x32_bf16 v[20:23], v[158:161], v[204:207], v[20:23]
	v_mfma_f32_16x16x32_bf16 v[16:19], v[166:169], v[204:207], v[16:19]
	v_mfma_f32_16x16x32_bf16 v[4:7], v[158:161], v[212:215], v[4:7]
	v_mfma_f32_16x16x32_bf16 v[0:3], v[166:169], v[212:215], v[0:3]
	v_mfma_f32_16x16x32_bf16 v[52:55], v[162:165], v[178:181], v[52:55]
	v_mfma_f32_16x16x32_bf16 v[48:51], v[170:173], v[178:181], v[48:51]
	v_mfma_f32_16x16x32_bf16 v[36:39], v[162:165], v[186:189], v[36:39]
	v_mfma_f32_16x16x32_bf16 v[32:35], v[170:173], v[186:189], v[32:35]
	v_mfma_f32_16x16x32_bf16 v[20:23], v[162:165], v[208:211], v[20:23]
	v_mfma_f32_16x16x32_bf16 v[16:19], v[170:173], v[208:211], v[16:19]
	v_mfma_f32_16x16x32_bf16 v[4:7], v[162:165], v[216:219], v[4:7]
	v_mfma_f32_16x16x32_bf16 v[0:3], v[170:173], v[216:219], v[0:3]
	s_barrier
	s_setprio 0
	s_add_u32 s24, s24, 0x100
	s_addc_u32 s25, s25, 0
	s_add_u32 s33, s33, 0x100
	s_addc_u32 s48, s48, 0
	s_cmp_ge_i32 s49, s38
	s_mov_b32 s26, s49
	s_cbranch_scc0 .LBB0_464
	s_branch .LBB0_465
.LBB0_464:
	s_add_i32 s49, s26, 2
	s_add_u32 s50, s24, 0x80
	s_addc_u32 s27, s25, 0
	s_add_i32 s52, 0, 0x10000
	s_cmp_eq_u32 s42, s26
	s_cselect_b32 s27, s9, s27
	s_cselect_b32 s26, s8, s50
	s_cselect_b32 s51, s23, s48
	s_cselect_b32 s50, s22, s33
	s_add_i32 s53, 0, 0x14000
	v_add_u32_e32 v154, s52, v140
	v_add_u32_e32 v170, s53, v140
	ds_read_b128 v[142:145], v154
	ds_read_b128 v[146:149], v154 offset:1024
	ds_read_b128 v[150:153], v154 offset:2048
	ds_read_b128 v[154:157], v154 offset:3072
	ds_read_b128 v[158:161], v170
	ds_read_b128 v[162:165], v170 offset:1024
	ds_read_b128 v[166:169], v170 offset:2048
	ds_read_b128 v[170:173], v170 offset:3072
	v_lshl_add_u64 v[190:191], s[24:25], 0, v[134:135]
	s_add_i32 m0, s34, 0xc000
	ds_read_b128 v[174:177], v141
	ds_read_b128 v[178:181], v141 offset:1024
	ds_read_b128 v[182:185], v141 offset:2048
	ds_read_b128 v[186:189], v141 offset:3072
	ds_read_b128 v[204:207], v141 offset:4096
	ds_read_b128 v[208:211], v141 offset:5120
	ds_read_b128 v[212:215], v141 offset:6144
	ds_read_b128 v[216:219], v141 offset:7168
	global_load_lds_dwordx4 v[190:191], off
	v_lshl_add_u64 v[190:191], s[24:25], 0, v[136:137]
	s_add_i32 m0, s34, 0xe000
	s_nop 0
	global_load_lds_dwordx4 v[190:191], off
	s_waitcnt vmcnt(8)
	s_waitcnt lgkmcnt(0)
	s_setprio 1
	s_barrier
; #define PG8_STAGE(bufoff, gbase, voff) do { _Pragma("unroll") for (int _i = 0; _i < 2; ++_i) \
;         __builtin_amdgcn_global_load_lds((const unsigned*)((const char*)(gbase) + (voff)[_i]), (PG8_LAS unsigned*)(lds + (bufoff) + ldsw + _i * 8192), 16, 0, 0); } while (0)
; #define PG8_LDA(dst, b, h) do { _Pragma("unroll") for (int m = 0; m < 4; ++m) _Pragma("unroll") for (int k = 0; k < 2; ++k) dst[m][k] = *(const PG8_LAS bf16x8*)(lds + PG8_SA(b, h) + aoff + m * 2048 + k * 1024); } while (0)
; #define PG8_MMA(ai, bj, At, Bt) do { __builtin_amdgcn_s_setprio(1); _Pragma("unroll") for (int m = 0; m < 4; ++m) _Pragma("unroll") for (int n = 0; n < 2; ++n) _Pragma("unroll") for (int k = 0; k < 2; ++k) \
;         acc[ai][bj][m][n] = __builtin_amdgcn_mfma_f32_16x16x32_bf16(Bt[n][k], At[m][k], acc[ai][bj][m][n], 0, 0, 0); __builtin_amdgcn_s_setprio(0); } while (0)
; #define PG8_WAIT_V(n) asm volatile("s_waitcnt vmcnt(" #n ")" ::: "memory")
; #define PG8_WAIT_SEL(d, w4, w8) do { if constexpr (Epi::SPLIT) { if (d) { if constexpr (Epi::NSH == 4) PG8_WAIT_V(w4); else PG8_WAIT_V(w8); } else PG8_WAIT_V(8); } else PG8_WAIT_V(8); } while (0)
; #define PG8_WAIT_L(n) asm volatile("s_waitcnt lgkmcnt(" #n ")" ::: "memory")
; #define PG8_BAR __builtin_amdgcn_s_barrier()
; #define PG8_SCHED __builtin_amdgcn_sched_barrier(0)
; template <class Epi, class Sched, bool ALIGN_EPI = false, bool SP2 = false>
; __device__ __forceinline__ void gemm_phase(PG8_LAS unsigned char* lds, const Gemm g, const Sched& S, const Epi& E) {
;     ...
;             PG8_WAIT_L(0); PG8_BAR; PG8_MMA(0, 0, At, B0); PG8_MMA(0, 1, At, B1);
;             if constexpr (Epi::SPLIT) { if (defer) {
;                 E.second(acc, prev, rv1, wr, wc, fr, fq);
;                 _Pragma("unroll") for (int b = 0; b < 2; ++b) _Pragma("unroll") for (int m = 0; m < 4; ++m) _Pragma("unroll") for (int n = 0; n < 2; ++n) acc[1][b][m][n] = (f32x4){0.f, 0.f, 0.f, 0.f}; } }
;             PG8_BAR; PG8_SCHED;
;             PG8_LDA(At, 0, 1); PG8_STAGE(PG8_SB(0, 0), b2, voffB); PG8_STAGE(PG8_SB(0, 1), b2 + hstep, voffB); PG8_STAGE(PG8_SA(0, 0), a2, voffA);
;             if (plast) PG8_WAIT_V(10); else PG8_WAIT_SEL(defer, 16, 24);
;             PG8_WAIT_L(0); PG8_BAR; PG8_MMA(1, 0, At, B0); PG8_MMA(1, 1, At, B1); PG8_BAR; PG8_SCHED;
	v_mfma_f32_16x16x32_bf16 v[120:123], v[142:145], v[174:177], v[120:123]
	v_mfma_f32_16x16x32_bf16 v[124:127], v[150:153], v[174:177], v[124:127]
	v_mfma_f32_16x16x32_bf16 v[108:111], v[142:145], v[182:185], v[108:111]
	v_mfma_f32_16x16x32_bf16 v[104:107], v[150:153], v[182:185], v[104:107]
	v_mfma_f32_16x16x32_bf16 v[92:95], v[142:145], v[204:207], v[92:95]
	v_mfma_f32_16x16x32_bf16 v[88:91], v[150:153], v[204:207], v[88:91]
	v_mfma_f32_16x16x32_bf16 v[76:79], v[142:145], v[212:215], v[76:79]
	v_mfma_f32_16x16x32_bf16 v[72:75], v[150:153], v[212:215], v[72:75]
	v_mfma_f32_16x16x32_bf16 v[120:123], v[146:149], v[178:181], v[120:123]
	v_mfma_f32_16x16x32_bf16 v[124:127], v[154:157], v[178:181], v[124:127]
	v_mfma_f32_16x16x32_bf16 v[108:111], v[146:149], v[186:189], v[108:111]
	v_mfma_f32_16x16x32_bf16 v[104:107], v[154:157], v[186:189], v[104:107]
	v_mfma_f32_16x16x32_bf16 v[92:95], v[146:149], v[208:211], v[92:95]
	v_mfma_f32_16x16x32_bf16 v[88:91], v[154:157], v[208:211], v[88:91]
	v_mfma_f32_16x16x32_bf16 v[76:79], v[146:149], v[216:219], v[76:79]
	v_mfma_f32_16x16x32_bf16 v[72:75], v[154:157], v[216:219], v[72:75]
	s_setprio 0
	s_setprio 1
	v_mfma_f32_16x16x32_bf16 v[116:119], v[158:161], v[174:177], v[116:119]
	v_mfma_f32_16x16x32_bf16 v[112:115], v[166:169], v[174:177], v[112:115]
	v_mfma_f32_16x16x32_bf16 v[100:103], v[158:161], v[182:185], v[100:103]
	v_mfma_f32_16x16x32_bf16 v[96:99], v[166:169], v[182:185], v[96:99]
	v_mfma_f32_16x16x32_bf16 v[84:87], v[158:161], v[204:207], v[84:87]
	v_mfma_f32_16x16x32_bf16 v[80:83], v[166:169], v[204:207], v[80:83]
	v_mfma_f32_16x16x32_bf16 v[68:71], v[158:161], v[212:215], v[68:71]
	v_mfma_f32_16x16x32_bf16 v[64:67], v[166:169], v[212:215], v[64:67]
	v_mfma_f32_16x16x32_bf16 v[116:119], v[162:165], v[178:181], v[116:119]
	v_mfma_f32_16x16x32_bf16 v[112:115], v[170:173], v[178:181], v[112:115]
	v_mfma_f32_16x16x32_bf16 v[100:103], v[162:165], v[186:189], v[100:103]
	v_mfma_f32_16x16x32_bf16 v[96:99], v[170:173], v[186:189], v[96:99]
	v_mfma_f32_16x16x32_bf16 v[84:87], v[162:165], v[208:211], v[84:87]
	v_mfma_f32_16x16x32_bf16 v[80:83], v[170:173], v[208:211], v[80:83]
	v_mfma_f32_16x16x32_bf16 v[68:71], v[162:165], v[216:219], v[68:71]
	v_mfma_f32_16x16x32_bf16 v[64:67], v[170:173], v[216:219], v[64:67]
	s_barrier
	s_setprio 0
	s_add_i32 s52, s52, s31
	v_lshl_add_u64 v[190:191], s[50:51], 0, v[192:193]
	s_mov_b32 m0, s52
	ds_read_b128 v[174:177], v141 offset:16384
	ds_read_b128 v[178:181], v141 offset:17408
	ds_read_b128 v[182:185], v141 offset:18432
	ds_read_b128 v[186:189], v141 offset:19456
	ds_read_b128 v[204:207], v141 offset:20480
	ds_read_b128 v[208:211], v141 offset:21504
	ds_read_b128 v[212:215], v141 offset:22528
	ds_read_b128 v[216:219], v141 offset:23552
	global_load_lds_dwordx4 v[190:191], off
	s_add_i32 m0, s52, 0x2000
	v_lshl_add_u64 v[194:195], s[50:51], 0, v[128:129]
	s_add_u32 s50, s50, s12
	s_addc_u32 s51, s51, s13
	s_add_i32 s52, s53, s31
	global_load_lds_dwordx4 v[194:195], off
	v_lshl_add_u64 v[200:201], s[50:51], 0, v[192:193]
	s_mov_b32 m0, s52
	v_lshl_add_u64 v[202:203], s[50:51], 0, v[128:129]
	global_load_lds_dwordx4 v[200:201], off
	s_add_i32 m0, s52, 0x2000
	v_lshl_add_u64 v[220:221], s[26:27], 0, v[132:133]
	global_load_lds_dwordx4 v[202:203], off
	s_mov_b32 m0, s34
	v_lshl_add_u64 v[222:223], s[26:27], 0, v[130:131]
	global_load_lds_dwordx4 v[220:221], off
	s_mov_b32 m0, s35
	s_nop 0
	global_load_lds_dwordx4 v[222:223], off
	s_waitcnt vmcnt(8)
	s_waitcnt lgkmcnt(0)
	s_setprio 1
	s_barrier
	v_mfma_f32_16x16x32_bf16 v[60:63], v[142:145], v[174:177], v[60:63]
	v_mfma_f32_16x16x32_bf16 v[56:59], v[150:153], v[174:177], v[56:59]
	v_mfma_f32_16x16x32_bf16 v[44:47], v[142:145], v[182:185], v[44:47]
	v_mfma_f32_16x16x32_bf16 v[40:43], v[150:153], v[182:185], v[40:43]
	v_mfma_f32_16x16x32_bf16 v[28:31], v[142:145], v[204:207], v[28:31]
	v_mfma_f32_16x16x32_bf16 v[24:27], v[150:153], v[204:207], v[24:27]
	v_mfma_f32_16x16x32_bf16 v[12:15], v[142:145], v[212:215], v[12:15]
	v_mfma_f32_16x16x32_bf16 v[8:11], v[150:153], v[212:215], v[8:11]
	v_mfma_f32_16x16x32_bf16 v[60:63], v[146:149], v[178:181], v[60:63]
	v_mfma_f32_16x16x32_bf16 v[56:59], v[154:157], v[178:181], v[56:59]
	v_mfma_f32_16x16x32_bf16 v[44:47], v[146:149], v[186:189], v[44:47]
	v_mfma_f32_16x16x32_bf16 v[40:43], v[154:157], v[186:189], v[40:43]
	v_mfma_f32_16x16x32_bf16 v[28:31], v[146:149], v[208:211], v[28:31]
	v_mfma_f32_16x16x32_bf16 v[24:27], v[154:157], v[208:211], v[24:27]
	v_mfma_f32_16x16x32_bf16 v[12:15], v[146:149], v[216:219], v[12:15]
	v_mfma_f32_16x16x32_bf16 v[8:11], v[154:157], v[216:219], v[8:11]
	s_setprio 0
	s_setprio 1
	v_mfma_f32_16x16x32_bf16 v[52:55], v[158:161], v[174:177], v[52:55]
	v_mfma_f32_16x16x32_bf16 v[48:51], v[166:169], v[174:177], v[48:51]
	v_mfma_f32_16x16x32_bf16 v[36:39], v[158:161], v[182:185], v[36:39]
	v_mfma_f32_16x16x32_bf16 v[32:35], v[166:169], v[182:185], v[32:35]
	v_mfma_f32_16x16x32_bf16 v[20:23], v[158:161], v[204:207], v[20:23]
	v_mfma_f32_16x16x32_bf16 v[16:19], v[166:169], v[204:207], v[16:19]
	v_mfma_f32_16x16x32_bf16 v[4:7], v[158:161], v[212:215], v[4:7]
	v_mfma_f32_16x16x32_bf16 v[0:3], v[166:169], v[212:215], v[0:3]
	v_mfma_f32_16x16x32_bf16 v[52:55], v[162:165], v[178:181], v[52:55]
	v_mfma_f32_16x16x32_bf16 v[48:51], v[170:173], v[178:181], v[48:51]
	v_mfma_f32_16x16x32_bf16 v[36:39], v[162:165], v[186:189], v[36:39]
	v_mfma_f32_16x16x32_bf16 v[32:35], v[170:173], v[186:189], v[32:35]
	v_mfma_f32_16x16x32_bf16 v[20:23], v[162:165], v[208:211], v[20:23]
	v_mfma_f32_16x16x32_bf16 v[16:19], v[170:173], v[208:211], v[16:19]
	v_mfma_f32_16x16x32_bf16 v[4:7], v[162:165], v[216:219], v[4:7]
	v_mfma_f32_16x16x32_bf16 v[0:3], v[170:173], v[216:219], v[0:3]
	s_barrier
; #define PG8_STAGE(bufoff, gbase, voff) do { _Pragma("unroll") for (int _i = 0; _i < 2; ++_i) \
;         __builtin_amdgcn_global_load_lds((const unsigned*)((const char*)(gbase) + (voff)[_i]), (PG8_LAS unsigned*)(lds + (bufoff) + ldsw + _i * 8192), 16, 0, 0); } while (0)
; #define PG8_LDA(dst, b, h) do { _Pragma("unroll") for (int m = 0; m < 4; ++m) _Pragma("unroll") for (int k = 0; k < 2; ++k) dst[m][k] = *(const PG8_LAS bf16x8*)(lds + PG8_SA(b, h) + aoff + m * 2048 + k * 1024); } while (0)
; #define PG8_LDB(dst, b, h) do { _Pragma("unroll") for (int n = 0; n < 2; ++n) _Pragma("unroll") for (int k = 0; k < 2; ++k) dst[n][k] = *(const PG8_LAS bf16x8*)(lds + PG8_SB(b, h) + boff + n * 2048 + k * 1024); } while (0)
; #define PG8_MMA(ai, bj, At, Bt) do { __builtin_amdgcn_s_setprio(1); _Pragma("unroll") for (int m = 0; m < 4; ++m) _Pragma("unroll") for (int n = 0; n < 2; ++n) _Pragma("unroll") for (int k = 0; k < 2; ++k) \
;         acc[ai][bj][m][n] = __builtin_amdgcn_mfma_f32_16x16x32_bf16(Bt[n][k], At[m][k], acc[ai][bj][m][n], 0, 0, 0); __builtin_amdgcn_s_setprio(0); } while (0)
; #define PG8_WAIT_SEL(d, w4, w8) do { if constexpr (Epi::SPLIT) { if (d) { if constexpr (Epi::NSH == 4) PG8_WAIT_V(w4); else PG8_WAIT_V(w8); } else PG8_WAIT_V(8); } else PG8_WAIT_V(8); } while (0)
; #define PG8_WAIT_L(n) asm volatile("s_waitcnt lgkmcnt(" #n ")" ::: "memory")
; #define PG8_BAR __builtin_amdgcn_s_barrier()
; #define PG8_SCHED __builtin_amdgcn_sched_barrier(0)
; template <class Epi, class Sched, bool ALIGN_EPI = false, bool SP2 = false>
; __device__ __forceinline__ void gemm_phase(PG8_LAS unsigned char* lds, const Gemm g, const Sched& S, const Epi& E) {
;     ...
;             PG8_LDB(B0, 1, 0); PG8_LDB(B1, 1, 1); PG8_SCHED; PG8_LDA(At, 1, 0); PG8_STAGE(PG8_SA(0, 1), a2 + hstepA, voffA);
;             PG8_WAIT_SEL(defer, 12, 16); PG8_WAIT_L(0); PG8_BAR; PG8_MMA(0, 0, At, B0); PG8_MMA(0, 1, At, B1); PG8_BAR; PG8_SCHED;
	s_setprio 0
	s_add_i32 s50, 0, 0x18000
	s_add_i32 s51, 0, 0x1c000
	v_add_u32_e32 v154, s50, v140
	v_add_u32_e32 v170, s51, v140
	ds_read_b128 v[142:145], v154
	ds_read_b128 v[146:149], v154 offset:1024
	ds_read_b128 v[150:153], v154 offset:2048
	ds_read_b128 v[154:157], v154 offset:3072
	ds_read_b128 v[158:161], v170
	ds_read_b128 v[162:165], v170 offset:1024
	ds_read_b128 v[166:169], v170 offset:2048
	ds_read_b128 v[170:173], v170 offset:3072
	s_add_u32 s26, s26, s0
	s_addc_u32 s27, s27, s1
	s_mov_b32 m0, s36
	v_lshl_add_u64 v[224:225], s[26:27], 0, v[132:133]
	ds_read_b128 v[174:177], v141 offset:32768
	ds_read_b128 v[178:181], v141 offset:33792
	ds_read_b128 v[182:185], v141 offset:34816
	ds_read_b128 v[186:189], v141 offset:35840
	ds_read_b128 v[204:207], v141 offset:36864
	ds_read_b128 v[208:211], v141 offset:37888
	ds_read_b128 v[212:215], v141 offset:38912
	ds_read_b128 v[216:219], v141 offset:39936
	global_load_lds_dwordx4 v[224:225], off
	v_lshl_add_u64 v[224:225], s[26:27], 0, v[130:131]
	s_mov_b32 m0, s37
	s_nop 0
	global_load_lds_dwordx4 v[224:225], off
	s_waitcnt vmcnt(8)
	s_waitcnt lgkmcnt(0)
	s_setprio 1
	s_barrier
	v_mfma_f32_16x16x32_bf16 v[120:123], v[142:145], v[174:177], v[120:123]
	v_mfma_f32_16x16x32_bf16 v[124:127], v[150:153], v[174:177], v[124:127]
	v_mfma_f32_16x16x32_bf16 v[108:111], v[142:145], v[182:185], v[108:111]
	v_mfma_f32_16x16x32_bf16 v[104:107], v[150:153], v[182:185], v[104:107]
	v_mfma_f32_16x16x32_bf16 v[92:95], v[142:145], v[204:207], v[92:95]
	v_mfma_f32_16x16x32_bf16 v[88:91], v[150:153], v[204:207], v[88:91]
	v_mfma_f32_16x16x32_bf16 v[76:79], v[142:145], v[212:215], v[76:79]
	v_mfma_f32_16x16x32_bf16 v[72:75], v[150:153], v[212:215], v[72:75]
	v_mfma_f32_16x16x32_bf16 v[120:123], v[146:149], v[178:181], v[120:123]
	v_mfma_f32_16x16x32_bf16 v[124:127], v[154:157], v[178:181], v[124:127]
	v_mfma_f32_16x16x32_bf16 v[108:111], v[146:149], v[186:189], v[108:111]
	v_mfma_f32_16x16x32_bf16 v[104:107], v[154:157], v[186:189], v[104:107]
	v_mfma_f32_16x16x32_bf16 v[92:95], v[146:149], v[208:211], v[92:95]
	v_mfma_f32_16x16x32_bf16 v[88:91], v[154:157], v[208:211], v[88:91]
	v_mfma_f32_16x16x32_bf16 v[76:79], v[146:149], v[216:219], v[76:79]
	v_mfma_f32_16x16x32_bf16 v[72:75], v[154:157], v[216:219], v[72:75]
	s_setprio 0
	s_setprio 1
	v_mfma_f32_16x16x32_bf16 v[116:119], v[158:161], v[174:177], v[116:119]
	v_mfma_f32_16x16x32_bf16 v[112:115], v[166:169], v[174:177], v[112:115]
	v_mfma_f32_16x16x32_bf16 v[100:103], v[158:161], v[182:185], v[100:103]
	v_mfma_f32_16x16x32_bf16 v[96:99], v[166:169], v[182:185], v[96:99]
	v_mfma_f32_16x16x32_bf16 v[84:87], v[158:161], v[204:207], v[84:87]
	v_mfma_f32_16x16x32_bf16 v[80:83], v[166:169], v[204:207], v[80:83]
	v_mfma_f32_16x16x32_bf16 v[68:71], v[158:161], v[212:215], v[68:71]
	v_mfma_f32_16x16x32_bf16 v[64:67], v[166:169], v[212:215], v[64:67]
	v_mfma_f32_16x16x32_bf16 v[116:119], v[162:165], v[178:181], v[116:119]
	v_mfma_f32_16x16x32_bf16 v[112:115], v[170:173], v[178:181], v[112:115]
	v_mfma_f32_16x16x32_bf16 v[100:103], v[162:165], v[186:189], v[100:103]
	v_mfma_f32_16x16x32_bf16 v[96:99], v[170:173], v[186:189], v[96:99]
	v_mfma_f32_16x16x32_bf16 v[84:87], v[162:165], v[208:211], v[84:87]
	v_mfma_f32_16x16x32_bf16 v[80:83], v[170:173], v[208:211], v[80:83]
	v_mfma_f32_16x16x32_bf16 v[68:71], v[162:165], v[216:219], v[68:71]
	v_mfma_f32_16x16x32_bf16 v[64:67], v[170:173], v[216:219], v[64:67]
	s_barrier
; #define PG8_STAGE(bufoff, gbase, voff) do { _Pragma("unroll") for (int _i = 0; _i < 2; ++_i) \
;         __builtin_amdgcn_global_load_lds((const unsigned*)((const char*)(gbase) + (voff)[_i]), (PG8_LAS unsigned*)(lds + (bufoff) + ldsw + _i * 8192), 16, 0, 0); } while (0)
; #define PG8_LDA(dst, b, h) do { _Pragma("unroll") for (int m = 0; m < 4; ++m) _Pragma("unroll") for (int k = 0; k < 2; ++k) dst[m][k] = *(const PG8_LAS bf16x8*)(lds + PG8_SA(b, h) + aoff + m * 2048 + k * 1024); } while (0)
; #define PG8_MMA(ai, bj, At, Bt) do { __builtin_amdgcn_s_setprio(1); _Pragma("unroll") for (int m = 0; m < 4; ++m) _Pragma("unroll") for (int n = 0; n < 2; ++n) _Pragma("unroll") for (int k = 0; k < 2; ++k) \
;         acc[ai][bj][m][n] = __builtin_amdgcn_mfma_f32_16x16x32_bf16(Bt[n][k], At[m][k], acc[ai][bj][m][n], 0, 0, 0); __builtin_amdgcn_s_setprio(0); } while (0)
; #define PG8_WAIT_V(n) asm volatile("s_waitcnt vmcnt(" #n ")" ::: "memory")
; #define PG8_WAIT_L(n) asm volatile("s_waitcnt lgkmcnt(" #n ")" ::: "memory")
; #define PG8_BAR __builtin_amdgcn_s_barrier()
; #define PG8_SCHED __builtin_amdgcn_sched_barrier(0)
; template <class Epi, class Sched, bool ALIGN_EPI = false, bool SP2 = false>
; __device__ __forceinline__ void gemm_phase(PG8_LAS unsigned char* lds, const Gemm g, const Sched& S, const Epi& E) {
;     ...
;             PG8_LDA(At, 1, 1); PG8_STAGE(PG8_SB(1, 0), b3, voffB); PG8_STAGE(PG8_SB(1, 1), b3 + hstep, voffB); PG8_STAGE(PG8_SA(1, 0), a3, voffA);
;             PG8_WAIT_V(8); PG8_WAIT_L(0); PG8_BAR; PG8_MMA(1, 0, At, B0); PG8_MMA(1, 1, At, B1); PG8_BAR; PG8_SCHED;
	s_setprio 0
	s_add_i32 s26, s50, s31
	v_lshl_add_u64 v[190:191], v[190:191], 0, s[90:91]
	s_mov_b32 m0, s26
	ds_read_b128 v[174:177], v141 offset:49152
	ds_read_b128 v[178:181], v141 offset:50176
	ds_read_b128 v[182:185], v141 offset:51200
	ds_read_b128 v[186:189], v141 offset:52224
	ds_read_b128 v[204:207], v141 offset:53248
	ds_read_b128 v[208:211], v141 offset:54272
	ds_read_b128 v[212:215], v141 offset:55296
	ds_read_b128 v[216:219], v141 offset:56320
	global_load_lds_dwordx4 v[190:191], off
	v_lshl_add_u64 v[190:191], v[194:195], 0, s[90:91]
	s_add_i32 m0, s26, 0x2000
	s_add_i32 s26, s51, s31
	global_load_lds_dwordx4 v[190:191], off
	v_lshl_add_u64 v[190:191], v[200:201], 0, s[90:91]
	s_mov_b32 m0, s26
	s_nop 0
	global_load_lds_dwordx4 v[190:191], off
	v_lshl_add_u64 v[190:191], v[202:203], 0, s[90:91]
	s_add_i32 m0, s26, 0x2000
	s_nop 0
	global_load_lds_dwordx4 v[190:191], off
	v_lshl_add_u64 v[190:191], v[220:221], 0, s[90:91]
	s_mov_b32 m0, s40
	s_nop 0
	global_load_lds_dwordx4 v[190:191], off
	v_lshl_add_u64 v[190:191], v[222:223], 0, s[90:91]
	s_mov_b32 m0, s41
	s_nop 0
	global_load_lds_dwordx4 v[190:191], off
	s_waitcnt vmcnt(8)
	s_waitcnt lgkmcnt(0)
	s_setprio 1
	s_barrier
	v_mfma_f32_16x16x32_bf16 v[60:63], v[142:145], v[174:177], v[60:63]
	v_mfma_f32_16x16x32_bf16 v[56:59], v[150:153], v[174:177], v[56:59]
	v_mfma_f32_16x16x32_bf16 v[44:47], v[142:145], v[182:185], v[44:47]
	v_mfma_f32_16x16x32_bf16 v[40:43], v[150:153], v[182:185], v[40:43]
	v_mfma_f32_16x16x32_bf16 v[28:31], v[142:145], v[204:207], v[28:31]
	v_mfma_f32_16x16x32_bf16 v[24:27], v[150:153], v[204:207], v[24:27]
	v_mfma_f32_16x16x32_bf16 v[12:15], v[142:145], v[212:215], v[12:15]
	v_mfma_f32_16x16x32_bf16 v[8:11], v[150:153], v[212:215], v[8:11]
	v_mfma_f32_16x16x32_bf16 v[60:63], v[146:149], v[178:181], v[60:63]
	v_mfma_f32_16x16x32_bf16 v[56:59], v[154:157], v[178:181], v[56:59]
	v_mfma_f32_16x16x32_bf16 v[44:47], v[146:149], v[186:189], v[44:47]
	v_mfma_f32_16x16x32_bf16 v[40:43], v[154:157], v[186:189], v[40:43]
	v_mfma_f32_16x16x32_bf16 v[28:31], v[146:149], v[208:211], v[28:31]
	v_mfma_f32_16x16x32_bf16 v[24:27], v[154:157], v[208:211], v[24:27]
	v_mfma_f32_16x16x32_bf16 v[12:15], v[146:149], v[216:219], v[12:15]
	v_mfma_f32_16x16x32_bf16 v[8:11], v[154:157], v[216:219], v[8:11]
	s_setprio 0
	s_setprio 1
	v_mfma_f32_16x16x32_bf16 v[52:55], v[158:161], v[174:177], v[52:55]
	v_mfma_f32_16x16x32_bf16 v[48:51], v[166:169], v[174:177], v[48:51]
	v_mfma_f32_16x16x32_bf16 v[36:39], v[158:161], v[182:185], v[36:39]
	v_mfma_f32_16x16x32_bf16 v[32:35], v[166:169], v[182:185], v[32:35]
	v_mfma_f32_16x16x32_bf16 v[20:23], v[158:161], v[204:207], v[20:23]
	v_mfma_f32_16x16x32_bf16 v[16:19], v[166:169], v[204:207], v[16:19]
	v_mfma_f32_16x16x32_bf16 v[4:7], v[158:161], v[212:215], v[4:7]
	v_mfma_f32_16x16x32_bf16 v[0:3], v[166:169], v[212:215], v[0:3]
	v_mfma_f32_16x16x32_bf16 v[52:55], v[162:165], v[178:181], v[52:55]
	v_mfma_f32_16x16x32_bf16 v[48:51], v[170:173], v[178:181], v[48:51]
	v_mfma_f32_16x16x32_bf16 v[36:39], v[162:165], v[186:189], v[36:39]
	v_mfma_f32_16x16x32_bf16 v[32:35], v[170:173], v[186:189], v[32:35]
	v_mfma_f32_16x16x32_bf16 v[20:23], v[162:165], v[208:211], v[20:23]
	v_mfma_f32_16x16x32_bf16 v[16:19], v[170:173], v[208:211], v[16:19]
	v_mfma_f32_16x16x32_bf16 v[4:7], v[162:165], v[216:219], v[4:7]
	v_mfma_f32_16x16x32_bf16 v[0:3], v[170:173], v[216:219], v[0:3]
	s_barrier
	s_setprio 0
	s_add_u32 s24, s24, 0x100
	s_addc_u32 s25, s25, 0
	s_add_u32 s33, s33, 0x100
	s_addc_u32 s48, s48, 0
	s_cmp_ge_i32 s49, s38
	s_mov_b32 s26, s49
	s_cbranch_scc0 .LBB0_464

; #define PG8_STAGE(bufoff, gbase, voff) do { _Pragma("unroll") for (int _i = 0; _i < 2; ++_i) \
;         __builtin_amdgcn_global_load_lds((const unsigned*)((const char*)(gbase) + (voff)[_i]), (PG8_LAS unsigned*)(lds + (bufoff) + ldsw + _i * 8192), 16, 0, 0); } while (0)
; #define PG8_LDA(dst, b, h) do { _Pragma("unroll") for (int m = 0; m < 4; ++m) _Pragma("unroll") for (int k = 0; k < 2; ++k) dst[m][k] = *(const PG8_LAS bf16x8*)(lds + PG8_SA(b, h) + aoff + m * 2048 + k * 1024); } while (0)
; #define PG8_LDB(dst, b, h) do { _Pragma("unroll") for (int n = 0; n < 2; ++n) _Pragma("unroll") for (int k = 0; k < 2; ++k) dst[n][k] = *(const PG8_LAS bf16x8*)(lds + PG8_SB(b, h) + boff + n * 2048 + k * 1024); } while (0)
; #define PG8_WAIT_V(n) asm volatile("s_waitcnt vmcnt(" #n ")" ::: "memory")
; #define PG8_WAIT_L(n) asm volatile("s_waitcnt lgkmcnt(" #n ")" ::: "memory")
; template <class Epi, class Sched, bool ALIGN_EPI = false, bool SP2 = false>
; __device__ __forceinline__ void gemm_phase(PG8_LAS unsigned char* lds, const Gemm g, const Sched& S, const Epi& E) {
;     ...
;             const char* a1 = cA + (size_t)(t + 1) * kstep;
;             const char* a2 = last ? nA : cA + (size_t)(t + 2) * kstep; const char* b2 = last ? nB : cB + (size_t)(t + 2) * kstep;
;             const char* a3 = a2 + kstep; const char* b3 = b2 + kstep;
;             if (last && has_next) S.a_ready(nxt);
;             if constexpr (SP2) {
;             PG8_LDB(B0, 0, 0); PG8_LDB(B1, 0, 1); PG8_SCHED; PG8_LDA(At, 0, 0); PG8_STAGE(PG8_SA(1, 1), a1 + hstepA, voffA);
;             if (plast) PG8_WAIT_V(10); else PG8_WAIT_SEL(defer, 12, 16);
;             PG8_WAIT_L(0); PG8_BAR; PG8_MMA(0, 0, At, B0); PG8_MMA(0, 1, At, B1);
;             if constexpr (Epi::SPLIT) { if (defer) {
;                 E.second(acc, prev, rv1, wr, wc, fr, fq);
;                 _Pragma("unroll") for (int b = 0; b < 2; ++b) _Pragma("unroll") for (int m = 0; m < 4; ++m) _Pragma("unroll") for (int n = 0; n < 2; ++n) acc[1][b][m][n] = (f32x4){0.f, 0.f, 0.f, 0.f}; } }
;             PG8_BAR; PG8_SCHED;
;             PG8_LDA(At, 0, 1); PG8_STAGE(PG8_SB(0, 0), b2, voffB); PG8_STAGE(PG8_SB(0, 1), b2 + hstep, voffB); PG8_STAGE(PG8_SA(0, 0), a2, voffA);
;             if (plast) PG8_WAIT_V(10); else PG8_WAIT_SEL(defer, 16, 24);
;             PG8_WAIT_L(0); PG8_BAR; PG8_MMA(1, 0, At, B0); PG8_MMA(1, 1, At, B1); PG8_BAR; PG8_SCHED;
.Lpk_dn_497:
	s_add_i32 s49, s26, 2
	s_add_u32 s50, s0, 0x80
	s_addc_u32 s27, s1, 0
	s_add_i32 s52, 0, 0x10000
	s_cmp_eq_u32 s43, s26
	s_cselect_b32 s27, s9, s27
	s_cselect_b32 s26, s8, s50
	s_cselect_b32 s51, s25, s48
	s_cselect_b32 s50, s24, s33
	s_add_i32 s53, 0, 0x14000
	v_add_u32_e32 v140, s52, v186
	v_add_u32_e32 v166, s53, v186
	ds_read_b128 v[128:131], v140
	ds_read_b128 v[132:135], v140 offset:1024
	ds_read_b128 v[136:139], v140 offset:2048
	ds_read_b128 v[140:143], v140 offset:3072
	ds_read_b128 v[144:147], v166
	ds_read_b128 v[148:151], v166 offset:1024
	ds_read_b128 v[152:155], v166 offset:2048
	ds_read_b128 v[166:169], v166 offset:3072
	v_lshl_add_u64 v[182:183], s[0:1], 0, v[162:163]
	s_add_i32 m0, s31, 0xc000
	ds_read_b128 v[170:173], v187
	ds_read_b128 v[174:177], v187 offset:1024
	ds_read_b128 v[178:181], v187 offset:2048
	ds_read_b128 v[188:191], v187 offset:3072
	ds_read_b128 v[204:207], v187 offset:4096
	ds_read_b128 v[208:211], v187 offset:5120
	ds_read_b128 v[212:215], v187 offset:6144
	ds_read_b128 v[216:219], v187 offset:7168
	global_load_lds_dwordx4 v[182:183], off
	v_lshl_add_u64 v[182:183], s[0:1], 0, v[164:165]
	s_add_i32 m0, s31, 0xe000
	s_nop 0
	global_load_lds_dwordx4 v[182:183], off
	s_waitcnt vmcnt(8)
	s_waitcnt lgkmcnt(0)
	s_setprio 1
	s_barrier
	v_mfma_f32_16x16x32_bf16 v[120:123], v[128:131], v[170:173], 0
	v_mfma_f32_16x16x32_bf16 v[124:127], v[136:139], v[170:173], 0
	v_mfma_f32_16x16x32_bf16 v[108:111], v[128:131], v[178:181], 0
	v_mfma_f32_16x16x32_bf16 v[104:107], v[136:139], v[178:181], 0
	v_mfma_f32_16x16x32_bf16 v[92:95], v[128:131], v[204:207], 0
	v_mfma_f32_16x16x32_bf16 v[88:91], v[136:139], v[204:207], 0
	v_mfma_f32_16x16x32_bf16 v[76:79], v[128:131], v[212:215], 0
	v_mfma_f32_16x16x32_bf16 v[72:75], v[136:139], v[212:215], 0
	v_mfma_f32_16x16x32_bf16 v[120:123], v[132:135], v[174:177], v[120:123]
	v_mfma_f32_16x16x32_bf16 v[124:127], v[140:143], v[174:177], v[124:127]
	v_mfma_f32_16x16x32_bf16 v[108:111], v[132:135], v[188:191], v[108:111]
	v_mfma_f32_16x16x32_bf16 v[104:107], v[140:143], v[188:191], v[104:107]
	v_mfma_f32_16x16x32_bf16 v[92:95], v[132:135], v[208:211], v[92:95]
	v_mfma_f32_16x16x32_bf16 v[88:91], v[140:143], v[208:211], v[88:91]
	v_mfma_f32_16x16x32_bf16 v[76:79], v[132:135], v[216:219], v[76:79]
	v_mfma_f32_16x16x32_bf16 v[72:75], v[140:143], v[216:219], v[72:75]
	s_setprio 0
	s_setprio 1
	v_mfma_f32_16x16x32_bf16 v[116:119], v[144:147], v[170:173], 0
	v_mfma_f32_16x16x32_bf16 v[112:115], v[152:155], v[170:173], 0
	v_mfma_f32_16x16x32_bf16 v[100:103], v[144:147], v[178:181], 0
	v_mfma_f32_16x16x32_bf16 v[96:99], v[152:155], v[178:181], 0
	v_mfma_f32_16x16x32_bf16 v[84:87], v[144:147], v[204:207], 0
	v_mfma_f32_16x16x32_bf16 v[80:83], v[152:155], v[204:207], 0
	v_mfma_f32_16x16x32_bf16 v[68:71], v[144:147], v[212:215], 0
	v_mfma_f32_16x16x32_bf16 v[64:67], v[152:155], v[212:215], 0
	v_mfma_f32_16x16x32_bf16 v[116:119], v[148:151], v[174:177], v[116:119]
	v_mfma_f32_16x16x32_bf16 v[112:115], v[166:169], v[174:177], v[112:115]
	v_mfma_f32_16x16x32_bf16 v[100:103], v[148:151], v[188:191], v[100:103]
	v_mfma_f32_16x16x32_bf16 v[96:99], v[166:169], v[188:191], v[96:99]
	v_mfma_f32_16x16x32_bf16 v[84:87], v[148:151], v[208:211], v[84:87]
	v_mfma_f32_16x16x32_bf16 v[80:83], v[166:169], v[208:211], v[80:83]
	v_mfma_f32_16x16x32_bf16 v[68:71], v[148:151], v[216:219], v[68:71]
	v_mfma_f32_16x16x32_bf16 v[64:67], v[166:169], v[216:219], v[64:67]
	s_barrier
	s_setprio 0
	s_add_i32 s52, s52, s30
	v_lshl_add_u64 v[182:183], s[50:51], 0, v[192:193]
	s_mov_b32 m0, s52
	ds_read_b128 v[170:173], v187 offset:16384
	ds_read_b128 v[174:177], v187 offset:17408
	ds_read_b128 v[178:181], v187 offset:18432
	ds_read_b128 v[188:191], v187 offset:19456
	ds_read_b128 v[204:207], v187 offset:20480
	ds_read_b128 v[208:211], v187 offset:21504
	ds_read_b128 v[212:215], v187 offset:22528
	ds_read_b128 v[216:219], v187 offset:23552
	global_load_lds_dwordx4 v[182:183], off
	s_add_i32 m0, s52, 0x2000
	v_lshl_add_u64 v[194:195], s[50:51], 0, v[156:157]
	s_add_u32 s50, s50, s14
	s_addc_u32 s51, s51, s15
	s_add_i32 s52, s53, s30
	global_load_lds_dwordx4 v[194:195], off
	v_lshl_add_u64 v[200:201], s[50:51], 0, v[192:193]
	s_mov_b32 m0, s52
	v_lshl_add_u64 v[202:203], s[50:51], 0, v[156:157]
	global_load_lds_dwordx4 v[200:201], off
	s_add_i32 m0, s52, 0x2000
	v_lshl_add_u64 v[220:221], s[26:27], 0, v[160:161]
	global_load_lds_dwordx4 v[202:203], off
	s_mov_b32 m0, s31
	v_lshl_add_u64 v[222:223], s[26:27], 0, v[158:159]
	global_load_lds_dwordx4 v[220:221], off
	s_mov_b32 m0, s34
	s_nop 0
	global_load_lds_dwordx4 v[222:223], off
	s_waitcnt vmcnt(8)
	s_waitcnt lgkmcnt(0)
	s_setprio 1
	s_barrier
; #define PG8_STAGE(bufoff, gbase, voff) do { _Pragma("unroll") for (int _i = 0; _i < 2; ++_i) \
;         __builtin_amdgcn_global_load_lds((const unsigned*)((const char*)(gbase) + (voff)[_i]), (PG8_LAS unsigned*)(lds + (bufoff) + ldsw + _i * 8192), 16, 0, 0); } while (0)
; #define PG8_LDA(dst, b, h) do { _Pragma("unroll") for (int m = 0; m < 4; ++m) _Pragma("unroll") for (int k = 0; k < 2; ++k) dst[m][k] = *(const PG8_LAS bf16x8*)(lds + PG8_SA(b, h) + aoff + m * 2048 + k * 1024); } while (0)
; #define PG8_LDB(dst, b, h) do { _Pragma("unroll") for (int n = 0; n < 2; ++n) _Pragma("unroll") for (int k = 0; k < 2; ++k) dst[n][k] = *(const PG8_LAS bf16x8*)(lds + PG8_SB(b, h) + boff + n * 2048 + k * 1024); } while (0)
; #define PG8_MMA(ai, bj, At, Bt) do { __builtin_amdgcn_s_setprio(1); _Pragma("unroll") for (int m = 0; m < 4; ++m) _Pragma("unroll") for (int n = 0; n < 2; ++n) _Pragma("unroll") for (int k = 0; k < 2; ++k) \
;         acc[ai][bj][m][n] = __builtin_amdgcn_mfma_f32_16x16x32_bf16(Bt[n][k], At[m][k], acc[ai][bj][m][n], 0, 0, 0); __builtin_amdgcn_s_setprio(0); } while (0)
; #define PG8_WAIT_SEL(d, w4, w8) do { if constexpr (Epi::SPLIT) { if (d) { if constexpr (Epi::NSH == 4) PG8_WAIT_V(w4); else PG8_WAIT_V(w8); } else PG8_WAIT_V(8); } else PG8_WAIT_V(8); } while (0)
; #define PG8_WAIT_L(n) asm volatile("s_waitcnt lgkmcnt(" #n ")" ::: "memory")
; #define PG8_BAR __builtin_amdgcn_s_barrier()
; #define PG8_SCHED __builtin_amdgcn_sched_barrier(0)
; template <class Epi, class Sched, bool ALIGN_EPI = false, bool SP2 = false>
; __device__ __forceinline__ void gemm_phase(PG8_LAS unsigned char* lds, const Gemm g, const Sched& S, const Epi& E) {
;     ...
;             PG8_WAIT_L(0); PG8_BAR; PG8_MMA(1, 0, At, B0); PG8_MMA(1, 1, At, B1); PG8_BAR; PG8_SCHED;
;             PG8_LDB(B0, 1, 0); PG8_LDB(B1, 1, 1); PG8_SCHED; PG8_LDA(At, 1, 0); PG8_STAGE(PG8_SA(0, 1), a2 + hstepA, voffA);
;             PG8_WAIT_SEL(defer, 12, 16); PG8_WAIT_L(0); PG8_BAR; PG8_MMA(0, 0, At, B0); PG8_MMA(0, 1, At, B1); PG8_BAR; PG8_SCHED;
	v_mfma_f32_16x16x32_bf16 v[60:63], v[128:131], v[170:173], 0
	v_mfma_f32_16x16x32_bf16 v[56:59], v[136:139], v[170:173], 0
	v_mfma_f32_16x16x32_bf16 v[44:47], v[128:131], v[178:181], 0
	v_mfma_f32_16x16x32_bf16 v[40:43], v[136:139], v[178:181], 0
	v_mfma_f32_16x16x32_bf16 v[28:31], v[128:131], v[204:207], 0
	v_mfma_f32_16x16x32_bf16 v[24:27], v[136:139], v[204:207], 0
	v_mfma_f32_16x16x32_bf16 v[12:15], v[128:131], v[212:215], 0
	v_mfma_f32_16x16x32_bf16 v[8:11], v[136:139], v[212:215], 0
	v_mfma_f32_16x16x32_bf16 v[60:63], v[132:135], v[174:177], v[60:63]
	v_mfma_f32_16x16x32_bf16 v[56:59], v[140:143], v[174:177], v[56:59]
	v_mfma_f32_16x16x32_bf16 v[44:47], v[132:135], v[188:191], v[44:47]
	v_mfma_f32_16x16x32_bf16 v[40:43], v[140:143], v[188:191], v[40:43]
	v_mfma_f32_16x16x32_bf16 v[28:31], v[132:135], v[208:211], v[28:31]
	v_mfma_f32_16x16x32_bf16 v[24:27], v[140:143], v[208:211], v[24:27]
	v_mfma_f32_16x16x32_bf16 v[12:15], v[132:135], v[216:219], v[12:15]
	v_mfma_f32_16x16x32_bf16 v[8:11], v[140:143], v[216:219], v[8:11]
	s_setprio 0
	s_setprio 1
	v_mfma_f32_16x16x32_bf16 v[52:55], v[144:147], v[170:173], 0
	v_mfma_f32_16x16x32_bf16 v[48:51], v[152:155], v[170:173], 0
	v_mfma_f32_16x16x32_bf16 v[36:39], v[144:147], v[178:181], 0
	v_mfma_f32_16x16x32_bf16 v[32:35], v[152:155], v[178:181], 0
	v_mfma_f32_16x16x32_bf16 v[20:23], v[144:147], v[204:207], 0
	v_mfma_f32_16x16x32_bf16 v[16:19], v[152:155], v[204:207], 0
	v_mfma_f32_16x16x32_bf16 v[4:7], v[144:147], v[212:215], 0
	v_mfma_f32_16x16x32_bf16 v[0:3], v[152:155], v[212:215], 0
	v_mfma_f32_16x16x32_bf16 v[52:55], v[148:151], v[174:177], v[52:55]
	v_mfma_f32_16x16x32_bf16 v[48:51], v[166:169], v[174:177], v[48:51]
	v_mfma_f32_16x16x32_bf16 v[36:39], v[148:151], v[188:191], v[36:39]
	v_mfma_f32_16x16x32_bf16 v[32:35], v[166:169], v[188:191], v[32:35]
	v_mfma_f32_16x16x32_bf16 v[20:23], v[148:151], v[208:211], v[20:23]
	v_mfma_f32_16x16x32_bf16 v[16:19], v[166:169], v[208:211], v[16:19]
	v_mfma_f32_16x16x32_bf16 v[4:7], v[148:151], v[216:219], v[4:7]
	v_mfma_f32_16x16x32_bf16 v[0:3], v[166:169], v[216:219], v[0:3]
	s_barrier
	s_setprio 0
	s_add_i32 s50, 0, 0x18000
	s_add_i32 s51, 0, 0x1c000
	v_add_u32_e32 v140, s50, v186
	v_add_u32_e32 v166, s51, v186
	ds_read_b128 v[128:131], v140
	ds_read_b128 v[132:135], v140 offset:1024
	ds_read_b128 v[136:139], v140 offset:2048
	ds_read_b128 v[140:143], v140 offset:3072
	ds_read_b128 v[144:147], v166
	ds_read_b128 v[148:151], v166 offset:1024
	ds_read_b128 v[152:155], v166 offset:2048
	ds_read_b128 v[166:169], v166 offset:3072
	s_add_u32 s26, s26, s10
	s_addc_u32 s27, s27, s11
	s_mov_b32 m0, s35
	v_lshl_add_u64 v[224:225], s[26:27], 0, v[160:161]
	ds_read_b128 v[170:173], v187 offset:32768
	ds_read_b128 v[174:177], v187 offset:33792
	ds_read_b128 v[178:181], v187 offset:34816
	ds_read_b128 v[188:191], v187 offset:35840
	ds_read_b128 v[204:207], v187 offset:36864
	ds_read_b128 v[208:211], v187 offset:37888
	ds_read_b128 v[212:215], v187 offset:38912
	ds_read_b128 v[216:219], v187 offset:39936
	global_load_lds_dwordx4 v[224:225], off
	v_lshl_add_u64 v[224:225], s[26:27], 0, v[158:159]
	s_mov_b32 m0, s36
	s_nop 0
	global_load_lds_dwordx4 v[224:225], off
	s_waitcnt vmcnt(8)
	s_waitcnt lgkmcnt(0)
	s_setprio 1
	s_barrier
	v_mfma_f32_16x16x32_bf16 v[120:123], v[128:131], v[170:173], v[120:123]
	v_mfma_f32_16x16x32_bf16 v[124:127], v[136:139], v[170:173], v[124:127]
	v_mfma_f32_16x16x32_bf16 v[108:111], v[128:131], v[178:181], v[108:111]
	v_mfma_f32_16x16x32_bf16 v[104:107], v[136:139], v[178:181], v[104:107]
	v_mfma_f32_16x16x32_bf16 v[92:95], v[128:131], v[204:207], v[92:95]
	v_mfma_f32_16x16x32_bf16 v[88:91], v[136:139], v[204:207], v[88:91]
	v_mfma_f32_16x16x32_bf16 v[76:79], v[128:131], v[212:215], v[76:79]
	v_mfma_f32_16x16x32_bf16 v[72:75], v[136:139], v[212:215], v[72:75]
	v_mfma_f32_16x16x32_bf16 v[120:123], v[132:135], v[174:177], v[120:123]
	v_mfma_f32_16x16x32_bf16 v[124:127], v[140:143], v[174:177], v[124:127]
	v_mfma_f32_16x16x32_bf16 v[108:111], v[132:135], v[188:191], v[108:111]
	v_mfma_f32_16x16x32_bf16 v[104:107], v[140:143], v[188:191], v[104:107]
	v_mfma_f32_16x16x32_bf16 v[92:95], v[132:135], v[208:211], v[92:95]
	v_mfma_f32_16x16x32_bf16 v[88:91], v[140:143], v[208:211], v[88:91]
	v_mfma_f32_16x16x32_bf16 v[76:79], v[132:135], v[216:219], v[76:79]
	v_mfma_f32_16x16x32_bf16 v[72:75], v[140:143], v[216:219], v[72:75]
	s_setprio 0
	s_setprio 1
	v_mfma_f32_16x16x32_bf16 v[116:119], v[144:147], v[170:173], v[116:119]
	v_mfma_f32_16x16x32_bf16 v[112:115], v[152:155], v[170:173], v[112:115]
	v_mfma_f32_16x16x32_bf16 v[100:103], v[144:147], v[178:181], v[100:103]
	v_mfma_f32_16x16x32_bf16 v[96:99], v[152:155], v[178:181], v[96:99]
	v_mfma_f32_16x16x32_bf16 v[84:87], v[144:147], v[204:207], v[84:87]
	v_mfma_f32_16x16x32_bf16 v[80:83], v[152:155], v[204:207], v[80:83]
	v_mfma_f32_16x16x32_bf16 v[68:71], v[144:147], v[212:215], v[68:71]
	v_mfma_f32_16x16x32_bf16 v[64:67], v[152:155], v[212:215], v[64:67]
	v_mfma_f32_16x16x32_bf16 v[116:119], v[148:151], v[174:177], v[116:119]
	v_mfma_f32_16x16x32_bf16 v[112:115], v[166:169], v[174:177], v[112:115]
	v_mfma_f32_16x16x32_bf16 v[100:103], v[148:151], v[188:191], v[100:103]
	v_mfma_f32_16x16x32_bf16 v[96:99], v[166:169], v[188:191], v[96:99]
	v_mfma_f32_16x16x32_bf16 v[84:87], v[148:151], v[208:211], v[84:87]
	v_mfma_f32_16x16x32_bf16 v[80:83], v[166:169], v[208:211], v[80:83]
	v_mfma_f32_16x16x32_bf16 v[68:71], v[148:151], v[216:219], v[68:71]
	v_mfma_f32_16x16x32_bf16 v[64:67], v[166:169], v[216:219], v[64:67]
	s_barrier
; #define PG8_STAGE(bufoff, gbase, voff) do { _Pragma("unroll") for (int _i = 0; _i < 2; ++_i) \
;         __builtin_amdgcn_global_load_lds((const unsigned*)((const char*)(gbase) + (voff)[_i]), (PG8_LAS unsigned*)(lds + (bufoff) + ldsw + _i * 8192), 16, 0, 0); } while (0)
; #define PG8_LDA(dst, b, h) do { _Pragma("unroll") for (int m = 0; m < 4; ++m) _Pragma("unroll") for (int k = 0; k < 2; ++k) dst[m][k] = *(const PG8_LAS bf16x8*)(lds + PG8_SA(b, h) + aoff + m * 2048 + k * 1024); } while (0)
; #define PG8_LDB(dst, b, h) do { _Pragma("unroll") for (int n = 0; n < 2; ++n) _Pragma("unroll") for (int k = 0; k < 2; ++k) dst[n][k] = *(const PG8_LAS bf16x8*)(lds + PG8_SB(b, h) + boff + n * 2048 + k * 1024); } while (0)
; #define PG8_MMA(ai, bj, At, Bt) do { __builtin_amdgcn_s_setprio(1); _Pragma("unroll") for (int m = 0; m < 4; ++m) _Pragma("unroll") for (int n = 0; n < 2; ++n) _Pragma("unroll") for (int k = 0; k < 2; ++k) \
;         acc[ai][bj][m][n] = __builtin_amdgcn_mfma_f32_16x16x32_bf16(Bt[n][k], At[m][k], acc[ai][bj][m][n], 0, 0, 0); __builtin_amdgcn_s_setprio(0); } while (0)
; #define PG8_WAIT_V(n) asm volatile("s_waitcnt vmcnt(" #n ")" ::: "memory")
; #define PG8_WAIT_L(n) asm volatile("s_waitcnt lgkmcnt(" #n ")" ::: "memory")
; template <class Epi, class Sched, bool ALIGN_EPI = false, bool SP2 = false>
; __device__ __forceinline__ void gemm_phase(PG8_LAS unsigned char* lds, const Gemm g, const Sched& S, const Epi& E) {
;     ...
;             const char* a1 = cA + (size_t)(t + 1) * kstep;
;             const char* a2 = last ? nA : cA + (size_t)(t + 2) * kstep; const char* b2 = last ? nB : cB + (size_t)(t + 2) * kstep;
;             const char* a3 = a2 + kstep; const char* b3 = b2 + kstep;
;             if (last && has_next) S.a_ready(nxt);
;             if constexpr (SP2) {
;             PG8_LDB(B0, 0, 0); PG8_LDB(B1, 0, 1); PG8_SCHED; PG8_LDA(At, 0, 0); PG8_STAGE(PG8_SA(1, 1), a1 + hstepA, voffA);
;             if (plast) PG8_WAIT_V(10); else PG8_WAIT_SEL(defer, 12, 16);
;             PG8_WAIT_L(0); PG8_BAR; PG8_MMA(0, 0, At, B0); PG8_MMA(0, 1, At, B1);
;     ...
;             PG8_LDA(At, 1, 1); PG8_STAGE(PG8_SB(1, 0), b3, voffB); PG8_STAGE(PG8_SB(1, 1), b3 + hstep, voffB); PG8_STAGE(PG8_SA(1, 0), a3, voffA);
;             PG8_WAIT_V(8); PG8_WAIT_L(0); PG8_BAR; PG8_MMA(1, 0, At, B0); PG8_MMA(1, 1, At, B1); PG8_BAR; PG8_SCHED;
	s_setprio 0
	s_add_i32 s26, s50, s30
	v_lshl_add_u64 v[182:183], v[182:183], 0, s[90:91]
	s_mov_b32 m0, s26
	ds_read_b128 v[170:173], v187 offset:49152
	ds_read_b128 v[174:177], v187 offset:50176
	ds_read_b128 v[178:181], v187 offset:51200
	ds_read_b128 v[188:191], v187 offset:52224
	ds_read_b128 v[204:207], v187 offset:53248
	ds_read_b128 v[208:211], v187 offset:54272
	ds_read_b128 v[212:215], v187 offset:55296
	ds_read_b128 v[216:219], v187 offset:56320
	global_load_lds_dwordx4 v[182:183], off
	v_lshl_add_u64 v[182:183], v[194:195], 0, s[90:91]
	s_add_i32 m0, s26, 0x2000
	s_add_i32 s26, s51, s30
	global_load_lds_dwordx4 v[182:183], off
	v_lshl_add_u64 v[182:183], v[200:201], 0, s[90:91]
	s_mov_b32 m0, s26
	s_nop 0
	global_load_lds_dwordx4 v[182:183], off
	v_lshl_add_u64 v[182:183], v[202:203], 0, s[90:91]
	s_add_i32 m0, s26, 0x2000
	s_nop 0
	global_load_lds_dwordx4 v[182:183], off
	v_lshl_add_u64 v[182:183], v[220:221], 0, s[90:91]
	s_mov_b32 m0, s41
	s_nop 0
	global_load_lds_dwordx4 v[182:183], off
	v_lshl_add_u64 v[182:183], v[222:223], 0, s[90:91]
	s_mov_b32 m0, s42
	s_nop 0
	global_load_lds_dwordx4 v[182:183], off
	s_waitcnt vmcnt(8)
	s_waitcnt lgkmcnt(0)
	s_setprio 1
	s_barrier
	v_mfma_f32_16x16x32_bf16 v[60:63], v[128:131], v[170:173], v[60:63]
	v_mfma_f32_16x16x32_bf16 v[56:59], v[136:139], v[170:173], v[56:59]
	v_mfma_f32_16x16x32_bf16 v[44:47], v[128:131], v[178:181], v[44:47]
	v_mfma_f32_16x16x32_bf16 v[40:43], v[136:139], v[178:181], v[40:43]
	v_mfma_f32_16x16x32_bf16 v[28:31], v[128:131], v[204:207], v[28:31]
	v_mfma_f32_16x16x32_bf16 v[24:27], v[136:139], v[204:207], v[24:27]
	v_mfma_f32_16x16x32_bf16 v[12:15], v[128:131], v[212:215], v[12:15]
	v_mfma_f32_16x16x32_bf16 v[8:11], v[136:139], v[212:215], v[8:11]
	v_mfma_f32_16x16x32_bf16 v[60:63], v[132:135], v[174:177], v[60:63]
	v_mfma_f32_16x16x32_bf16 v[56:59], v[140:143], v[174:177], v[56:59]
	v_mfma_f32_16x16x32_bf16 v[44:47], v[132:135], v[188:191], v[44:47]
	v_mfma_f32_16x16x32_bf16 v[40:43], v[140:143], v[188:191], v[40:43]
	v_mfma_f32_16x16x32_bf16 v[28:31], v[132:135], v[208:211], v[28:31]
	v_mfma_f32_16x16x32_bf16 v[24:27], v[140:143], v[208:211], v[24:27]
	v_mfma_f32_16x16x32_bf16 v[12:15], v[132:135], v[216:219], v[12:15]
	v_mfma_f32_16x16x32_bf16 v[8:11], v[140:143], v[216:219], v[8:11]
	s_setprio 0
	s_setprio 1
	v_mfma_f32_16x16x32_bf16 v[52:55], v[144:147], v[170:173], v[52:55]
	v_mfma_f32_16x16x32_bf16 v[48:51], v[152:155], v[170:173], v[48:51]
	v_mfma_f32_16x16x32_bf16 v[36:39], v[144:147], v[178:181], v[36:39]
	v_mfma_f32_16x16x32_bf16 v[32:35], v[152:155], v[178:181], v[32:35]
	v_mfma_f32_16x16x32_bf16 v[20:23], v[144:147], v[204:207], v[20:23]
	v_mfma_f32_16x16x32_bf16 v[16:19], v[152:155], v[204:207], v[16:19]
	v_mfma_f32_16x16x32_bf16 v[4:7], v[144:147], v[212:215], v[4:7]
	v_mfma_f32_16x16x32_bf16 v[0:3], v[152:155], v[212:215], v[0:3]
	v_mfma_f32_16x16x32_bf16 v[52:55], v[148:151], v[174:177], v[52:55]
	v_mfma_f32_16x16x32_bf16 v[48:51], v[166:169], v[174:177], v[48:51]
	v_mfma_f32_16x16x32_bf16 v[36:39], v[148:151], v[188:191], v[36:39]
	v_mfma_f32_16x16x32_bf16 v[32:35], v[166:169], v[188:191], v[32:35]
	v_mfma_f32_16x16x32_bf16 v[20:23], v[148:151], v[208:211], v[20:23]
	v_mfma_f32_16x16x32_bf16 v[16:19], v[166:169], v[208:211], v[16:19]
	v_mfma_f32_16x16x32_bf16 v[4:7], v[148:151], v[216:219], v[4:7]
	v_mfma_f32_16x16x32_bf16 v[0:3], v[166:169], v[216:219], v[0:3]
	s_barrier
	s_setprio 0
	s_add_u32 s0, s0, 0x100
	s_addc_u32 s1, s1, 0
	s_add_u32 s33, s33, 0x100
	s_addc_u32 s48, s48, 0
	s_cmp_ge_i32 s49, s38
	s_mov_b32 s26, s49
	s_cbranch_scc0 .LBB0_497
	s_branch .LBB0_498
.LBB0_497:
	s_add_i32 s49, s26, 2
	s_add_u32 s50, s0, 0x80
	s_addc_u32 s27, s1, 0
	s_add_i32 s52, 0, 0x10000
	s_cmp_eq_u32 s43, s26
	s_cselect_b32 s27, s9, s27
	s_cselect_b32 s26, s8, s50
	s_cselect_b32 s51, s25, s48
	s_cselect_b32 s50, s24, s33
	s_add_i32 s53, 0, 0x14000
	v_add_u32_e32 v140, s52, v186
	v_add_u32_e32 v166, s53, v186
	ds_read_b128 v[128:131], v140
	ds_read_b128 v[132:135], v140 offset:1024
	ds_read_b128 v[136:139], v140 offset:2048
	ds_read_b128 v[140:143], v140 offset:3072
	ds_read_b128 v[144:147], v166
	ds_read_b128 v[148:151], v166 offset:1024
	ds_read_b128 v[152:155], v166 offset:2048
	ds_read_b128 v[166:169], v166 offset:3072
	v_lshl_add_u64 v[182:183], s[0:1], 0, v[162:163]
	s_add_i32 m0, s31, 0xc000
	ds_read_b128 v[170:173], v187
	ds_read_b128 v[174:177], v187 offset:1024
	ds_read_b128 v[178:181], v187 offset:2048
	ds_read_b128 v[188:191], v187 offset:3072
	ds_read_b128 v[204:207], v187 offset:4096
	ds_read_b128 v[208:211], v187 offset:5120
	ds_read_b128 v[212:215], v187 offset:6144
	ds_read_b128 v[216:219], v187 offset:7168
	global_load_lds_dwordx4 v[182:183], off
	v_lshl_add_u64 v[182:183], s[0:1], 0, v[164:165]
	s_add_i32 m0, s31, 0xe000
	s_nop 0
	global_load_lds_dwordx4 v[182:183], off
	s_waitcnt vmcnt(8)
	s_waitcnt lgkmcnt(0)
	s_setprio 1
	s_barrier
; #define PG8_STAGE(bufoff, gbase, voff) do { _Pragma("unroll") for (int _i = 0; _i < 2; ++_i) \
;         __builtin_amdgcn_global_load_lds((const unsigned*)((const char*)(gbase) + (voff)[_i]), (PG8_LAS unsigned*)(lds + (bufoff) + ldsw + _i * 8192), 16, 0, 0); } while (0)
; #define PG8_LDA(dst, b, h) do { _Pragma("unroll") for (int m = 0; m < 4; ++m) _Pragma("unroll") for (int k = 0; k < 2; ++k) dst[m][k] = *(const PG8_LAS bf16x8*)(lds + PG8_SA(b, h) + aoff + m * 2048 + k * 1024); } while (0)
; #define PG8_MMA(ai, bj, At, Bt) do { __builtin_amdgcn_s_setprio(1); _Pragma("unroll") for (int m = 0; m < 4; ++m) _Pragma("unroll") for (int n = 0; n < 2; ++n) _Pragma("unroll") for (int k = 0; k < 2; ++k) \
;         acc[ai][bj][m][n] = __builtin_amdgcn_mfma_f32_16x16x32_bf16(Bt[n][k], At[m][k], acc[ai][bj][m][n], 0, 0, 0); __builtin_amdgcn_s_setprio(0); } while (0)
; #define PG8_WAIT_V(n) asm volatile("s_waitcnt vmcnt(" #n ")" ::: "memory")
; #define PG8_WAIT_SEL(d, w4, w8) do { if constexpr (Epi::SPLIT) { if (d) { if constexpr (Epi::NSH == 4) PG8_WAIT_V(w4); else PG8_WAIT_V(w8); } else PG8_WAIT_V(8); } else PG8_WAIT_V(8); } while (0)
; #define PG8_WAIT_L(n) asm volatile("s_waitcnt lgkmcnt(" #n ")" ::: "memory")
; #define PG8_BAR __builtin_amdgcn_s_barrier()
; #define PG8_SCHED __builtin_amdgcn_sched_barrier(0)
; template <class Epi, class Sched, bool ALIGN_EPI = false, bool SP2 = false>
; __device__ __forceinline__ void gemm_phase(PG8_LAS unsigned char* lds, const Gemm g, const Sched& S, const Epi& E) {
;     ...
;             PG8_WAIT_L(0); PG8_BAR; PG8_MMA(0, 0, At, B0); PG8_MMA(0, 1, At, B1);
;             if constexpr (Epi::SPLIT) { if (defer) {
;                 E.second(acc, prev, rv1, wr, wc, fr, fq);
;                 _Pragma("unroll") for (int b = 0; b < 2; ++b) _Pragma("unroll") for (int m = 0; m < 4; ++m) _Pragma("unroll") for (int n = 0; n < 2; ++n) acc[1][b][m][n] = (f32x4){0.f, 0.f, 0.f, 0.f}; } }
;             PG8_BAR; PG8_SCHED;
;             PG8_LDA(At, 0, 1); PG8_STAGE(PG8_SB(0, 0), b2, voffB); PG8_STAGE(PG8_SB(0, 1), b2 + hstep, voffB); PG8_STAGE(PG8_SA(0, 0), a2, voffA);
;             if (plast) PG8_WAIT_V(10); else PG8_WAIT_SEL(defer, 16, 24);
;             PG8_WAIT_L(0); PG8_BAR; PG8_MMA(1, 0, At, B0); PG8_MMA(1, 1, At, B1); PG8_BAR; PG8_SCHED;
	v_mfma_f32_16x16x32_bf16 v[120:123], v[128:131], v[170:173], v[120:123]
	v_mfma_f32_16x16x32_bf16 v[124:127], v[136:139], v[170:173], v[124:127]
	v_mfma_f32_16x16x32_bf16 v[108:111], v[128:131], v[178:181], v[108:111]
	v_mfma_f32_16x16x32_bf16 v[104:107], v[136:139], v[178:181], v[104:107]
	v_mfma_f32_16x16x32_bf16 v[92:95], v[128:131], v[204:207], v[92:95]
	v_mfma_f32_16x16x32_bf16 v[88:91], v[136:139], v[204:207], v[88:91]
	v_mfma_f32_16x16x32_bf16 v[76:79], v[128:131], v[212:215], v[76:79]
	v_mfma_f32_16x16x32_bf16 v[72:75], v[136:139], v[212:215], v[72:75]
	v_mfma_f32_16x16x32_bf16 v[120:123], v[132:135], v[174:177], v[120:123]
	v_mfma_f32_16x16x32_bf16 v[124:127], v[140:143], v[174:177], v[124:127]
	v_mfma_f32_16x16x32_bf16 v[108:111], v[132:135], v[188:191], v[108:111]
	v_mfma_f32_16x16x32_bf16 v[104:107], v[140:143], v[188:191], v[104:107]
	v_mfma_f32_16x16x32_bf16 v[92:95], v[132:135], v[208:211], v[92:95]
	v_mfma_f32_16x16x32_bf16 v[88:91], v[140:143], v[208:211], v[88:91]
	v_mfma_f32_16x16x32_bf16 v[76:79], v[132:135], v[216:219], v[76:79]
	v_mfma_f32_16x16x32_bf16 v[72:75], v[140:143], v[216:219], v[72:75]
	s_setprio 0
	s_setprio 1
	v_mfma_f32_16x16x32_bf16 v[116:119], v[144:147], v[170:173], v[116:119]
	v_mfma_f32_16x16x32_bf16 v[112:115], v[152:155], v[170:173], v[112:115]
	v_mfma_f32_16x16x32_bf16 v[100:103], v[144:147], v[178:181], v[100:103]
	v_mfma_f32_16x16x32_bf16 v[96:99], v[152:155], v[178:181], v[96:99]
	v_mfma_f32_16x16x32_bf16 v[84:87], v[144:147], v[204:207], v[84:87]
	v_mfma_f32_16x16x32_bf16 v[80:83], v[152:155], v[204:207], v[80:83]
	v_mfma_f32_16x16x32_bf16 v[68:71], v[144:147], v[212:215], v[68:71]
	v_mfma_f32_16x16x32_bf16 v[64:67], v[152:155], v[212:215], v[64:67]
	v_mfma_f32_16x16x32_bf16 v[116:119], v[148:151], v[174:177], v[116:119]
	v_mfma_f32_16x16x32_bf16 v[112:115], v[166:169], v[174:177], v[112:115]
	v_mfma_f32_16x16x32_bf16 v[100:103], v[148:151], v[188:191], v[100:103]
	v_mfma_f32_16x16x32_bf16 v[96:99], v[166:169], v[188:191], v[96:99]
	v_mfma_f32_16x16x32_bf16 v[84:87], v[148:151], v[208:211], v[84:87]
	v_mfma_f32_16x16x32_bf16 v[80:83], v[166:169], v[208:211], v[80:83]
	v_mfma_f32_16x16x32_bf16 v[68:71], v[148:151], v[216:219], v[68:71]
	v_mfma_f32_16x16x32_bf16 v[64:67], v[166:169], v[216:219], v[64:67]
	s_barrier
	s_setprio 0
	s_add_i32 s52, s52, s30
	v_lshl_add_u64 v[182:183], s[50:51], 0, v[192:193]
	s_mov_b32 m0, s52
	ds_read_b128 v[170:173], v187 offset:16384
	ds_read_b128 v[174:177], v187 offset:17408
	ds_read_b128 v[178:181], v187 offset:18432
	ds_read_b128 v[188:191], v187 offset:19456
	ds_read_b128 v[204:207], v187 offset:20480
	ds_read_b128 v[208:211], v187 offset:21504
	ds_read_b128 v[212:215], v187 offset:22528
	ds_read_b128 v[216:219], v187 offset:23552
	global_load_lds_dwordx4 v[182:183], off
	s_add_i32 m0, s52, 0x2000
	v_lshl_add_u64 v[194:195], s[50:51], 0, v[156:157]
	s_add_u32 s50, s50, s14
	s_addc_u32 s51, s51, s15
	s_add_i32 s52, s53, s30
	global_load_lds_dwordx4 v[194:195], off
	v_lshl_add_u64 v[200:201], s[50:51], 0, v[192:193]
	s_mov_b32 m0, s52
	v_lshl_add_u64 v[202:203], s[50:51], 0, v[156:157]
	global_load_lds_dwordx4 v[200:201], off
	s_add_i32 m0, s52, 0x2000
	v_lshl_add_u64 v[220:221], s[26:27], 0, v[160:161]
	global_load_lds_dwordx4 v[202:203], off
	s_mov_b32 m0, s31
	v_lshl_add_u64 v[222:223], s[26:27], 0, v[158:159]
	global_load_lds_dwordx4 v[220:221], off
	s_mov_b32 m0, s34
	s_nop 0
	global_load_lds_dwordx4 v[222:223], off
	s_waitcnt vmcnt(8)
	s_waitcnt lgkmcnt(0)
	s_setprio 1
	s_barrier
	v_mfma_f32_16x16x32_bf16 v[60:63], v[128:131], v[170:173], v[60:63]
	v_mfma_f32_16x16x32_bf16 v[56:59], v[136:139], v[170:173], v[56:59]
	v_mfma_f32_16x16x32_bf16 v[44:47], v[128:131], v[178:181], v[44:47]
	v_mfma_f32_16x16x32_bf16 v[40:43], v[136:139], v[178:181], v[40:43]
	v_mfma_f32_16x16x32_bf16 v[28:31], v[128:131], v[204:207], v[28:31]
	v_mfma_f32_16x16x32_bf16 v[24:27], v[136:139], v[204:207], v[24:27]
	v_mfma_f32_16x16x32_bf16 v[12:15], v[128:131], v[212:215], v[12:15]
	v_mfma_f32_16x16x32_bf16 v[8:11], v[136:139], v[212:215], v[8:11]
	v_mfma_f32_16x16x32_bf16 v[60:63], v[132:135], v[174:177], v[60:63]
	v_mfma_f32_16x16x32_bf16 v[56:59], v[140:143], v[174:177], v[56:59]
	v_mfma_f32_16x16x32_bf16 v[44:47], v[132:135], v[188:191], v[44:47]
	v_mfma_f32_16x16x32_bf16 v[40:43], v[140:143], v[188:191], v[40:43]
	v_mfma_f32_16x16x32_bf16 v[28:31], v[132:135], v[208:211], v[28:31]
	v_mfma_f32_16x16x32_bf16 v[24:27], v[140:143], v[208:211], v[24:27]
	v_mfma_f32_16x16x32_bf16 v[12:15], v[132:135], v[216:219], v[12:15]
	v_mfma_f32_16x16x32_bf16 v[8:11], v[140:143], v[216:219], v[8:11]
	s_setprio 0
	s_setprio 1
	v_mfma_f32_16x16x32_bf16 v[52:55], v[144:147], v[170:173], v[52:55]
	v_mfma_f32_16x16x32_bf16 v[48:51], v[152:155], v[170:173], v[48:51]
	v_mfma_f32_16x16x32_bf16 v[36:39], v[144:147], v[178:181], v[36:39]
	v_mfma_f32_16x16x32_bf16 v[32:35], v[152:155], v[178:181], v[32:35]
	v_mfma_f32_16x16x32_bf16 v[20:23], v[144:147], v[204:207], v[20:23]
	v_mfma_f32_16x16x32_bf16 v[16:19], v[152:155], v[204:207], v[16:19]
	v_mfma_f32_16x16x32_bf16 v[4:7], v[144:147], v[212:215], v[4:7]
	v_mfma_f32_16x16x32_bf16 v[0:3], v[152:155], v[212:215], v[0:3]
	v_mfma_f32_16x16x32_bf16 v[52:55], v[148:151], v[174:177], v[52:55]
	v_mfma_f32_16x16x32_bf16 v[48:51], v[166:169], v[174:177], v[48:51]
	v_mfma_f32_16x16x32_bf16 v[36:39], v[148:151], v[188:191], v[36:39]
	v_mfma_f32_16x16x32_bf16 v[32:35], v[166:169], v[188:191], v[32:35]
	v_mfma_f32_16x16x32_bf16 v[20:23], v[148:151], v[208:211], v[20:23]
	v_mfma_f32_16x16x32_bf16 v[16:19], v[166:169], v[208:211], v[16:19]
	v_mfma_f32_16x16x32_bf16 v[4:7], v[148:151], v[216:219], v[4:7]
	v_mfma_f32_16x16x32_bf16 v[0:3], v[166:169], v[216:219], v[0:3]
	s_barrier
; #define PG8_STAGE(bufoff, gbase, voff) do { _Pragma("unroll") for (int _i = 0; _i < 2; ++_i) \
;         __builtin_amdgcn_global_load_lds((const unsigned*)((const char*)(gbase) + (voff)[_i]), (PG8_LAS unsigned*)(lds + (bufoff) + ldsw + _i * 8192), 16, 0, 0); } while (0)
; #define PG8_LDA(dst, b, h) do { _Pragma("unroll") for (int m = 0; m < 4; ++m) _Pragma("unroll") for (int k = 0; k < 2; ++k) dst[m][k] = *(const PG8_LAS bf16x8*)(lds + PG8_SA(b, h) + aoff + m * 2048 + k * 1024); } while (0)
; #define PG8_LDB(dst, b, h) do { _Pragma("unroll") for (int n = 0; n < 2; ++n) _Pragma("unroll") for (int k = 0; k < 2; ++k) dst[n][k] = *(const PG8_LAS bf16x8*)(lds + PG8_SB(b, h) + boff + n * 2048 + k * 1024); } while (0)
; #define PG8_MMA(ai, bj, At, Bt) do { __builtin_amdgcn_s_setprio(1); _Pragma("unroll") for (int m = 0; m < 4; ++m) _Pragma("unroll") for (int n = 0; n < 2; ++n) _Pragma("unroll") for (int k = 0; k < 2; ++k) \
;         acc[ai][bj][m][n] = __builtin_amdgcn_mfma_f32_16x16x32_bf16(Bt[n][k], At[m][k], acc[ai][bj][m][n], 0, 0, 0); __builtin_amdgcn_s_setprio(0); } while (0)
; #define PG8_WAIT_SEL(d, w4, w8) do { if constexpr (Epi::SPLIT) { if (d) { if constexpr (Epi::NSH == 4) PG8_WAIT_V(w4); else PG8_WAIT_V(w8); } else PG8_WAIT_V(8); } else PG8_WAIT_V(8); } while (0)
; #define PG8_WAIT_L(n) asm volatile("s_waitcnt lgkmcnt(" #n ")" ::: "memory")
; #define PG8_BAR __builtin_amdgcn_s_barrier()
; #define PG8_SCHED __builtin_amdgcn_sched_barrier(0)
; template <class Epi, class Sched, bool ALIGN_EPI = false, bool SP2 = false>
; __device__ __forceinline__ void gemm_phase(PG8_LAS unsigned char* lds, const Gemm g, const Sched& S, const Epi& E) {
;     ...
;             PG8_LDB(B0, 1, 0); PG8_LDB(B1, 1, 1); PG8_SCHED; PG8_LDA(At, 1, 0); PG8_STAGE(PG8_SA(0, 1), a2 + hstepA, voffA);
;             PG8_WAIT_SEL(defer, 12, 16); PG8_WAIT_L(0); PG8_BAR; PG8_MMA(0, 0, At, B0); PG8_MMA(0, 1, At, B1); PG8_BAR; PG8_SCHED;
	s_setprio 0
	s_add_i32 s50, 0, 0x18000
	s_add_i32 s51, 0, 0x1c000
	v_add_u32_e32 v140, s50, v186
	v_add_u32_e32 v166, s51, v186
	ds_read_b128 v[128:131], v140
	ds_read_b128 v[132:135], v140 offset:1024
	ds_read_b128 v[136:139], v140 offset:2048
	ds_read_b128 v[140:143], v140 offset:3072
	ds_read_b128 v[144:147], v166
	ds_read_b128 v[148:151], v166 offset:1024
	ds_read_b128 v[152:155], v166 offset:2048
	ds_read_b128 v[166:169], v166 offset:3072
	s_add_u32 s26, s26, s10
	s_addc_u32 s27, s27, s11
	s_mov_b32 m0, s35
	v_lshl_add_u64 v[224:225], s[26:27], 0, v[160:161]
	ds_read_b128 v[170:173], v187 offset:32768
	ds_read_b128 v[174:177], v187 offset:33792
	ds_read_b128 v[178:181], v187 offset:34816
	ds_read_b128 v[188:191], v187 offset:35840
	ds_read_b128 v[204:207], v187 offset:36864
	ds_read_b128 v[208:211], v187 offset:37888
	ds_read_b128 v[212:215], v187 offset:38912
	ds_read_b128 v[216:219], v187 offset:39936
	global_load_lds_dwordx4 v[224:225], off
	v_lshl_add_u64 v[224:225], s[26:27], 0, v[158:159]
	s_mov_b32 m0, s36
	s_nop 0
	global_load_lds_dwordx4 v[224:225], off
	s_waitcnt vmcnt(8)
	s_waitcnt lgkmcnt(0)
	s_setprio 1
	s_barrier
	v_mfma_f32_16x16x32_bf16 v[120:123], v[128:131], v[170:173], v[120:123]
	v_mfma_f32_16x16x32_bf16 v[124:127], v[136:139], v[170:173], v[124:127]
	v_mfma_f32_16x16x32_bf16 v[108:111], v[128:131], v[178:181], v[108:111]
	v_mfma_f32_16x16x32_bf16 v[104:107], v[136:139], v[178:181], v[104:107]
	v_mfma_f32_16x16x32_bf16 v[92:95], v[128:131], v[204:207], v[92:95]
	v_mfma_f32_16x16x32_bf16 v[88:91], v[136:139], v[204:207], v[88:91]
	v_mfma_f32_16x16x32_bf16 v[76:79], v[128:131], v[212:215], v[76:79]
	v_mfma_f32_16x16x32_bf16 v[72:75], v[136:139], v[212:215], v[72:75]
	v_mfma_f32_16x16x32_bf16 v[120:123], v[132:135], v[174:177], v[120:123]
	v_mfma_f32_16x16x32_bf16 v[124:127], v[140:143], v[174:177], v[124:127]
	v_mfma_f32_16x16x32_bf16 v[108:111], v[132:135], v[188:191], v[108:111]
	v_mfma_f32_16x16x32_bf16 v[104:107], v[140:143], v[188:191], v[104:107]
	v_mfma_f32_16x16x32_bf16 v[92:95], v[132:135], v[208:211], v[92:95]
	v_mfma_f32_16x16x32_bf16 v[88:91], v[140:143], v[208:211], v[88:91]
	v_mfma_f32_16x16x32_bf16 v[76:79], v[132:135], v[216:219], v[76:79]
	v_mfma_f32_16x16x32_bf16 v[72:75], v[140:143], v[216:219], v[72:75]
	s_setprio 0
	s_setprio 1
	v_mfma_f32_16x16x32_bf16 v[116:119], v[144:147], v[170:173], v[116:119]
	v_mfma_f32_16x16x32_bf16 v[112:115], v[152:155], v[170:173], v[112:115]
	v_mfma_f32_16x16x32_bf16 v[100:103], v[144:147], v[178:181], v[100:103]
	v_mfma_f32_16x16x32_bf16 v[96:99], v[152:155], v[178:181], v[96:99]
	v_mfma_f32_16x16x32_bf16 v[84:87], v[144:147], v[204:207], v[84:87]
	v_mfma_f32_16x16x32_bf16 v[80:83], v[152:155], v[204:207], v[80:83]
	v_mfma_f32_16x16x32_bf16 v[68:71], v[144:147], v[212:215], v[68:71]
	v_mfma_f32_16x16x32_bf16 v[64:67], v[152:155], v[212:215], v[64:67]
	v_mfma_f32_16x16x32_bf16 v[116:119], v[148:151], v[174:177], v[116:119]
	v_mfma_f32_16x16x32_bf16 v[112:115], v[166:169], v[174:177], v[112:115]
	v_mfma_f32_16x16x32_bf16 v[100:103], v[148:151], v[188:191], v[100:103]
	v_mfma_f32_16x16x32_bf16 v[96:99], v[166:169], v[188:191], v[96:99]
	v_mfma_f32_16x16x32_bf16 v[84:87], v[148:151], v[208:211], v[84:87]
	v_mfma_f32_16x16x32_bf16 v[80:83], v[166:169], v[208:211], v[80:83]
	v_mfma_f32_16x16x32_bf16 v[68:71], v[148:151], v[216:219], v[68:71]
	v_mfma_f32_16x16x32_bf16 v[64:67], v[166:169], v[216:219], v[64:67]
	s_barrier
; #define PG8_STAGE(bufoff, gbase, voff) do { _Pragma("unroll") for (int _i = 0; _i < 2; ++_i) \
;         __builtin_amdgcn_global_load_lds((const unsigned*)((const char*)(gbase) + (voff)[_i]), (PG8_LAS unsigned*)(lds + (bufoff) + ldsw + _i * 8192), 16, 0, 0); } while (0)
; #define PG8_LDA(dst, b, h) do { _Pragma("unroll") for (int m = 0; m < 4; ++m) _Pragma("unroll") for (int k = 0; k < 2; ++k) dst[m][k] = *(const PG8_LAS bf16x8*)(lds + PG8_SA(b, h) + aoff + m * 2048 + k * 1024); } while (0)
; #define PG8_MMA(ai, bj, At, Bt) do { __builtin_amdgcn_s_setprio(1); _Pragma("unroll") for (int m = 0; m < 4; ++m) _Pragma("unroll") for (int n = 0; n < 2; ++n) _Pragma("unroll") for (int k = 0; k < 2; ++k) \
;         acc[ai][bj][m][n] = __builtin_amdgcn_mfma_f32_16x16x32_bf16(Bt[n][k], At[m][k], acc[ai][bj][m][n], 0, 0, 0); __builtin_amdgcn_s_setprio(0); } while (0)
; #define PG8_WAIT_V(n) asm volatile("s_waitcnt vmcnt(" #n ")" ::: "memory")
; #define PG8_WAIT_L(n) asm volatile("s_waitcnt lgkmcnt(" #n ")" ::: "memory")
; #define PG8_BAR __builtin_amdgcn_s_barrier()
; #define PG8_SCHED __builtin_amdgcn_sched_barrier(0)
; template <class Epi, class Sched, bool ALIGN_EPI = false, bool SP2 = false>
; __device__ __forceinline__ void gemm_phase(PG8_LAS unsigned char* lds, const Gemm g, const Sched& S, const Epi& E) {
;     ...
;             PG8_LDA(At, 1, 1); PG8_STAGE(PG8_SB(1, 0), b3, voffB); PG8_STAGE(PG8_SB(1, 1), b3 + hstep, voffB); PG8_STAGE(PG8_SA(1, 0), a3, voffA);
;             PG8_WAIT_V(8); PG8_WAIT_L(0); PG8_BAR; PG8_MMA(1, 0, At, B0); PG8_MMA(1, 1, At, B1); PG8_BAR; PG8_SCHED;
	s_setprio 0
	s_add_i32 s26, s50, s30
	v_lshl_add_u64 v[182:183], v[182:183], 0, s[90:91]
	s_mov_b32 m0, s26
	ds_read_b128 v[170:173], v187 offset:49152
	ds_read_b128 v[174:177], v187 offset:50176
	ds_read_b128 v[178:181], v187 offset:51200
	ds_read_b128 v[188:191], v187 offset:52224
	ds_read_b128 v[204:207], v187 offset:53248
	ds_read_b128 v[208:211], v187 offset:54272
	ds_read_b128 v[212:215], v187 offset:55296
	ds_read_b128 v[216:219], v187 offset:56320
	global_load_lds_dwordx4 v[182:183], off
	v_lshl_add_u64 v[182:183], v[194:195], 0, s[90:91]
	s_add_i32 m0, s26, 0x2000
	s_add_i32 s26, s51, s30
	global_load_lds_dwordx4 v[182:183], off
	v_lshl_add_u64 v[182:183], v[200:201], 0, s[90:91]
	s_mov_b32 m0, s26
	s_nop 0
	global_load_lds_dwordx4 v[182:183], off
	v_lshl_add_u64 v[182:183], v[202:203], 0, s[90:91]
	s_add_i32 m0, s26, 0x2000
	s_nop 0
	global_load_lds_dwordx4 v[182:183], off
	v_lshl_add_u64 v[182:183], v[220:221], 0, s[90:91]
	s_mov_b32 m0, s41
	s_nop 0
	global_load_lds_dwordx4 v[182:183], off
	v_lshl_add_u64 v[182:183], v[222:223], 0, s[90:91]
	s_mov_b32 m0, s42
	s_nop 0
	global_load_lds_dwordx4 v[182:183], off
	s_waitcnt vmcnt(8)
	s_waitcnt lgkmcnt(0)
	s_setprio 1
	s_barrier
	v_mfma_f32_16x16x32_bf16 v[60:63], v[128:131], v[170:173], v[60:63]
	v_mfma_f32_16x16x32_bf16 v[56:59], v[136:139], v[170:173], v[56:59]
	v_mfma_f32_16x16x32_bf16 v[44:47], v[128:131], v[178:181], v[44:47]
	v_mfma_f32_16x16x32_bf16 v[40:43], v[136:139], v[178:181], v[40:43]
	v_mfma_f32_16x16x32_bf16 v[28:31], v[128:131], v[204:207], v[28:31]
	v_mfma_f32_16x16x32_bf16 v[24:27], v[136:139], v[204:207], v[24:27]
	v_mfma_f32_16x16x32_bf16 v[12:15], v[128:131], v[212:215], v[12:15]
	v_mfma_f32_16x16x32_bf16 v[8:11], v[136:139], v[212:215], v[8:11]
	v_mfma_f32_16x16x32_bf16 v[60:63], v[132:135], v[174:177], v[60:63]
	v_mfma_f32_16x16x32_bf16 v[56:59], v[140:143], v[174:177], v[56:59]
	v_mfma_f32_16x16x32_bf16 v[44:47], v[132:135], v[188:191], v[44:47]
	v_mfma_f32_16x16x32_bf16 v[40:43], v[140:143], v[188:191], v[40:43]
	v_mfma_f32_16x16x32_bf16 v[28:31], v[132:135], v[208:211], v[28:31]
	v_mfma_f32_16x16x32_bf16 v[24:27], v[140:143], v[208:211], v[24:27]
	v_mfma_f32_16x16x32_bf16 v[12:15], v[132:135], v[216:219], v[12:15]
	v_mfma_f32_16x16x32_bf16 v[8:11], v[140:143], v[216:219], v[8:11]
	s_setprio 0
	s_setprio 1
	v_mfma_f32_16x16x32_bf16 v[52:55], v[144:147], v[170:173], v[52:55]
	v_mfma_f32_16x16x32_bf16 v[48:51], v[152:155], v[170:173], v[48:51]
	v_mfma_f32_16x16x32_bf16 v[36:39], v[144:147], v[178:181], v[36:39]
	v_mfma_f32_16x16x32_bf16 v[32:35], v[152:155], v[178:181], v[32:35]
	v_mfma_f32_16x16x32_bf16 v[20:23], v[144:147], v[204:207], v[20:23]
	v_mfma_f32_16x16x32_bf16 v[16:19], v[152:155], v[204:207], v[16:19]
	v_mfma_f32_16x16x32_bf16 v[4:7], v[144:147], v[212:215], v[4:7]
	v_mfma_f32_16x16x32_bf16 v[0:3], v[152:155], v[212:215], v[0:3]
	v_mfma_f32_16x16x32_bf16 v[52:55], v[148:151], v[174:177], v[52:55]
	v_mfma_f32_16x16x32_bf16 v[48:51], v[166:169], v[174:177], v[48:51]
	v_mfma_f32_16x16x32_bf16 v[36:39], v[148:151], v[188:191], v[36:39]
	v_mfma_f32_16x16x32_bf16 v[32:35], v[166:169], v[188:191], v[32:35]
	v_mfma_f32_16x16x32_bf16 v[20:23], v[148:151], v[208:211], v[20:23]
	v_mfma_f32_16x16x32_bf16 v[16:19], v[166:169], v[208:211], v[16:19]
	v_mfma_f32_16x16x32_bf16 v[4:7], v[148:151], v[216:219], v[4:7]
	v_mfma_f32_16x16x32_bf16 v[0:3], v[166:169], v[216:219], v[0:3]
	s_barrier
	s_setprio 0
	s_add_u32 s0, s0, 0x100
	s_addc_u32 s1, s1, 0
	s_add_u32 s33, s33, 0x100
	s_addc_u32 s48, s48, 0
	s_cmp_ge_i32 s49, s38
	s_mov_b32 s26, s49
	s_cbranch_scc0 .LBB0_497

; #define PG8_STAGE(bufoff, gbase, voff) do { _Pragma("unroll") for (int _i = 0; _i < 2; ++_i) \
;         __builtin_amdgcn_global_load_lds((const unsigned*)((const char*)(gbase) + (voff)[_i]), (PG8_LAS unsigned*)(lds + (bufoff) + ldsw + _i * 8192), 16, 0, 0); } while (0)
; #define PG8_LDA(dst, b, h) do { _Pragma("unroll") for (int m = 0; m < 4; ++m) _Pragma("unroll") for (int k = 0; k < 2; ++k) dst[m][k] = *(const PG8_LAS bf16x8*)(lds + PG8_SA(b, h) + aoff + m * 2048 + k * 1024); } while (0)
; #define PG8_LDB(dst, b, h) do { _Pragma("unroll") for (int n = 0; n < 2; ++n) _Pragma("unroll") for (int k = 0; k < 2; ++k) dst[n][k] = *(const PG8_LAS bf16x8*)(lds + PG8_SB(b, h) + boff + n * 2048 + k * 1024); } while (0)
; #define PG8_WAIT_V(n) asm volatile("s_waitcnt vmcnt(" #n ")" ::: "memory")
; #define PG8_WAIT_SEL(d, w4, w8) do { if constexpr (Epi::SPLIT) { if (d) { if constexpr (Epi::NSH == 4) PG8_WAIT_V(w4); else PG8_WAIT_V(w8); } else PG8_WAIT_V(8); } else PG8_WAIT_V(8); } while (0)
; #define PG8_BAR __builtin_amdgcn_s_barrier()
; template <class Epi, class Sched, bool ALIGN_EPI = false, bool SP2 = false>
; __device__ __forceinline__ void gemm_phase(PG8_LAS unsigned char* lds, const Gemm g, const Sched& S, const Epi& E) {
;     ...
;             const char* a2 = last ? nA : cA + (size_t)(t + 2) * kstep; const char* b2 = last ? nB : cB + (size_t)(t + 2) * kstep;
;             const char* a3 = a2 + kstep; const char* b3 = b2 + kstep;
;             if (last && has_next) S.a_ready(nxt);
;             if constexpr (SP2) {
;             PG8_LDB(B0, 0, 0); PG8_LDB(B1, 0, 1); PG8_SCHED; PG8_LDA(At, 0, 0); PG8_STAGE(PG8_SA(1, 1), a1 + hstepA, voffA);
;             if (plast) PG8_WAIT_V(10); else PG8_WAIT_SEL(defer, 12, 16);
;             PG8_WAIT_L(0); PG8_BAR; PG8_MMA(0, 0, At, B0); PG8_MMA(0, 1, At, B1);
;             if constexpr (Epi::SPLIT) { if (defer) {
;                 E.second(acc, prev, rv1, wr, wc, fr, fq);
;                 _Pragma("unroll") for (int b = 0; b < 2; ++b) _Pragma("unroll") for (int m = 0; m < 4; ++m) _Pragma("unroll") for (int n = 0; n < 2; ++n) acc[1][b][m][n] = (f32x4){0.f, 0.f, 0.f, 0.f}; } }
;             PG8_BAR; PG8_SCHED;
;             PG8_LDA(At, 0, 1); PG8_STAGE(PG8_SB(0, 0), b2, voffB); PG8_STAGE(PG8_SB(0, 1), b2 + hstep, voffB); PG8_STAGE(PG8_SA(0, 0), a2, voffA);
;             if (plast) PG8_WAIT_V(10); else PG8_WAIT_SEL(defer, 16, 24);
.Lpk_pg_567:
	s_add_u32 s36, s28, 0x80
	s_addc_u32 s37, s29, 0
	s_waitcnt lgkmcnt(0)
	s_and_b64 s[30:31], s[30:31], exec
	s_cselect_b32 s31, s7, s37
	s_cselect_b32 s30, s6, s36
	s_cselect_b32 s37, s27, s33
	s_cselect_b32 s36, s26, s1
	s_setprio 1
	s_barrier
	v_mfma_f32_16x16x32_bf16 v[124:127], v[144:147], v[184:187], 0
	v_mfma_f32_16x16x32_bf16 v[120:123], v[152:155], v[184:187], 0
	v_mfma_f32_16x16x32_bf16 v[108:111], v[144:147], v[176:179], 0
	v_mfma_f32_16x16x32_bf16 v[104:107], v[152:155], v[176:179], 0
	v_mfma_f32_16x16x32_bf16 v[92:95], v[144:147], v[168:171], 0
	v_mfma_f32_16x16x32_bf16 v[88:91], v[152:155], v[168:171], 0
	v_mfma_f32_16x16x32_bf16 v[76:79], v[144:147], v[160:163], 0
	v_mfma_f32_16x16x32_bf16 v[72:75], v[152:155], v[160:163], 0
	v_mfma_f32_16x16x32_bf16 v[124:127], v[148:151], v[188:191], v[124:127]
	v_mfma_f32_16x16x32_bf16 v[120:123], v[156:159], v[188:191], v[120:123]
	v_mfma_f32_16x16x32_bf16 v[108:111], v[148:151], v[180:183], v[108:111]
	v_mfma_f32_16x16x32_bf16 v[104:107], v[156:159], v[180:183], v[104:107]
	v_mfma_f32_16x16x32_bf16 v[92:95], v[148:151], v[172:175], v[92:95]
	v_mfma_f32_16x16x32_bf16 v[88:91], v[156:159], v[172:175], v[88:91]
	v_mfma_f32_16x16x32_bf16 v[76:79], v[148:151], v[164:167], v[76:79]
	v_mfma_f32_16x16x32_bf16 v[72:75], v[156:159], v[164:167], v[72:75]
	s_setprio 0
	s_setprio 1
	v_mfma_f32_16x16x32_bf16 v[116:119], v[128:131], v[184:187], 0
	v_mfma_f32_16x16x32_bf16 v[112:115], v[136:139], v[184:187], 0
	v_mfma_f32_16x16x32_bf16 v[100:103], v[128:131], v[176:179], 0
	v_mfma_f32_16x16x32_bf16 v[96:99], v[136:139], v[176:179], 0
	v_mfma_f32_16x16x32_bf16 v[84:87], v[128:131], v[168:171], 0
	v_mfma_f32_16x16x32_bf16 v[80:83], v[136:139], v[168:171], 0
	v_mfma_f32_16x16x32_bf16 v[68:71], v[128:131], v[160:163], 0
	v_mfma_f32_16x16x32_bf16 v[64:67], v[136:139], v[160:163], 0
	v_mfma_f32_16x16x32_bf16 v[116:119], v[132:135], v[188:191], v[116:119]
	v_mfma_f32_16x16x32_bf16 v[112:115], v[140:143], v[188:191], v[112:115]
	v_mfma_f32_16x16x32_bf16 v[100:103], v[132:135], v[180:183], v[100:103]
	v_mfma_f32_16x16x32_bf16 v[96:99], v[140:143], v[180:183], v[96:99]
	v_mfma_f32_16x16x32_bf16 v[84:87], v[132:135], v[172:175], v[84:87]
	v_mfma_f32_16x16x32_bf16 v[80:83], v[140:143], v[172:175], v[80:83]
	v_mfma_f32_16x16x32_bf16 v[68:71], v[132:135], v[164:167], v[68:71]
	v_mfma_f32_16x16x32_bf16 v[64:67], v[140:143], v[164:167], v[64:67]
	s_barrier
	s_setprio 0
	s_mov_b32 m0, s42
	v_lshl_add_u64 v[222:223], s[36:37], 0, v[192:193]
	v_lshl_add_u64 v[220:221], s[36:37], 0, v[204:205]
	s_add_u32 s36, s36, s12
	ds_read_b128 v[184:187], v240 offset:16384
	ds_read_b128 v[188:191], v240 offset:17408
	ds_read_b128 v[176:179], v240 offset:18432
	ds_read_b128 v[180:183], v240 offset:19456
	ds_read_b128 v[168:171], v240 offset:20480
	ds_read_b128 v[172:175], v240 offset:21504
	ds_read_b128 v[160:163], v240 offset:22528
	ds_read_b128 v[164:167], v240 offset:23552
	global_load_lds_dwordx4 v[222:223], off
	s_mov_b32 m0, s43
	s_addc_u32 s37, s37, s13
	global_load_lds_dwordx4 v[220:221], off
	v_lshl_add_u64 v[230:231], s[36:37], 0, v[192:193]
	s_mov_b32 m0, s44
	v_lshl_add_u64 v[228:229], s[36:37], 0, v[204:205]
	global_load_lds_dwordx4 v[230:231], off
	s_mov_b32 m0, s45
	v_lshl_add_u64 v[224:225], s[30:31], 0, v[208:209]
	global_load_lds_dwordx4 v[228:229], off
	s_mov_b32 m0, s41
	v_lshl_add_u64 v[226:227], s[30:31], 0, v[206:207]
	global_load_lds_dwordx4 v[224:225], off
	s_mov_b32 m0, s46
	s_mov_b64 s[36:37], -1
	global_load_lds_dwordx4 v[226:227], off
	s_and_b64 vcc, exec, s[34:35]
	s_cbranch_vccz .Lpk_pg_569
	s_waitcnt vmcnt(8)
	s_mov_b64 s[36:37], 0

; #define PG8_STAGE(bufoff, gbase, voff) do { _Pragma("unroll") for (int _i = 0; _i < 2; ++_i) \
;         __builtin_amdgcn_global_load_lds((const unsigned*)((const char*)(gbase) + (voff)[_i]), (PG8_LAS unsigned*)(lds + (bufoff) + ldsw + _i * 8192), 16, 0, 0); } while (0)
; #define PG8_LDA(dst, b, h) do { _Pragma("unroll") for (int m = 0; m < 4; ++m) _Pragma("unroll") for (int k = 0; k < 2; ++k) dst[m][k] = *(const PG8_LAS bf16x8*)(lds + PG8_SA(b, h) + aoff + m * 2048 + k * 1024); } while (0)
; #define PG8_LDB(dst, b, h) do { _Pragma("unroll") for (int n = 0; n < 2; ++n) _Pragma("unroll") for (int k = 0; k < 2; ++k) dst[n][k] = *(const PG8_LAS bf16x8*)(lds + PG8_SB(b, h) + boff + n * 2048 + k * 1024); } while (0)
; #define PG8_MMA(ai, bj, At, Bt) do { __builtin_amdgcn_s_setprio(1); _Pragma("unroll") for (int m = 0; m < 4; ++m) _Pragma("unroll") for (int n = 0; n < 2; ++n) _Pragma("unroll") for (int k = 0; k < 2; ++k) \
;         acc[ai][bj][m][n] = __builtin_amdgcn_mfma_f32_16x16x32_bf16(Bt[n][k], At[m][k], acc[ai][bj][m][n], 0, 0, 0); __builtin_amdgcn_s_setprio(0); } while (0)
; #define PG8_WAIT_SEL(d, w4, w8) do { if constexpr (Epi::SPLIT) { if (d) { if constexpr (Epi::NSH == 4) PG8_WAIT_V(w4); else PG8_WAIT_V(w8); } else PG8_WAIT_V(8); } else PG8_WAIT_V(8); } while (0)
; #define PG8_WAIT_L(n) asm volatile("s_waitcnt lgkmcnt(" #n ")" ::: "memory")
; #define PG8_BAR __builtin_amdgcn_s_barrier()
; #define PG8_SCHED __builtin_amdgcn_sched_barrier(0)
; template <class Epi, class Sched, bool ALIGN_EPI = false, bool SP2 = false>
; __device__ __forceinline__ void gemm_phase(PG8_LAS unsigned char* lds, const Gemm g, const Sched& S, const Epi& E) {
;     ...
;             PG8_WAIT_L(0); PG8_BAR; PG8_MMA(1, 0, At, B0); PG8_MMA(1, 1, At, B1); PG8_BAR; PG8_SCHED;
;             PG8_LDB(B0, 1, 0); PG8_LDB(B1, 1, 1); PG8_SCHED; PG8_LDA(At, 1, 0); PG8_STAGE(PG8_SA(0, 1), a2 + hstepA, voffA);
;             PG8_WAIT_SEL(defer, 12, 16); PG8_WAIT_L(0); PG8_BAR; PG8_MMA(0, 0, At, B0); PG8_MMA(0, 1, At, B1); PG8_BAR; PG8_SCHED;
.Lpk_pg_560:
	s_waitcnt lgkmcnt(0)
	s_add_i32 s59, s59, 2
	s_setprio 1
	s_barrier
	v_mfma_f32_16x16x32_bf16 v[60:63], v[144:147], v[184:187], 0
	v_mfma_f32_16x16x32_bf16 v[56:59], v[152:155], v[184:187], 0
	v_mfma_f32_16x16x32_bf16 v[44:47], v[144:147], v[176:179], 0
	v_mfma_f32_16x16x32_bf16 v[40:43], v[152:155], v[176:179], 0
	v_mfma_f32_16x16x32_bf16 v[28:31], v[144:147], v[168:171], 0
	v_mfma_f32_16x16x32_bf16 v[24:27], v[152:155], v[168:171], 0
	v_mfma_f32_16x16x32_bf16 v[12:15], v[144:147], v[160:163], 0
	v_mfma_f32_16x16x32_bf16 v[8:11], v[152:155], v[160:163], 0
	v_mfma_f32_16x16x32_bf16 v[60:63], v[148:151], v[188:191], v[60:63]
	v_mfma_f32_16x16x32_bf16 v[56:59], v[156:159], v[188:191], v[56:59]
	v_mfma_f32_16x16x32_bf16 v[44:47], v[148:151], v[180:183], v[44:47]
	v_mfma_f32_16x16x32_bf16 v[40:43], v[156:159], v[180:183], v[40:43]
	v_mfma_f32_16x16x32_bf16 v[28:31], v[148:151], v[172:175], v[28:31]
	v_mfma_f32_16x16x32_bf16 v[24:27], v[156:159], v[172:175], v[24:27]
	v_mfma_f32_16x16x32_bf16 v[12:15], v[148:151], v[164:167], v[12:15]
	v_mfma_f32_16x16x32_bf16 v[8:11], v[156:159], v[164:167], v[8:11]
	s_setprio 0
	s_setprio 1
	v_mfma_f32_16x16x32_bf16 v[52:55], v[128:131], v[184:187], 0
	v_mfma_f32_16x16x32_bf16 v[48:51], v[136:139], v[184:187], 0
	v_mfma_f32_16x16x32_bf16 v[36:39], v[128:131], v[176:179], 0
	v_mfma_f32_16x16x32_bf16 v[32:35], v[136:139], v[176:179], 0
	v_mfma_f32_16x16x32_bf16 v[20:23], v[128:131], v[168:171], 0
	v_mfma_f32_16x16x32_bf16 v[16:19], v[136:139], v[168:171], 0
	v_mfma_f32_16x16x32_bf16 v[4:7], v[128:131], v[160:163], 0
	v_mfma_f32_16x16x32_bf16 v[0:3], v[136:139], v[160:163], 0
	v_mfma_f32_16x16x32_bf16 v[52:55], v[132:135], v[188:191], v[52:55]
	v_mfma_f32_16x16x32_bf16 v[48:51], v[140:143], v[188:191], v[48:51]
	v_mfma_f32_16x16x32_bf16 v[36:39], v[132:135], v[180:183], v[36:39]
	v_mfma_f32_16x16x32_bf16 v[32:35], v[140:143], v[180:183], v[32:35]
	v_mfma_f32_16x16x32_bf16 v[20:23], v[132:135], v[172:175], v[20:23]
	v_mfma_f32_16x16x32_bf16 v[16:19], v[140:143], v[172:175], v[16:19]
	v_mfma_f32_16x16x32_bf16 v[4:7], v[132:135], v[164:167], v[4:7]
	v_mfma_f32_16x16x32_bf16 v[0:3], v[140:143], v[164:167], v[0:3]
	s_barrier
	s_setprio 0
	s_add_i32 s34, 0, 0x18000
	s_add_i32 s35, 0, 0x1c000
	v_add_u32_e32 v140, s34, v239
	v_add_u32_e32 v156, s35, v239
	ds_read_b128 v[128:131], v140
	ds_read_b128 v[132:135], v140 offset:1024
	ds_read_b128 v[136:139], v140 offset:2048
	ds_read_b128 v[140:143], v140 offset:3072
	ds_read_b128 v[144:147], v156
	ds_read_b128 v[148:151], v156 offset:1024
	ds_read_b128 v[152:155], v156 offset:2048
	ds_read_b128 v[156:159], v156 offset:3072
	s_add_u32 s30, s30, s8
	s_addc_u32 s31, s31, s9
	s_mov_b32 m0, s47
	v_lshl_add_u64 v[194:195], s[30:31], 0, v[208:209]
	ds_read_b128 v[160:163], v240 offset:32768
	ds_read_b128 v[164:167], v240 offset:33792
	ds_read_b128 v[168:171], v240 offset:34816
	ds_read_b128 v[172:175], v240 offset:35840
	ds_read_b128 v[176:179], v240 offset:36864
	ds_read_b128 v[180:183], v240 offset:37888
	ds_read_b128 v[184:187], v240 offset:38912
	ds_read_b128 v[188:191], v240 offset:39936
	global_load_lds_dwordx4 v[194:195], off
	v_lshl_add_u64 v[194:195], s[30:31], 0, v[206:207]
	s_mov_b32 m0, s48
	s_nop 0
	global_load_lds_dwordx4 v[194:195], off
	s_waitcnt vmcnt(8)
	s_waitcnt lgkmcnt(0)
	s_setprio 1
	s_barrier
	v_mfma_f32_16x16x32_bf16 v[124:127], v[128:131], v[160:163], v[124:127]
	v_mfma_f32_16x16x32_bf16 v[120:123], v[136:139], v[160:163], v[120:123]
	v_mfma_f32_16x16x32_bf16 v[108:111], v[128:131], v[168:171], v[108:111]
	v_mfma_f32_16x16x32_bf16 v[104:107], v[136:139], v[168:171], v[104:107]
	v_mfma_f32_16x16x32_bf16 v[92:95], v[128:131], v[176:179], v[92:95]
	v_mfma_f32_16x16x32_bf16 v[88:91], v[136:139], v[176:179], v[88:91]
	v_mfma_f32_16x16x32_bf16 v[76:79], v[128:131], v[184:187], v[76:79]
	v_mfma_f32_16x16x32_bf16 v[72:75], v[136:139], v[184:187], v[72:75]
	v_mfma_f32_16x16x32_bf16 v[124:127], v[132:135], v[164:167], v[124:127]
	v_mfma_f32_16x16x32_bf16 v[120:123], v[140:143], v[164:167], v[120:123]
	v_mfma_f32_16x16x32_bf16 v[108:111], v[132:135], v[172:175], v[108:111]
	v_mfma_f32_16x16x32_bf16 v[104:107], v[140:143], v[172:175], v[104:107]
	v_mfma_f32_16x16x32_bf16 v[92:95], v[132:135], v[180:183], v[92:95]
	v_mfma_f32_16x16x32_bf16 v[88:91], v[140:143], v[180:183], v[88:91]
	v_mfma_f32_16x16x32_bf16 v[76:79], v[132:135], v[188:191], v[76:79]
	v_mfma_f32_16x16x32_bf16 v[72:75], v[140:143], v[188:191], v[72:75]
	s_setprio 0
	s_setprio 1
	v_mfma_f32_16x16x32_bf16 v[116:119], v[144:147], v[160:163], v[116:119]
	v_mfma_f32_16x16x32_bf16 v[112:115], v[152:155], v[160:163], v[112:115]
	v_mfma_f32_16x16x32_bf16 v[100:103], v[144:147], v[168:171], v[100:103]
	v_mfma_f32_16x16x32_bf16 v[96:99], v[152:155], v[168:171], v[96:99]
	v_mfma_f32_16x16x32_bf16 v[84:87], v[144:147], v[176:179], v[84:87]
	v_mfma_f32_16x16x32_bf16 v[80:83], v[152:155], v[176:179], v[80:83]
	v_mfma_f32_16x16x32_bf16 v[68:71], v[144:147], v[184:187], v[68:71]
	v_mfma_f32_16x16x32_bf16 v[64:67], v[152:155], v[184:187], v[64:67]
	v_mfma_f32_16x16x32_bf16 v[116:119], v[148:151], v[164:167], v[116:119]
	v_mfma_f32_16x16x32_bf16 v[112:115], v[156:159], v[164:167], v[112:115]
	v_mfma_f32_16x16x32_bf16 v[100:103], v[148:151], v[172:175], v[100:103]
	v_mfma_f32_16x16x32_bf16 v[96:99], v[156:159], v[172:175], v[96:99]
	v_mfma_f32_16x16x32_bf16 v[84:87], v[148:151], v[180:183], v[84:87]
	v_mfma_f32_16x16x32_bf16 v[80:83], v[156:159], v[180:183], v[80:83]
	v_mfma_f32_16x16x32_bf16 v[68:71], v[148:151], v[188:191], v[68:71]
	v_mfma_f32_16x16x32_bf16 v[64:67], v[156:159], v[188:191], v[64:67]
	s_barrier
; #define PG8_STAGE(bufoff, gbase, voff) do { _Pragma("unroll") for (int _i = 0; _i < 2; ++_i) \
;         __builtin_amdgcn_global_load_lds((const unsigned*)((const char*)(gbase) + (voff)[_i]), (PG8_LAS unsigned*)(lds + (bufoff) + ldsw + _i * 8192), 16, 0, 0); } while (0)
; #define PG8_LDA(dst, b, h) do { _Pragma("unroll") for (int m = 0; m < 4; ++m) _Pragma("unroll") for (int k = 0; k < 2; ++k) dst[m][k] = *(const PG8_LAS bf16x8*)(lds + PG8_SA(b, h) + aoff + m * 2048 + k * 1024); } while (0)
; #define PG8_MMA(ai, bj, At, Bt) do { __builtin_amdgcn_s_setprio(1); _Pragma("unroll") for (int m = 0; m < 4; ++m) _Pragma("unroll") for (int n = 0; n < 2; ++n) _Pragma("unroll") for (int k = 0; k < 2; ++k) \
;         acc[ai][bj][m][n] = __builtin_amdgcn_mfma_f32_16x16x32_bf16(Bt[n][k], At[m][k], acc[ai][bj][m][n], 0, 0, 0); __builtin_amdgcn_s_setprio(0); } while (0)
; #define PG8_WAIT_V(n) asm volatile("s_waitcnt vmcnt(" #n ")" ::: "memory")
; #define PG8_WAIT_L(n) asm volatile("s_waitcnt lgkmcnt(" #n ")" ::: "memory")
; #define PG8_BAR __builtin_amdgcn_s_barrier()
; #define PG8_SCHED __builtin_amdgcn_sched_barrier(0)
; template <class Epi, class Sched, bool ALIGN_EPI = false, bool SP2 = false>
; __device__ __forceinline__ void gemm_phase(PG8_LAS unsigned char* lds, const Gemm g, const Sched& S, const Epi& E) {
;     ...
;             PG8_WAIT_L(0); PG8_BAR; PG8_MMA(1, 0, At, B0); PG8_MMA(1, 1, At, B1); PG8_BAR; PG8_SCHED;
;     ...
;             PG8_LDA(At, 1, 1); PG8_STAGE(PG8_SB(1, 0), b3, voffB); PG8_STAGE(PG8_SB(1, 1), b3 + hstep, voffB); PG8_STAGE(PG8_SA(1, 0), a3, voffA);
;             PG8_WAIT_V(8); PG8_WAIT_L(0); PG8_BAR; PG8_MMA(1, 0, At, B0); PG8_MMA(1, 1, At, B1); PG8_BAR; PG8_SCHED;
	s_setprio 0
	s_add_i32 s30, s34, s40
	v_lshl_add_u64 v[194:195], v[222:223], 0, s[90:91]
	s_mov_b32 m0, s30
	ds_read_b128 v[160:163], v240 offset:49152
	ds_read_b128 v[164:167], v240 offset:50176
	ds_read_b128 v[168:171], v240 offset:51200
	ds_read_b128 v[172:175], v240 offset:52224
	ds_read_b128 v[176:179], v240 offset:53248
	ds_read_b128 v[180:183], v240 offset:54272
	ds_read_b128 v[184:187], v240 offset:55296
	ds_read_b128 v[188:191], v240 offset:56320
	global_load_lds_dwordx4 v[194:195], off
	v_lshl_add_u64 v[194:195], v[220:221], 0, s[90:91]
	s_add_i32 m0, s30, 0x2000
	s_add_i32 s30, s35, s40
	global_load_lds_dwordx4 v[194:195], off
	v_lshl_add_u64 v[194:195], v[230:231], 0, s[90:91]
	s_mov_b32 m0, s30
	s_nop 0
	global_load_lds_dwordx4 v[194:195], off
	v_lshl_add_u64 v[194:195], v[228:229], 0, s[90:91]
	s_add_i32 m0, s30, 0x2000
	s_nop 0
	global_load_lds_dwordx4 v[194:195], off
	v_lshl_add_u64 v[194:195], v[224:225], 0, s[90:91]
	s_mov_b32 m0, s53
	s_nop 0
	global_load_lds_dwordx4 v[194:195], off
	v_lshl_add_u64 v[194:195], v[226:227], 0, s[90:91]
	s_mov_b32 m0, s54
	s_nop 0
	global_load_lds_dwordx4 v[194:195], off
	s_waitcnt vmcnt(8)
	s_waitcnt lgkmcnt(0)
	s_setprio 1
	s_barrier
	v_mfma_f32_16x16x32_bf16 v[60:63], v[128:131], v[160:163], v[60:63]
	v_mfma_f32_16x16x32_bf16 v[56:59], v[136:139], v[160:163], v[56:59]
	v_mfma_f32_16x16x32_bf16 v[44:47], v[128:131], v[168:171], v[44:47]
	v_mfma_f32_16x16x32_bf16 v[40:43], v[136:139], v[168:171], v[40:43]
	v_mfma_f32_16x16x32_bf16 v[28:31], v[128:131], v[176:179], v[28:31]
	v_mfma_f32_16x16x32_bf16 v[24:27], v[136:139], v[176:179], v[24:27]
	v_mfma_f32_16x16x32_bf16 v[12:15], v[128:131], v[184:187], v[12:15]
	v_mfma_f32_16x16x32_bf16 v[8:11], v[136:139], v[184:187], v[8:11]
	v_mfma_f32_16x16x32_bf16 v[60:63], v[132:135], v[164:167], v[60:63]
	v_mfma_f32_16x16x32_bf16 v[56:59], v[140:143], v[164:167], v[56:59]
	v_mfma_f32_16x16x32_bf16 v[44:47], v[132:135], v[172:175], v[44:47]
	v_mfma_f32_16x16x32_bf16 v[40:43], v[140:143], v[172:175], v[40:43]
	v_mfma_f32_16x16x32_bf16 v[28:31], v[132:135], v[180:183], v[28:31]
	v_mfma_f32_16x16x32_bf16 v[24:27], v[140:143], v[180:183], v[24:27]
	v_mfma_f32_16x16x32_bf16 v[12:15], v[132:135], v[188:191], v[12:15]
	v_mfma_f32_16x16x32_bf16 v[8:11], v[140:143], v[188:191], v[8:11]
	s_setprio 0
	s_setprio 1
	v_mfma_f32_16x16x32_bf16 v[52:55], v[144:147], v[160:163], v[52:55]
	v_mfma_f32_16x16x32_bf16 v[48:51], v[152:155], v[160:163], v[48:51]
	v_mfma_f32_16x16x32_bf16 v[36:39], v[144:147], v[168:171], v[36:39]
	v_mfma_f32_16x16x32_bf16 v[32:35], v[152:155], v[168:171], v[32:35]
	v_mfma_f32_16x16x32_bf16 v[20:23], v[144:147], v[176:179], v[20:23]
	v_mfma_f32_16x16x32_bf16 v[16:19], v[152:155], v[176:179], v[16:19]
	v_mfma_f32_16x16x32_bf16 v[4:7], v[144:147], v[184:187], v[4:7]
	v_mfma_f32_16x16x32_bf16 v[0:3], v[152:155], v[184:187], v[0:3]
	v_mfma_f32_16x16x32_bf16 v[52:55], v[148:151], v[164:167], v[52:55]
	v_mfma_f32_16x16x32_bf16 v[48:51], v[156:159], v[164:167], v[48:51]
	v_mfma_f32_16x16x32_bf16 v[36:39], v[148:151], v[172:175], v[36:39]
	v_mfma_f32_16x16x32_bf16 v[32:35], v[156:159], v[172:175], v[32:35]
	v_mfma_f32_16x16x32_bf16 v[20:23], v[148:151], v[180:183], v[20:23]
	v_mfma_f32_16x16x32_bf16 v[16:19], v[156:159], v[180:183], v[16:19]
	v_mfma_f32_16x16x32_bf16 v[4:7], v[148:151], v[188:191], v[4:7]
	v_mfma_f32_16x16x32_bf16 v[0:3], v[156:159], v[188:191], v[0:3]
	s_barrier
	s_setprio 0
	s_add_u32 s28, s28, 0x100
	s_addc_u32 s29, s29, 0
	s_add_u32 s1, s1, 0x100
	s_addc_u32 s33, s33, 0
	s_cmp_ge_i32 s59, s50
	s_cbranch_scc1 .LBB0_571
	s_branch .LBB0_561
.LBB0_560:
	s_waitcnt lgkmcnt(0)
	s_add_i32 s59, s59, 2
	s_setprio 1
	s_barrier
	v_mfma_f32_16x16x32_bf16 v[60:63], v[144:147], v[184:187], v[60:63]
	v_mfma_f32_16x16x32_bf16 v[56:59], v[152:155], v[184:187], v[56:59]
	v_mfma_f32_16x16x32_bf16 v[44:47], v[144:147], v[176:179], v[44:47]
	v_mfma_f32_16x16x32_bf16 v[40:43], v[152:155], v[176:179], v[40:43]
	v_mfma_f32_16x16x32_bf16 v[28:31], v[144:147], v[168:171], v[28:31]
	v_mfma_f32_16x16x32_bf16 v[24:27], v[152:155], v[168:171], v[24:27]
	v_mfma_f32_16x16x32_bf16 v[12:15], v[144:147], v[160:163], v[12:15]
	v_mfma_f32_16x16x32_bf16 v[8:11], v[152:155], v[160:163], v[8:11]
	v_mfma_f32_16x16x32_bf16 v[60:63], v[148:151], v[188:191], v[60:63]
	v_mfma_f32_16x16x32_bf16 v[56:59], v[156:159], v[188:191], v[56:59]
	v_mfma_f32_16x16x32_bf16 v[44:47], v[148:151], v[180:183], v[44:47]
	v_mfma_f32_16x16x32_bf16 v[40:43], v[156:159], v[180:183], v[40:43]
	v_mfma_f32_16x16x32_bf16 v[28:31], v[148:151], v[172:175], v[28:31]
	v_mfma_f32_16x16x32_bf16 v[24:27], v[156:159], v[172:175], v[24:27]
	v_mfma_f32_16x16x32_bf16 v[12:15], v[148:151], v[164:167], v[12:15]
	v_mfma_f32_16x16x32_bf16 v[8:11], v[156:159], v[164:167], v[8:11]
	s_setprio 0
	s_setprio 1
	v_mfma_f32_16x16x32_bf16 v[52:55], v[128:131], v[184:187], v[52:55]
	v_mfma_f32_16x16x32_bf16 v[48:51], v[136:139], v[184:187], v[48:51]
	v_mfma_f32_16x16x32_bf16 v[36:39], v[128:131], v[176:179], v[36:39]
	v_mfma_f32_16x16x32_bf16 v[32:35], v[136:139], v[176:179], v[32:35]
	v_mfma_f32_16x16x32_bf16 v[20:23], v[128:131], v[168:171], v[20:23]
	v_mfma_f32_16x16x32_bf16 v[16:19], v[136:139], v[168:171], v[16:19]
	v_mfma_f32_16x16x32_bf16 v[4:7], v[128:131], v[160:163], v[4:7]
	v_mfma_f32_16x16x32_bf16 v[0:3], v[136:139], v[160:163], v[0:3]
	v_mfma_f32_16x16x32_bf16 v[52:55], v[132:135], v[188:191], v[52:55]
	v_mfma_f32_16x16x32_bf16 v[48:51], v[140:143], v[188:191], v[48:51]
	v_mfma_f32_16x16x32_bf16 v[36:39], v[132:135], v[180:183], v[36:39]
	v_mfma_f32_16x16x32_bf16 v[32:35], v[140:143], v[180:183], v[32:35]
	v_mfma_f32_16x16x32_bf16 v[20:23], v[132:135], v[172:175], v[20:23]
	v_mfma_f32_16x16x32_bf16 v[16:19], v[140:143], v[172:175], v[16:19]
	v_mfma_f32_16x16x32_bf16 v[4:7], v[132:135], v[164:167], v[4:7]
	v_mfma_f32_16x16x32_bf16 v[0:3], v[140:143], v[164:167], v[0:3]
	s_barrier
; #define PG8_STAGE(bufoff, gbase, voff) do { _Pragma("unroll") for (int _i = 0; _i < 2; ++_i) \
;         __builtin_amdgcn_global_load_lds((const unsigned*)((const char*)(gbase) + (voff)[_i]), (PG8_LAS unsigned*)(lds + (bufoff) + ldsw + _i * 8192), 16, 0, 0); } while (0)
; #define PG8_LDA(dst, b, h) do { _Pragma("unroll") for (int m = 0; m < 4; ++m) _Pragma("unroll") for (int k = 0; k < 2; ++k) dst[m][k] = *(const PG8_LAS bf16x8*)(lds + PG8_SA(b, h) + aoff + m * 2048 + k * 1024); } while (0)
; #define PG8_LDB(dst, b, h) do { _Pragma("unroll") for (int n = 0; n < 2; ++n) _Pragma("unroll") for (int k = 0; k < 2; ++k) dst[n][k] = *(const PG8_LAS bf16x8*)(lds + PG8_SB(b, h) + boff + n * 2048 + k * 1024); } while (0)
; #define PG8_MMA(ai, bj, At, Bt) do { __builtin_amdgcn_s_setprio(1); _Pragma("unroll") for (int m = 0; m < 4; ++m) _Pragma("unroll") for (int n = 0; n < 2; ++n) _Pragma("unroll") for (int k = 0; k < 2; ++k) \
;         acc[ai][bj][m][n] = __builtin_amdgcn_mfma_f32_16x16x32_bf16(Bt[n][k], At[m][k], acc[ai][bj][m][n], 0, 0, 0); __builtin_amdgcn_s_setprio(0); } while (0)
; #define PG8_WAIT_V(n) asm volatile("s_waitcnt vmcnt(" #n ")" ::: "memory")
; #define PG8_WAIT_SEL(d, w4, w8) do { if constexpr (Epi::SPLIT) { if (d) { if constexpr (Epi::NSH == 4) PG8_WAIT_V(w4); else PG8_WAIT_V(w8); } else PG8_WAIT_V(8); } else PG8_WAIT_V(8); } while (0)
; #define PG8_WAIT_L(n) asm volatile("s_waitcnt lgkmcnt(" #n ")" ::: "memory")
; #define PG8_BAR __builtin_amdgcn_s_barrier()
; #define PG8_SCHED __builtin_amdgcn_sched_barrier(0)
; template <class Epi, class Sched, bool ALIGN_EPI = false, bool SP2 = false>
; __device__ __forceinline__ void gemm_phase(PG8_LAS unsigned char* lds, const Gemm g, const Sched& S, const Epi& E) {
;     ...
;             PG8_LDB(B0, 1, 0); PG8_LDB(B1, 1, 1); PG8_SCHED; PG8_LDA(At, 1, 0); PG8_STAGE(PG8_SA(0, 1), a2 + hstepA, voffA);
;             PG8_WAIT_SEL(defer, 12, 16); PG8_WAIT_L(0); PG8_BAR; PG8_MMA(0, 0, At, B0); PG8_MMA(0, 1, At, B1); PG8_BAR; PG8_SCHED;
;             PG8_LDA(At, 1, 1); PG8_STAGE(PG8_SB(1, 0), b3, voffB); PG8_STAGE(PG8_SB(1, 1), b3 + hstep, voffB); PG8_STAGE(PG8_SA(1, 0), a3, voffA);
;             PG8_WAIT_V(8); PG8_WAIT_L(0); PG8_BAR; PG8_MMA(1, 0, At, B0); PG8_MMA(1, 1, At, B1); PG8_BAR; PG8_SCHED;
	s_setprio 0
	s_add_i32 s34, 0, 0x18000
	s_add_i32 s35, 0, 0x1c000
	v_add_u32_e32 v140, s34, v239
	v_add_u32_e32 v156, s35, v239
	ds_read_b128 v[128:131], v140
	ds_read_b128 v[132:135], v140 offset:1024
	ds_read_b128 v[136:139], v140 offset:2048
	ds_read_b128 v[140:143], v140 offset:3072
	ds_read_b128 v[144:147], v156
	ds_read_b128 v[148:151], v156 offset:1024
	ds_read_b128 v[152:155], v156 offset:2048
	ds_read_b128 v[156:159], v156 offset:3072
	s_add_u32 s30, s30, s8
	s_addc_u32 s31, s31, s9
	s_mov_b32 m0, s47
	v_lshl_add_u64 v[194:195], s[30:31], 0, v[208:209]
	ds_read_b128 v[160:163], v240 offset:32768
	ds_read_b128 v[164:167], v240 offset:33792
	ds_read_b128 v[168:171], v240 offset:34816
	ds_read_b128 v[172:175], v240 offset:35840
	ds_read_b128 v[176:179], v240 offset:36864
	ds_read_b128 v[180:183], v240 offset:37888
	ds_read_b128 v[184:187], v240 offset:38912
	ds_read_b128 v[188:191], v240 offset:39936
	global_load_lds_dwordx4 v[194:195], off
	v_lshl_add_u64 v[194:195], s[30:31], 0, v[206:207]
	s_mov_b32 m0, s48
	s_nop 0
	global_load_lds_dwordx4 v[194:195], off
	s_waitcnt vmcnt(8)
	s_waitcnt lgkmcnt(0)
	s_setprio 1
	s_barrier
	v_mfma_f32_16x16x32_bf16 v[124:127], v[128:131], v[160:163], v[124:127]
	v_mfma_f32_16x16x32_bf16 v[120:123], v[136:139], v[160:163], v[120:123]
	v_mfma_f32_16x16x32_bf16 v[108:111], v[128:131], v[168:171], v[108:111]
	v_mfma_f32_16x16x32_bf16 v[104:107], v[136:139], v[168:171], v[104:107]
	v_mfma_f32_16x16x32_bf16 v[92:95], v[128:131], v[176:179], v[92:95]
	v_mfma_f32_16x16x32_bf16 v[88:91], v[136:139], v[176:179], v[88:91]
	v_mfma_f32_16x16x32_bf16 v[76:79], v[128:131], v[184:187], v[76:79]
	v_mfma_f32_16x16x32_bf16 v[72:75], v[136:139], v[184:187], v[72:75]
	v_mfma_f32_16x16x32_bf16 v[124:127], v[132:135], v[164:167], v[124:127]
	v_mfma_f32_16x16x32_bf16 v[120:123], v[140:143], v[164:167], v[120:123]
	v_mfma_f32_16x16x32_bf16 v[108:111], v[132:135], v[172:175], v[108:111]
	v_mfma_f32_16x16x32_bf16 v[104:107], v[140:143], v[172:175], v[104:107]
	v_mfma_f32_16x16x32_bf16 v[92:95], v[132:135], v[180:183], v[92:95]
	v_mfma_f32_16x16x32_bf16 v[88:91], v[140:143], v[180:183], v[88:91]
	v_mfma_f32_16x16x32_bf16 v[76:79], v[132:135], v[188:191], v[76:79]
	v_mfma_f32_16x16x32_bf16 v[72:75], v[140:143], v[188:191], v[72:75]
	s_setprio 0
	s_setprio 1
	v_mfma_f32_16x16x32_bf16 v[116:119], v[144:147], v[160:163], v[116:119]
	v_mfma_f32_16x16x32_bf16 v[112:115], v[152:155], v[160:163], v[112:115]
	v_mfma_f32_16x16x32_bf16 v[100:103], v[144:147], v[168:171], v[100:103]
	v_mfma_f32_16x16x32_bf16 v[96:99], v[152:155], v[168:171], v[96:99]
	v_mfma_f32_16x16x32_bf16 v[84:87], v[144:147], v[176:179], v[84:87]
	v_mfma_f32_16x16x32_bf16 v[80:83], v[152:155], v[176:179], v[80:83]
	v_mfma_f32_16x16x32_bf16 v[68:71], v[144:147], v[184:187], v[68:71]
	v_mfma_f32_16x16x32_bf16 v[64:67], v[152:155], v[184:187], v[64:67]
	v_mfma_f32_16x16x32_bf16 v[116:119], v[148:151], v[164:167], v[116:119]
	v_mfma_f32_16x16x32_bf16 v[112:115], v[156:159], v[164:167], v[112:115]
	v_mfma_f32_16x16x32_bf16 v[100:103], v[148:151], v[172:175], v[100:103]
	v_mfma_f32_16x16x32_bf16 v[96:99], v[156:159], v[172:175], v[96:99]
	v_mfma_f32_16x16x32_bf16 v[84:87], v[148:151], v[180:183], v[84:87]
	v_mfma_f32_16x16x32_bf16 v[80:83], v[156:159], v[180:183], v[80:83]
	v_mfma_f32_16x16x32_bf16 v[68:71], v[148:151], v[188:191], v[68:71]
	v_mfma_f32_16x16x32_bf16 v[64:67], v[156:159], v[188:191], v[64:67]
	s_barrier
	s_setprio 0
	s_add_i32 s30, s34, s40
	v_lshl_add_u64 v[194:195], v[222:223], 0, s[90:91]
	s_mov_b32 m0, s30
	ds_read_b128 v[160:163], v240 offset:49152
	ds_read_b128 v[164:167], v240 offset:50176
	ds_read_b128 v[168:171], v240 offset:51200
	ds_read_b128 v[172:175], v240 offset:52224
	ds_read_b128 v[176:179], v240 offset:53248
	ds_read_b128 v[180:183], v240 offset:54272
	ds_read_b128 v[184:187], v240 offset:55296
	ds_read_b128 v[188:191], v240 offset:56320
	global_load_lds_dwordx4 v[194:195], off
	v_lshl_add_u64 v[194:195], v[220:221], 0, s[90:91]
	s_add_i32 m0, s30, 0x2000
	s_add_i32 s30, s35, s40
	global_load_lds_dwordx4 v[194:195], off
	v_lshl_add_u64 v[194:195], v[230:231], 0, s[90:91]
	s_mov_b32 m0, s30
	s_nop 0
	global_load_lds_dwordx4 v[194:195], off
	v_lshl_add_u64 v[194:195], v[228:229], 0, s[90:91]
	s_add_i32 m0, s30, 0x2000
	s_nop 0
	global_load_lds_dwordx4 v[194:195], off
	v_lshl_add_u64 v[194:195], v[224:225], 0, s[90:91]
	s_mov_b32 m0, s53
	s_nop 0
	global_load_lds_dwordx4 v[194:195], off
	v_lshl_add_u64 v[194:195], v[226:227], 0, s[90:91]
	s_mov_b32 m0, s54
	s_nop 0
	global_load_lds_dwordx4 v[194:195], off
	s_waitcnt vmcnt(8)
	s_waitcnt lgkmcnt(0)
	s_setprio 1
	s_barrier
	v_mfma_f32_16x16x32_bf16 v[60:63], v[128:131], v[160:163], v[60:63]
	v_mfma_f32_16x16x32_bf16 v[56:59], v[136:139], v[160:163], v[56:59]
	v_mfma_f32_16x16x32_bf16 v[44:47], v[128:131], v[168:171], v[44:47]
	v_mfma_f32_16x16x32_bf16 v[40:43], v[136:139], v[168:171], v[40:43]
	v_mfma_f32_16x16x32_bf16 v[28:31], v[128:131], v[176:179], v[28:31]
	v_mfma_f32_16x16x32_bf16 v[24:27], v[136:139], v[176:179], v[24:27]
	v_mfma_f32_16x16x32_bf16 v[12:15], v[128:131], v[184:187], v[12:15]
	v_mfma_f32_16x16x32_bf16 v[8:11], v[136:139], v[184:187], v[8:11]
	v_mfma_f32_16x16x32_bf16 v[60:63], v[132:135], v[164:167], v[60:63]
	v_mfma_f32_16x16x32_bf16 v[56:59], v[140:143], v[164:167], v[56:59]
	v_mfma_f32_16x16x32_bf16 v[44:47], v[132:135], v[172:175], v[44:47]
	v_mfma_f32_16x16x32_bf16 v[40:43], v[140:143], v[172:175], v[40:43]
	v_mfma_f32_16x16x32_bf16 v[28:31], v[132:135], v[180:183], v[28:31]
	v_mfma_f32_16x16x32_bf16 v[24:27], v[140:143], v[180:183], v[24:27]
	v_mfma_f32_16x16x32_bf16 v[12:15], v[132:135], v[188:191], v[12:15]
	v_mfma_f32_16x16x32_bf16 v[8:11], v[140:143], v[188:191], v[8:11]
	s_setprio 0
	s_setprio 1
	v_mfma_f32_16x16x32_bf16 v[52:55], v[144:147], v[160:163], v[52:55]
	v_mfma_f32_16x16x32_bf16 v[48:51], v[152:155], v[160:163], v[48:51]
	v_mfma_f32_16x16x32_bf16 v[36:39], v[144:147], v[168:171], v[36:39]
	v_mfma_f32_16x16x32_bf16 v[32:35], v[152:155], v[168:171], v[32:35]
	v_mfma_f32_16x16x32_bf16 v[20:23], v[144:147], v[176:179], v[20:23]
	v_mfma_f32_16x16x32_bf16 v[16:19], v[152:155], v[176:179], v[16:19]
	v_mfma_f32_16x16x32_bf16 v[4:7], v[144:147], v[184:187], v[4:7]
	v_mfma_f32_16x16x32_bf16 v[0:3], v[152:155], v[184:187], v[0:3]
	v_mfma_f32_16x16x32_bf16 v[52:55], v[148:151], v[164:167], v[52:55]
	v_mfma_f32_16x16x32_bf16 v[48:51], v[156:159], v[164:167], v[48:51]
	v_mfma_f32_16x16x32_bf16 v[36:39], v[148:151], v[172:175], v[36:39]
	v_mfma_f32_16x16x32_bf16 v[32:35], v[156:159], v[172:175], v[32:35]
	v_mfma_f32_16x16x32_bf16 v[20:23], v[148:151], v[180:183], v[20:23]
	v_mfma_f32_16x16x32_bf16 v[16:19], v[156:159], v[180:183], v[16:19]
	v_mfma_f32_16x16x32_bf16 v[4:7], v[148:151], v[188:191], v[4:7]
	v_mfma_f32_16x16x32_bf16 v[0:3], v[156:159], v[188:191], v[0:3]
	s_barrier
	s_setprio 0
	s_add_u32 s28, s28, 0x100
	s_addc_u32 s29, s29, 0
	s_add_u32 s1, s1, 0x100
	s_addc_u32 s33, s33, 0
	s_cmp_ge_i32 s59, s50
	s_cbranch_scc1 .LBB0_571

; #define PG8_STAGE(bufoff, gbase, voff) do { _Pragma("unroll") for (int _i = 0; _i < 2; ++_i) \
;         __builtin_amdgcn_global_load_lds((const unsigned*)((const char*)(gbase) + (voff)[_i]), (PG8_LAS unsigned*)(lds + (bufoff) + ldsw + _i * 8192), 16, 0, 0); } while (0)
; #define PG8_LDA(dst, b, h) do { _Pragma("unroll") for (int m = 0; m < 4; ++m) _Pragma("unroll") for (int k = 0; k < 2; ++k) dst[m][k] = *(const PG8_LAS bf16x8*)(lds + PG8_SA(b, h) + aoff + m * 2048 + k * 1024); } while (0)
; #define PG8_LDB(dst, b, h) do { _Pragma("unroll") for (int n = 0; n < 2; ++n) _Pragma("unroll") for (int k = 0; k < 2; ++k) dst[n][k] = *(const PG8_LAS bf16x8*)(lds + PG8_SB(b, h) + boff + n * 2048 + k * 1024); } while (0)
; #define PG8_WAIT_V(n) asm volatile("s_waitcnt vmcnt(" #n ")" ::: "memory")
; #define PG8_WAIT_SEL(d, w4, w8) do { if constexpr (Epi::SPLIT) { if (d) { if constexpr (Epi::NSH == 4) PG8_WAIT_V(w4); else PG8_WAIT_V(w8); } else PG8_WAIT_V(8); } else PG8_WAIT_V(8); } while (0)
; #define PG8_BAR __builtin_amdgcn_s_barrier()
; template <class Epi, class Sched, bool ALIGN_EPI = false, bool SP2 = false>
; __device__ __forceinline__ void gemm_phase(PG8_LAS unsigned char* lds, const Gemm g, const Sched& S, const Epi& E) {
;     ...
;             const char* a2 = last ? nA : cA + (size_t)(t + 2) * kstep; const char* b2 = last ? nB : cB + (size_t)(t + 2) * kstep;
;             const char* a3 = a2 + kstep; const char* b3 = b2 + kstep;
;             if (last && has_next) S.a_ready(nxt);
;             if constexpr (SP2) {
;             PG8_LDB(B0, 0, 0); PG8_LDB(B1, 0, 1); PG8_SCHED; PG8_LDA(At, 0, 0); PG8_STAGE(PG8_SA(1, 1), a1 + hstepA, voffA);
;             if (plast) PG8_WAIT_V(10); else PG8_WAIT_SEL(defer, 12, 16);
;             PG8_WAIT_L(0); PG8_BAR; PG8_MMA(0, 0, At, B0); PG8_MMA(0, 1, At, B1);
;             if constexpr (Epi::SPLIT) { if (defer) {
;                 E.second(acc, prev, rv1, wr, wc, fr, fq);
;                 _Pragma("unroll") for (int b = 0; b < 2; ++b) _Pragma("unroll") for (int m = 0; m < 4; ++m) _Pragma("unroll") for (int n = 0; n < 2; ++n) acc[1][b][m][n] = (f32x4){0.f, 0.f, 0.f, 0.f}; } }
;             PG8_BAR; PG8_SCHED;
;             PG8_LDA(At, 0, 1); PG8_STAGE(PG8_SB(0, 0), b2, voffB); PG8_STAGE(PG8_SB(0, 1), b2 + hstep, voffB); PG8_STAGE(PG8_SA(0, 0), a2, voffA);
;             if (plast) PG8_WAIT_V(10); else PG8_WAIT_SEL(defer, 16, 24);
.LBB0_567:
	s_add_u32 s36, s28, 0x80
	s_addc_u32 s37, s29, 0
	s_waitcnt lgkmcnt(0)
	s_and_b64 s[30:31], s[30:31], exec
	s_cselect_b32 s31, s7, s37
	s_cselect_b32 s30, s6, s36
	s_cselect_b32 s37, s27, s33
	s_cselect_b32 s36, s26, s1
	s_setprio 1
	s_barrier
	v_mfma_f32_16x16x32_bf16 v[124:127], v[144:147], v[184:187], v[124:127]
	v_mfma_f32_16x16x32_bf16 v[120:123], v[152:155], v[184:187], v[120:123]
	v_mfma_f32_16x16x32_bf16 v[108:111], v[144:147], v[176:179], v[108:111]
	v_mfma_f32_16x16x32_bf16 v[104:107], v[152:155], v[176:179], v[104:107]
	v_mfma_f32_16x16x32_bf16 v[92:95], v[144:147], v[168:171], v[92:95]
	v_mfma_f32_16x16x32_bf16 v[88:91], v[152:155], v[168:171], v[88:91]
	v_mfma_f32_16x16x32_bf16 v[76:79], v[144:147], v[160:163], v[76:79]
	v_mfma_f32_16x16x32_bf16 v[72:75], v[152:155], v[160:163], v[72:75]
	v_mfma_f32_16x16x32_bf16 v[124:127], v[148:151], v[188:191], v[124:127]
	v_mfma_f32_16x16x32_bf16 v[120:123], v[156:159], v[188:191], v[120:123]
	v_mfma_f32_16x16x32_bf16 v[108:111], v[148:151], v[180:183], v[108:111]
	v_mfma_f32_16x16x32_bf16 v[104:107], v[156:159], v[180:183], v[104:107]
	v_mfma_f32_16x16x32_bf16 v[92:95], v[148:151], v[172:175], v[92:95]
	v_mfma_f32_16x16x32_bf16 v[88:91], v[156:159], v[172:175], v[88:91]
	v_mfma_f32_16x16x32_bf16 v[76:79], v[148:151], v[164:167], v[76:79]
	v_mfma_f32_16x16x32_bf16 v[72:75], v[156:159], v[164:167], v[72:75]
	s_setprio 0
	s_setprio 1
	v_mfma_f32_16x16x32_bf16 v[116:119], v[128:131], v[184:187], v[116:119]
	v_mfma_f32_16x16x32_bf16 v[112:115], v[136:139], v[184:187], v[112:115]
	v_mfma_f32_16x16x32_bf16 v[100:103], v[128:131], v[176:179], v[100:103]
	v_mfma_f32_16x16x32_bf16 v[96:99], v[136:139], v[176:179], v[96:99]
	v_mfma_f32_16x16x32_bf16 v[84:87], v[128:131], v[168:171], v[84:87]
	v_mfma_f32_16x16x32_bf16 v[80:83], v[136:139], v[168:171], v[80:83]
	v_mfma_f32_16x16x32_bf16 v[68:71], v[128:131], v[160:163], v[68:71]
	v_mfma_f32_16x16x32_bf16 v[64:67], v[136:139], v[160:163], v[64:67]
	v_mfma_f32_16x16x32_bf16 v[116:119], v[132:135], v[188:191], v[116:119]
	v_mfma_f32_16x16x32_bf16 v[112:115], v[140:143], v[188:191], v[112:115]
	v_mfma_f32_16x16x32_bf16 v[100:103], v[132:135], v[180:183], v[100:103]
	v_mfma_f32_16x16x32_bf16 v[96:99], v[140:143], v[180:183], v[96:99]
	v_mfma_f32_16x16x32_bf16 v[84:87], v[132:135], v[172:175], v[84:87]
	v_mfma_f32_16x16x32_bf16 v[80:83], v[140:143], v[172:175], v[80:83]
	v_mfma_f32_16x16x32_bf16 v[68:71], v[132:135], v[164:167], v[68:71]
	v_mfma_f32_16x16x32_bf16 v[64:67], v[140:143], v[164:167], v[64:67]
	s_barrier
	s_setprio 0
	s_mov_b32 m0, s42
	v_lshl_add_u64 v[222:223], s[36:37], 0, v[192:193]
	v_lshl_add_u64 v[220:221], s[36:37], 0, v[204:205]
	s_add_u32 s36, s36, s12
	ds_read_b128 v[184:187], v240 offset:16384
	ds_read_b128 v[188:191], v240 offset:17408
	ds_read_b128 v[176:179], v240 offset:18432
	ds_read_b128 v[180:183], v240 offset:19456
	ds_read_b128 v[168:171], v240 offset:20480
	ds_read_b128 v[172:175], v240 offset:21504
	ds_read_b128 v[160:163], v240 offset:22528
	ds_read_b128 v[164:167], v240 offset:23552
	global_load_lds_dwordx4 v[222:223], off
	s_mov_b32 m0, s43
	s_addc_u32 s37, s37, s13
	global_load_lds_dwordx4 v[220:221], off
	v_lshl_add_u64 v[230:231], s[36:37], 0, v[192:193]
	s_mov_b32 m0, s44
	v_lshl_add_u64 v[228:229], s[36:37], 0, v[204:205]
	global_load_lds_dwordx4 v[230:231], off
	s_mov_b32 m0, s45
	v_lshl_add_u64 v[224:225], s[30:31], 0, v[208:209]
	global_load_lds_dwordx4 v[228:229], off
	s_mov_b32 m0, s41
	v_lshl_add_u64 v[226:227], s[30:31], 0, v[206:207]
	global_load_lds_dwordx4 v[224:225], off
	s_mov_b32 m0, s46
	s_mov_b64 s[36:37], -1
	global_load_lds_dwordx4 v[226:227], off
	s_and_b64 vcc, exec, s[34:35]
	s_cbranch_vccz .LBB0_569
	s_waitcnt vmcnt(8)
	s_mov_b64 s[36:37], 0
